# RA static schedule: fewer prompt items on workgroups carrying a sample item; swa V staging loads batched
# baseline (speedup 1.0000x reference)
.LBB0_399:
	s_or_b64 exec, exec, s[4:5]
	s_and_b32 s2, s12, -2
	s_cmp_eq_u32 s13, 0
	s_cselect_b64 vcc, -1, 0
	s_lshl_b32 s4, s2, 4
	v_or_b32_e32 v47, s14, v75
	v_lshl_add_u32 v46, v79, 4, 0
	v_or_b32_e32 v48, s4, v75
	v_mad_u64_u32 v[100:101], s[6:7], v48, s88, v[46:47]
	s_or_b32 s6, s4, 16
	s_add_i32 s3, s2, 2
	v_or_b32_e32 v48, s6, v75
	s_lshl_b32 s12, s3, 4
	v_mad_u64_u32 v[98:99], s[8:9], v48, s88, v[46:47]
	v_or_b32_e32 v48, s12, v75
	s_add_i32 s20, s4, 48
	s_add_i32 s49, s2, 4
	v_mad_u64_u32 v[96:97], s[8:9], v48, s88, v[46:47]
	v_or_b32_e32 v48, s20, v75
	s_lshl_b32 s28, s49, 4
	v_mad_u64_u32 v[94:95], s[8:9], v48, s88, v[46:47]
	v_or_b32_e32 v48, s28, v75
	s_add_i32 s38, s4, 0x50
	v_mad_u64_u32 v[92:93], s[8:9], v48, s88, v[46:47]
	v_or_b32_e32 v48, s38, v75
	v_mad_u64_u32 v[90:91], s[8:9], v48, s88, v[46:47]
	s_add_i32 s88, s2, 6
	s_lshl_b32 s54, s88, 4
	s_movk_i32 s5, 0x90
	v_or_b32_e32 v48, s54, v75
	s_add_i32 s62, s4, 0x70
	s_add_i32 s89, s2, 8
	v_mad_u64_u32 v[88:89], s[8:9], v48, s5, v[46:47]
	v_or_b32_e32 v48, s62, v75
	s_lshl_b32 s70, s89, 4
	v_mad_u64_u32 v[86:87], s[8:9], v48, s5, v[46:47]
	v_or_b32_e32 v48, s70, v75
	s_add_i32 s78, s4, 0x90
	v_mad_u64_u32 v[84:85], s[8:9], v48, s5, v[46:47]
	v_or_b32_e32 v48, s78, v75
	v_mad_u64_u32 v[82:83], s[8:9], v48, s5, v[46:47]
	v_max_i32_e32 v46, 0x80, v47
	v_lshlrev_b32_e32 v48, 2, v79
	v_cndmask_b32_e32 v46, v47, v46, vcc
	v_add_u32_e32 v47, 0x80, v47
	v_or_b32_e32 v49, s4, v48
	v_cmp_lt_i32_e32 vcc, v49, v46
	v_cmp_gt_i32_e64 s[4:5], v49, v47
	v_or_b32_e32 v50, 1, v49
	s_or_b64 s[40:41], vcc, s[4:5]
	v_cmp_lt_i32_e32 vcc, v50, v46
	v_cmp_ge_i32_e64 s[4:5], v49, v47
	v_or_b32_e32 v50, 2, v49
	v_writelane_b32 v255, s40, 0
	s_or_b64 s[42:43], vcc, s[4:5]
	v_cmp_lt_i32_e32 vcc, v50, v46
	v_cmp_gt_i32_e64 s[4:5], v50, v47
	v_writelane_b32 v255, s41, 1
	s_or_b64 s[4:5], vcc, s[4:5]
	v_writelane_b32 v255, s4, 2
	v_or_b32_e32 v49, 3, v49
	v_cmp_lt_i32_e32 vcc, v49, v46
	v_writelane_b32 v255, s5, 3
	v_cmp_gt_i32_e64 s[4:5], v49, v47
	s_or_b64 s[4:5], vcc, s[4:5]
	v_or_b32_e32 v49, s6, v48
	v_writelane_b32 v255, s4, 4
	v_cmp_lt_i32_e32 vcc, v49, v46
	v_or_b32_e32 v50, 1, v49
	v_writelane_b32 v255, s5, 5
	v_cmp_gt_i32_e64 s[4:5], v49, v47
	s_or_b64 s[4:5], vcc, s[4:5]
	v_cmp_lt_i32_e32 vcc, v50, v46
	v_writelane_b32 v255, s4, 6
	v_cmp_ge_i32_e64 s[6:7], v49, v47
	v_or_b32_e32 v50, 2, v49
	v_writelane_b32 v255, s5, 7
	s_or_b64 s[6:7], vcc, s[6:7]
	v_cmp_lt_i32_e32 vcc, v50, v46
	v_cmp_gt_i32_e64 s[8:9], v50, v47
	v_or_b32_e32 v49, 3, v49
	v_writelane_b32 v255, s6, 8
	s_or_b64 s[4:5], vcc, s[8:9]
	v_cmp_lt_i32_e32 vcc, v49, v46
	v_cmp_gt_i32_e64 s[10:11], v49, v47
	v_or_b32_e32 v49, s12, v48
	v_writelane_b32 v255, s7, 9
	s_or_b64 s[44:45], vcc, s[10:11]
	v_cmp_lt_i32_e32 vcc, v49, v46
	v_cmp_gt_i32_e64 s[12:13], v49, v47
	v_or_b32_e32 v50, 1, v49
	v_writelane_b32 v255, s4, 10
	s_or_b64 s[8:9], vcc, s[12:13]
	v_cmp_lt_i32_e32 vcc, v50, v46
	v_cmp_ge_i32_e64 s[14:15], v49, v47
	v_or_b32_e32 v50, 2, v49
	v_writelane_b32 v255, s5, 11
	s_or_b64 s[12:13], vcc, s[14:15]
	v_cmp_lt_i32_e32 vcc, v50, v46
	v_cmp_gt_i32_e64 s[16:17], v50, v47
	v_or_b32_e32 v49, 3, v49
	v_writelane_b32 v255, s8, 12
	s_or_b64 s[10:11], vcc, s[16:17]
	v_cmp_lt_i32_e32 vcc, v49, v46
	v_cmp_gt_i32_e64 s[18:19], v49, v47
	v_or_b32_e32 v49, s20, v48
	v_writelane_b32 v255, s9, 13
	s_or_b64 s[8:9], vcc, s[18:19]
	v_cmp_lt_i32_e32 vcc, v49, v46
	v_cmp_gt_i32_e64 s[20:21], v49, v47
	v_or_b32_e32 v50, 1, v49
	s_or_b64 s[20:21], vcc, s[20:21]
	v_cmp_lt_i32_e32 vcc, v50, v46
	v_cmp_ge_i32_e64 s[22:23], v49, v47
	v_or_b32_e32 v50, 2, v49
	s_or_b64 s[18:19], vcc, s[22:23]
	v_cmp_lt_i32_e32 vcc, v50, v46
	v_cmp_gt_i32_e64 s[24:25], v50, v47
	v_or_b32_e32 v49, 3, v49
	s_or_b64 s[16:17], vcc, s[24:25]
	v_cmp_lt_i32_e32 vcc, v49, v46
	v_cmp_gt_i32_e64 s[26:27], v49, v47
	v_or_b32_e32 v49, s28, v48
	s_or_b64 s[14:15], vcc, s[26:27]
	v_cmp_lt_i32_e32 vcc, v49, v46
	v_cmp_gt_i32_e64 s[28:29], v49, v47
	v_or_b32_e32 v50, 1, v49
	s_or_b64 s[28:29], vcc, s[28:29]
	v_cmp_lt_i32_e32 vcc, v50, v46
	v_cmp_ge_i32_e64 s[30:31], v49, v47
	v_or_b32_e32 v50, 2, v49
	s_or_b64 s[24:25], vcc, s[30:31]
	v_cmp_lt_i32_e32 vcc, v50, v46
	v_cmp_gt_i32_e64 s[34:35], v50, v47
	v_or_b32_e32 v49, 3, v49
	s_or_b64 s[22:23], vcc, s[34:35]
	v_cmp_lt_i32_e32 vcc, v49, v46
	v_cmp_gt_i32_e64 s[36:37], v49, v47
	v_or_b32_e32 v49, s38, v48
	s_or_b64 s[26:27], vcc, s[36:37]
	v_cmp_lt_i32_e32 vcc, v49, v46
	v_cmp_gt_i32_e64 s[38:39], v49, v47
	v_or_b32_e32 v50, 1, v49
	s_or_b64 s[38:39], vcc, s[38:39]
	v_cmp_lt_i32_e32 vcc, v50, v46
	v_cmp_ge_i32_e64 s[46:47], v49, v47
	v_or_b32_e32 v50, 2, v49
	s_or_b64 s[30:31], vcc, s[46:47]
	v_cmp_lt_i32_e32 vcc, v50, v46
	v_cmp_gt_i32_e64 s[50:51], v50, v47
	v_or_b32_e32 v49, 3, v49
	s_or_b64 s[34:35], vcc, s[50:51]
	v_cmp_lt_i32_e32 vcc, v49, v46
	v_cmp_gt_i32_e64 s[52:53], v49, v47
	v_or_b32_e32 v49, s54, v48
	s_or_b64 s[36:37], vcc, s[52:53]
	v_cmp_lt_i32_e32 vcc, v49, v46
	v_cmp_gt_i32_e64 s[54:55], v49, v47
	v_or_b32_e32 v50, 1, v49
	s_or_b64 s[54:55], vcc, s[54:55]
	v_cmp_lt_i32_e32 vcc, v50, v46
	v_cmp_ge_i32_e64 s[56:57], v49, v47
	v_or_b32_e32 v50, 2, v49
	s_or_b64 s[46:47], vcc, s[56:57]
	v_cmp_lt_i32_e32 vcc, v50, v46
	v_cmp_gt_i32_e64 s[58:59], v50, v47
	v_or_b32_e32 v49, 3, v49
	s_or_b64 s[50:51], vcc, s[58:59]
	v_cmp_lt_i32_e32 vcc, v49, v46
	v_cmp_gt_i32_e64 s[60:61], v49, v47
	v_or_b32_e32 v49, s62, v48
	s_or_b64 s[52:53], vcc, s[60:61]
	v_cmp_lt_i32_e32 vcc, v49, v46
	v_cmp_gt_i32_e64 s[62:63], v49, v47
	v_or_b32_e32 v50, 1, v49
	s_or_b64 s[62:63], vcc, s[62:63]
	v_cmp_lt_i32_e32 vcc, v50, v46
	v_cmp_ge_i32_e64 s[64:65], v49, v47
	v_or_b32_e32 v50, 2, v49
	s_or_b64 s[56:57], vcc, s[64:65]
	v_cmp_lt_i32_e32 vcc, v50, v46
	v_cmp_gt_i32_e64 s[66:67], v50, v47
	v_or_b32_e32 v49, 3, v49
	s_or_b64 s[58:59], vcc, s[66:67]
	v_cmp_lt_i32_e32 vcc, v49, v46
	v_cmp_gt_i32_e64 s[68:69], v49, v47
	v_or_b32_e32 v49, s70, v48
	s_or_b64 s[60:61], vcc, s[68:69]
	v_cmp_lt_i32_e32 vcc, v49, v46
	v_cmp_gt_i32_e64 s[70:71], v49, v47
	v_or_b32_e32 v50, 1, v49
	v_ashrrev_i32_e32 v3, 31, v2
	s_or_b64 s[70:71], vcc, s[70:71]
	v_cmp_lt_i32_e32 vcc, v50, v46
	v_cmp_ge_i32_e64 s[72:73], v49, v47
	v_or_b32_e32 v50, 2, v49
	s_or_b64 s[64:65], vcc, s[72:73]
	v_cmp_lt_i32_e32 vcc, v50, v46
	v_cmp_gt_i32_e64 s[74:75], v50, v47
	v_or_b32_e32 v49, 3, v49
	v_lshlrev_b64 v[2:3], 11, v[2:3]
	v_lshlrev_b32_e32 v0, 3, v79
	s_or_b64 s[66:67], vcc, s[74:75]
	v_cmp_lt_i32_e32 vcc, v49, v46
	v_cmp_gt_i32_e64 s[76:77], v49, v47
	v_or_b32_e32 v48, s78, v48
	v_lshl_add_u64 v[2:3], s[0:1], 0, v[2:3]
	s_or_b64 s[68:69], vcc, s[76:77]
	v_cmp_lt_i32_e32 vcc, v48, v46
	v_cmp_gt_i32_e64 s[78:79], v48, v47
	v_or_b32_e32 v49, 1, v48
	v_lshl_add_u64 v[2:3], v[2:3], 0, v[0:1]
	s_mov_b64 s[0:1], 0xa000000
	s_or_b64 s[78:79], vcc, s[78:79]
	v_cmp_lt_i32_e32 vcc, v49, v46
	v_cmp_ge_i32_e64 s[80:81], v48, v47
	v_or_b32_e32 v49, 2, v48
	v_lshl_add_u64 v[80:81], v[2:3], 0, s[0:1]
	v_readlane_b32 s0, v254, 14
	s_or_b64 s[76:77], vcc, s[80:81]
	v_cmp_lt_i32_e32 vcc, v49, v46
	v_cmp_gt_i32_e64 s[82:83], v49, v47
	v_or_b32_e32 v48, 3, v48
	v_mov_b32_e32 v79, s0
	s_waitcnt lgkmcnt(0)
	s_barrier
	s_or_b64 s[72:73], vcc, s[82:83]
	v_cmp_lt_i32_e32 vcc, v48, v46
	v_cmp_gt_i32_e64 s[84:85], v48, v47
	v_add_u32_e32 v46, 0, v0
	v_mul_u32_u24_e32 v47, 0x210, v75
	s_lshl_b32 s2, s2, 5
	v_lshlrev_b32_e32 v64, 16, v38
	v_and_b32_e32 v66, 0xffff0000, v38
	v_lshlrev_b32_e32 v65, 16, v39
	v_and_b32_e32 v67, 0xffff0000, v39
	v_lshlrev_b32_e32 v68, 16, v40
	v_and_b32_e32 v70, 0xffff0000, v40
	v_lshlrev_b32_e32 v69, 16, v41
	v_and_b32_e32 v71, 0xffff0000, v41
	ds_read2_b64 v[38:41], v79 offset1:1
	v_add3_u32 v91, v46, s2, v47
	s_lshl_b32 s2, s3, 5
	v_add3_u32 v89, v46, s2, v47
	s_lshl_b32 s2, s49, 5
	v_add3_u32 v87, v46, s2, v47
	s_lshl_b32 s2, s88, 5
	v_readlane_b32 s0, v254, 51
	v_add3_u32 v85, v46, s2, v47
	s_lshl_b32 s2, s89, 5
	v_readlane_b32 s1, v254, 52
	s_or_b64 s[74:75], vcc, s[84:85]
	v_add3_u32 v83, v46, s2, v47
	s_waitcnt lgkmcnt(0)
	v_readfirstlane_b32 s2, v38
	s_lshl_b64 s[0:1], s[0:1], 2
	v_readfirstlane_b32 s3, v39
	s_add_u32 s2, s2, s0
	v_lshlrev_b32_e32 v3, 16, v43
	v_and_b32_e32 v59, 0xffff0000, v43
	v_lshlrev_b32_e32 v60, 16, v44
	v_and_b32_e32 v62, 0xffff0000, v44
	v_lshlrev_b32_e32 v61, 16, v45
	v_and_b32_e32 v63, 0xffff0000, v45
	s_addc_u32 s3, s3, s1
	v_lshlrev_b32_e32 v0, 2, v0
	v_mov_b32_e32 v44, v67
	v_mov_b32_e32 v45, v65
	v_lshlrev_b32_e32 v2, 16, v42
	v_and_b32_e32 v58, 0xffff0000, v42
	v_lshl_add_u64 v[38:39], s[2:3], 0, v[0:1]
	v_mov_b32_e32 v42, v59
	v_mov_b32_e32 v43, v3
	v_pk_mul_f32 v[44:45], v[44:45], v[44:45]
	flat_load_dwordx4 v[46:49], v[38:39] offset:128
	v_pk_fma_f32 v[72:73], v[42:43], v[42:43], v[44:45]
	flat_load_dwordx4 v[42:45], v[38:39]
	flat_load_dwordx4 v[50:53], v[38:39] offset:16
	flat_load_dwordx4 v[54:57], v[38:39] offset:144
	v_mul_f32_e32 v38, v58, v58
	v_mul_f32_e32 v39, v2, v2
	v_fmac_f32_e32 v38, v66, v66
	v_fmac_f32_e32 v39, v64, v64
	v_mov_b32_e32 v104, v18
	v_mov_b32_e32 v105, v20
	v_mov_b32_e32 v20, v19
	v_mov_b32_e32 v18, v70
	v_mov_b32_e32 v19, v68
	v_add_f32_e32 v38, v39, v38
	v_mov_b32_e32 v102, v10
	v_mov_b32_e32 v103, v12
	v_mov_b32_e32 v12, v11
	v_mov_b32_e32 v10, v62
	v_mov_b32_e32 v11, v60
	v_pk_mul_f32 v[18:19], v[18:19], v[18:19]
	v_add_f32_e32 v38, v73, v38
	v_pk_fma_f32 v[10:11], v[10:11], v[10:11], v[18:19]
	v_add_f32_e32 v38, v72, v38
	v_mov_b32_e32 v18, v63
	v_mov_b32_e32 v19, v61
	v_add_f32_e32 v11, v11, v38
	v_add_f32_e32 v10, v10, v11
	s_mov_b32 s2, 0xf800000
	v_readfirstlane_b32 s49, v40
	v_writelane_b32 v255, s12, 14
	s_mov_b32 s94, 0xf149f2ca
	s_mov_b64 s[84:85], s[8:9]
	v_writelane_b32 v255, s13, 15
	v_writelane_b32 v255, s18, 16
	s_mov_b64 s[82:83], s[10:11]
	s_waitcnt vmcnt(0) lgkmcnt(0)
	v_mov_b32_e32 v76, v46
	v_mov_b32_e32 v77, v48
	v_mov_b32_e32 v74, v42
	v_mov_b32_e32 v75, v44
	v_mov_b32_e32 v44, v43
	v_mov_b32_e32 v42, v71
	v_mov_b32_e32 v43, v69
	v_pk_mul_f32 v[42:43], v[42:43], v[42:43]
	v_mov_b32_e32 v48, v47
	v_pk_fma_f32 v[18:19], v[18:19], v[18:19], v[42:43]
	v_writelane_b32 v255, s19, 17
	v_add_f32_e32 v10, v19, v10
	v_add_f32_e32 v10, v18, v10
	ds_bpermute_b32 v11, v109, v10
	v_writelane_b32 v255, s16, 18
	s_waitcnt lgkmcnt(0)
	v_add_f32_e32 v10, v10, v11
	ds_bpermute_b32 v11, v110, v10
	v_writelane_b32 v255, s17, 19
	v_writelane_b32 v255, s70, 20
	s_waitcnt lgkmcnt(0)
	v_add_f32_e32 v10, v10, v11
	v_fmamk_f32 v10, v10, 0x3c800000, v219
	v_cmp_gt_f32_e32 vcc, s2, v10
	v_mul_f32_e32 v11, 0x4f800000, v10
	v_writelane_b32 v255, s71, 21
	v_cndmask_b32_e32 v10, v10, v11, vcc
	v_sqrt_f32_e32 v11, v10
	s_nop 0
	v_add_u32_e32 v18, -1, v11
	v_fma_f32 v19, -v18, v11, v10
	v_cmp_ge_f32_e64 s[88:89], 0, v19
	v_add_u32_e32 v19, 1, v11
	s_nop 0
	v_cndmask_b32_e64 v18, v11, v18, s[88:89]
	v_fma_f32 v11, -v19, v11, v10
	v_cmp_lt_f32_e64 s[88:89], 0, v11
	s_nop 1
	v_cndmask_b32_e64 v11, v18, v19, s[88:89]
	v_mul_f32_e32 v18, 0x37800000, v11
	v_cndmask_b32_e32 v11, v11, v18, vcc
	v_cmp_class_f32_e32 vcc, v10, v221
	v_readfirstlane_b32 s88, v41
	s_nop 0
	v_cndmask_b32_e32 v10, v11, v10, vcc
	v_div_scale_f32 v11, s[2:3], v10, v10, 1.0
	v_rcp_f32_e32 v18, v11
	s_add_i32 s2, s48, s93
	s_ashr_i32 s3, s2, 31
	s_lshl_b64 s[2:3], s[2:3], 2
	v_fma_f32 v19, -v11, v18, 1.0
	v_fmac_f32_e32 v18, v19, v18
	v_div_scale_f32 v19, vcc, 1.0, v10, 1.0
	v_mul_f32_e32 v38, v19, v18
	v_fma_f32 v39, -v11, v38, v19
	v_fmac_f32_e32 v38, v39, v18
	v_fma_f32 v11, -v11, v38, v19
	v_div_fmas_f32 v11, v11, v18, v38
	v_div_fixup_f32 v10, v11, v10, 1.0
	v_pk_mul_f32 v[18:19], v[10:11], v[64:65] op_sel_hi:[0,1]
	v_pk_mul_f32 v[38:39], v[76:77], v[18:19]
	v_pk_mul_f32 v[18:19], v[10:11], v[58:59] op_sel_hi:[0,1]
	v_pk_mul_f32 v[2:3], v[10:11], v[2:3] op_sel_hi:[0,1]
	v_pk_mul_f32 v[42:43], v[18:19], v[44:45]
	v_pk_mul_f32 v[18:19], v[10:11], v[66:67] op_sel_hi:[0,1]
	v_pk_mul_f32 v[2:3], v[74:75], v[2:3]
	v_pk_mul_f32 v[44:45], v[18:19], v[48:49]
	v_pk_mul_f32 v[18:19], v[102:103], v[38:39]
	v_mov_b32_e32 v58, v50
	v_pk_fma_f32 v[18:19], v[104:105], v[2:3], v[18:19]
	v_mov_b32_e32 v59, v52
	v_pk_mul_f32 v[46:47], v[18:19], s[86:87] op_sel_hi:[1,0]
	v_pk_mul_f32 v[18:19], v[12:13], v[44:45]
	v_mov_b32_e32 v52, v51
	v_pk_fma_f32 v[18:19], v[20:21], v[42:43], v[18:19]
	s_add_u32 s48, s49, s2
	v_pk_mul_f32 v[48:49], v[18:19], s[86:87] op_sel_hi:[1,0]
	v_pk_mul_f32 v[18:19], v[10:11], v[60:61] op_sel_hi:[0,1]
	v_pk_mul_f32 v[58:59], v[18:19], v[58:59]
	v_pk_mul_f32 v[18:19], v[10:11], v[68:69] op_sel_hi:[0,1]
	v_mov_b32_e32 v60, v54
	v_mov_b32_e32 v61, v56
	v_pk_mul_f32 v[60:61], v[18:19], v[60:61]
	v_pk_mul_f32 v[18:19], v[10:11], v[62:63] op_sel_hi:[0,1]
	v_pk_mul_f32 v[50:51], v[18:19], v[52:53]
	v_pk_mul_f32 v[10:11], v[10:11], v[70:71] op_sel_hi:[0,1]
	v_mov_b32_e32 v56, v55
	v_mov_b32_e32 v18, v14
	v_mov_b32_e32 v19, v16
	v_mov_b32_e32 v16, v15
	v_pk_mul_f32 v[14:15], v[104:105], v[38:39]
	v_pk_mul_f32 v[52:53], v[10:11], v[56:57]
	v_pk_fma_f32 v[2:3], v[102:103], v[2:3], v[14:15] neg_lo:[0,0,1] neg_hi:[0,0,1]
	v_pk_mul_f32 v[14:15], v[20:21], v[44:45]
	v_mov_b32_e32 v10, v6
	v_mov_b32_e32 v11, v8
	v_mov_b32_e32 v8, v7
	v_pk_fma_f32 v[14:15], v[12:13], v[42:43], v[14:15] neg_lo:[0,0,1] neg_hi:[0,0,1]
	v_pk_mul_f32 v[38:39], v[18:19], v[60:61]
	v_pk_mul_f32 v[42:43], v[16:17], v[52:53]
	v_pk_mul_f32 v[6:7], v[8:9], v[52:53]
	v_pk_mul_f32 v[14:15], v[14:15], s[86:87] op_sel_hi:[1,0]
	v_pk_fma_f32 v[38:39], v[10:11], v[58:59], v[38:39] neg_lo:[0,0,1] neg_hi:[0,0,1]
	v_pk_fma_f32 v[42:43], v[8:9], v[50:51], v[42:43] neg_lo:[0,0,1] neg_hi:[0,0,1]
	v_pk_fma_f32 v[6:7], v[16:17], v[50:51], v[6:7]
	v_pk_mul_f32 v[38:39], v[38:39], s[86:87] op_sel_hi:[1,0]
	v_pk_mul_f32 v[42:43], v[42:43], s[86:87] op_sel_hi:[1,0]
	v_bfe_u32 v50, v15, 16, 1
	v_bfe_u32 v51, v14, 16, 1
	v_pk_mul_f32 v[54:55], v[10:11], v[60:61]
	v_pk_mul_f32 v[2:3], v[2:3], s[86:87] op_sel_hi:[1,0]
	v_bfe_u32 v44, v43, 16, 1
	v_bfe_u32 v45, v42, 16, 1
	v_add3_u32 v14, v14, v51, s91
	v_add3_u32 v15, v15, v50, s91
	v_bfe_u32 v50, v38, 16, 1
	v_bfe_u32 v51, v39, 16, 1
	v_pk_fma_f32 v[54:55], v[18:19], v[58:59], v[54:55]
	v_add3_u32 v42, v42, v45, s91
	v_add3_u32 v43, v43, v44, s91
	v_bfe_u32 v44, v2, 16, 1
	v_bfe_u32 v45, v3, 16, 1
	v_add3_u32 v39, v39, v51, s91
	v_add3_u32 v38, v38, v50, s91
	v_pk_mul_f32 v[54:55], v[54:55], s[86:87] op_sel_hi:[1,0]
	v_add3_u32 v3, v3, v45, s91
	v_add3_u32 v2, v2, v44, s91
	v_lshrrev_b32_e32 v38, 16, v38
	v_lshrrev_b32_e32 v39, 16, v39
	v_pk_mul_f32 v[6:7], v[6:7], s[86:87] op_sel_hi:[1,0]
	v_lshrrev_b32_e32 v2, 16, v2
	v_lshrrev_b32_e32 v3, 16, v3
	v_and_or_b32 v115, v43, s33, v39
	v_and_or_b32 v114, v42, s33, v38
	v_bfe_u32 v38, v54, 16, 1
	v_bfe_u32 v39, v55, 16, 1
	v_and_or_b32 v113, v15, s33, v3
	v_and_or_b32 v112, v14, s33, v2
	v_bfe_u32 v2, v7, 16, 1
	v_bfe_u32 v3, v6, 16, 1
	v_add3_u32 v39, v55, v39, s91
	v_add3_u32 v38, v54, v38, s91
	v_add3_u32 v3, v6, v3, s91
	v_add3_u32 v2, v7, v2, s91
	v_lshrrev_b32_e32 v38, 16, v38
	v_lshrrev_b32_e32 v39, 16, v39
	v_and_or_b32 v119, v2, s33, v39
	v_and_or_b32 v118, v3, s33, v38
	ds_read_b128 v[38:41], v100
	ds_read_b128 v[42:45], v100 offset:64
	v_bfe_u32 v6, v46, 16, 1
	v_bfe_u32 v7, v47, 16, 1
	s_waitcnt lgkmcnt(1)
	v_mfma_f32_16x16x32_bf16 v[38:41], v[38:41], v[112:115], 0
	v_bfe_u32 v14, v49, 16, 1
	v_bfe_u32 v15, v48, 16, 1
	v_add3_u32 v7, v47, v7, s91
	v_add3_u32 v6, v46, v6, s91
	v_add3_u32 v15, v48, v15, s91
	v_add3_u32 v14, v49, v14, s91
	v_lshrrev_b32_e32 v6, 16, v6
	v_lshrrev_b32_e32 v7, 16, v7
	v_and_or_b32 v117, v14, s33, v7
	v_and_or_b32 v116, v15, s33, v6
	s_addc_u32 s49, s88, s3
	s_nop 1
	v_mov_b64_e32 v[148:149], s[48:49]
	global_load_dword v150, v[148:149], off
	v_mov_b64_e32 v[2:3], s[48:49]
	s_waitcnt lgkmcnt(0)
	v_mfma_f32_16x16x32_bf16 v[74:77], v[42:45], v[116:119], v[38:41]
	ds_read_b128 v[42:45], v98 offset:64
	s_waitcnt vmcnt(0)
	s_nop 0
	v_mov_b32_e32 v3, v150
	s_nop 1
	v_mov_b32_e32 v2, s94
	ds_read_b128 v[38:41], v98
	s_waitcnt lgkmcnt(0)
	v_mfma_f32_16x16x32_bf16 v[38:41], v[38:41], v[112:115], 0
	s_nop 1
	v_cndmask_b32_e64 v15, v74, v2, s[40:41]
	s_mov_b64 s[40:41], s[42:43]
	v_mfma_f32_16x16x32_bf16 v[70:73], v[42:45], v[116:119], v[38:41]
	ds_read_b128 v[42:45], v96 offset:64
	v_writelane_b32 v255, s40, 22
	v_cndmask_b32_e64 v14, v75, v227, s[42:43]
	ds_read_b128 v[38:41], v96
	s_waitcnt lgkmcnt(0)
	v_mfma_f32_16x16x32_bf16 v[38:41], v[38:41], v[112:115], 0
	v_writelane_b32 v255, s41, 23
	v_max3_f32 v2, v15, s94, v14
	v_readlane_b32 s80, v255, 2
	v_mfma_f32_16x16x32_bf16 v[66:69], v[42:45], v[116:119], v[38:41]
	ds_read_b128 v[42:45], v94 offset:64
	v_readlane_b32 s42, v255, 4
	v_readlane_b32 s81, v255, 3
	s_nop 0
	ds_read_b128 v[38:41], v94
	s_waitcnt lgkmcnt(0)
	v_mfma_f32_16x16x32_bf16 v[38:41], v[38:41], v[112:115], 0
	v_readlane_b32 s43, v255, 5
	v_cndmask_b32_e64 v7, v76, v227, s[80:81]
	v_mfma_f32_16x16x32_bf16 v[62:65], v[42:45], v[116:119], v[38:41]
	ds_read_b128 v[42:45], v92 offset:64
	v_cndmask_b32_e64 v6, v77, v227, s[42:43]
	v_readlane_b32 s48, v255, 6
	s_nop 1
	ds_read_b128 v[38:41], v92
	s_waitcnt lgkmcnt(0)
	v_mfma_f32_16x16x32_bf16 v[38:41], v[38:41], v[112:115], 0
	v_max3_f32 v76, v2, v7, v6
	v_mov_b32_e32 v2, s94
	v_readlane_b32 s49, v255, 7
	v_mfma_f32_16x16x32_bf16 v[58:61], v[42:45], v[116:119], v[38:41]
	ds_read_b128 v[42:45], v90 offset:64
	v_cndmask_b32_e64 v75, v70, v2, s[48:49]
	v_cndmask_b32_e64 v74, v71, v227, s[6:7]
	s_nop 0
	ds_read_b128 v[38:41], v90
	s_waitcnt lgkmcnt(0)
	v_mfma_f32_16x16x32_bf16 v[38:41], v[38:41], v[112:115], 0
	v_max3_f32 v2, v76, v75, v74
	v_cndmask_b32_e64 v71, v72, v227, s[4:5]
	v_mfma_f32_16x16x32_bf16 v[54:57], v[42:45], v[116:119], v[38:41]
	ds_read_b128 v[42:45], v88 offset:64
	v_cndmask_b32_e64 v70, v73, v227, s[44:45]
	v_readlane_b32 s4, v255, 12
	s_nop 1
	ds_read_b128 v[38:41], v88
	s_waitcnt lgkmcnt(0)
	v_mfma_f32_16x16x32_bf16 v[38:41], v[38:41], v[112:115], 0
	v_max3_f32 v76, v2, v71, v70
	v_mov_b32_e32 v2, s94
	v_readlane_b32 s5, v255, 13
	v_mfma_f32_16x16x32_bf16 v[50:53], v[42:45], v[116:119], v[38:41]
	ds_read_b128 v[42:45], v86 offset:64
	v_cndmask_b32_e64 v73, v66, v2, s[4:5]
	v_cndmask_b32_e64 v72, v67, v227, s[12:13]
	s_nop 0
	ds_read_b128 v[38:41], v86
	s_waitcnt lgkmcnt(0)
	v_mfma_f32_16x16x32_bf16 v[38:41], v[38:41], v[112:115], 0
	v_max3_f32 v2, v76, v73, v72
	v_cndmask_b32_e64 v67, v68, v227, s[10:11]
	v_mfma_f32_16x16x32_bf16 v[46:49], v[42:45], v[116:119], v[38:41]
	ds_read_b128 v[42:45], v84 offset:64
	v_cndmask_b32_e64 v66, v69, v227, s[8:9]
	v_max3_f32 v76, v2, v67, v66
	s_nop 1
	ds_read_b128 v[38:41], v84
	s_waitcnt lgkmcnt(0)
	v_mfma_f32_16x16x32_bf16 v[38:41], v[38:41], v[112:115], 0
	v_mov_b32_e32 v2, s94
	v_cndmask_b32_e64 v69, v62, v2, s[20:21]
	v_cndmask_b32_e64 v68, v63, v227, s[18:19]
	v_mfma_f32_16x16x32_bf16 v[42:45], v[42:45], v[116:119], v[38:41]
	v_max3_f32 v2, v76, v69, v68
	v_cndmask_b32_e64 v63, v64, v227, s[16:17]
	v_cndmask_b32_e64 v62, v65, v227, s[14:15]
	s_nop 0
	ds_read_b128 v[38:41], v82
	v_max3_f32 v76, v2, v63, v62
	v_mov_b32_e32 v2, s94
	v_cndmask_b32_e64 v65, v58, v2, s[28:29]
	v_cndmask_b32_e64 v64, v59, v227, s[24:25]
	v_max3_f32 v2, v76, v65, v64
	v_cndmask_b32_e64 v59, v60, v227, s[22:23]
	v_cndmask_b32_e64 v58, v61, v227, s[26:27]
	s_waitcnt lgkmcnt(0)
	v_mfma_f32_16x16x32_bf16 v[38:41], v[38:41], v[112:115], 0
	ds_read_b128 v[112:115], v82 offset:64
	v_max3_f32 v76, v2, v59, v58
	v_mov_b32_e32 v2, s94
	v_cndmask_b32_e64 v61, v54, v2, s[38:39]
	v_cndmask_b32_e64 v60, v55, v227, s[30:31]
	v_max3_f32 v2, v76, v61, v60
	v_cndmask_b32_e64 v55, v56, v227, s[34:35]
	v_cndmask_b32_e64 v54, v57, v227, s[36:37]
	v_max3_f32 v76, v2, v55, v54
	v_mov_b32_e32 v2, s94
	v_cndmask_b32_e64 v57, v50, v2, s[54:55]
	v_cndmask_b32_e64 v56, v51, v227, s[46:47]
	v_max3_f32 v2, v76, v57, v56
	v_cndmask_b32_e64 v51, v52, v227, s[50:51]
	v_cndmask_b32_e64 v50, v53, v227, s[52:53]
	v_max3_f32 v76, v2, v51, v50
	v_mov_b32_e32 v2, s94
	v_cndmask_b32_e64 v53, v46, v2, s[62:63]
	v_cndmask_b32_e64 v52, v47, v227, s[56:57]
	v_max3_f32 v2, v76, v53, v52
	v_cndmask_b32_e64 v47, v48, v227, s[58:59]
	v_cndmask_b32_e64 v46, v49, v227, s[60:61]
	s_waitcnt lgkmcnt(0)
	v_mfma_f32_16x16x32_bf16 v[38:41], v[112:115], v[116:119], v[38:41]
	v_max3_f32 v76, v2, v47, v46
	v_mov_b32_e32 v2, s94
	v_cndmask_b32_e64 v49, v42, v2, s[70:71]
	v_cndmask_b32_e64 v48, v43, v227, s[64:65]
	v_max3_f32 v2, v76, v49, v48
	v_cndmask_b32_e64 v43, v44, v227, s[66:67]
	v_cndmask_b32_e64 v42, v45, v227, s[68:69]
	s_mov_b64 s[4:5], s[24:25]
	v_max3_f32 v44, v2, v43, v42
	v_mov_b32_e32 v2, s94
	s_mov_b64 s[24:25], s[78:79]
	s_mov_b64 s[70:71], s[76:77]
	v_cndmask_b32_e64 v2, v38, v2, s[24:25]
	v_cndmask_b32_e64 v38, v39, v227, s[70:71]
	v_max3_f32 v39, v44, v2, v38
	v_cndmask_b32_e64 v40, v40, v227, s[72:73]
	v_cndmask_b32_e64 v41, v41, v227, s[74:75]
	v_max3_f32 v39, v39, v40, v41
	ds_bpermute_b32 v44, v109, v39
	s_mov_b32 s93, s95
	s_mov_b32 s6, 0xf800000
	v_readlane_b32 s8, v255, 0
	s_waitcnt lgkmcnt(0)
	v_max_f32_e32 v44, v44, v44
	v_max_f32_e32 v39, v39, v44
	ds_bpermute_b32 v44, v110, v39
	v_readlane_b32 s9, v255, 1
	v_readlane_b32 s18, v255, 6
	v_readlane_b32 s10, v255, 8
	v_readlane_b32 s19, v255, 7
	s_waitcnt vmcnt(0) lgkmcnt(0)
	v_max3_f32 v39, v39, v44, v3
	v_sub_f32_e32 v15, v15, v39
	v_mul_f32_e32 v15, 0x3fb8aa3b, v15
	v_sub_f32_e32 v14, v14, v39
	v_exp_f32_e32 v15, v15
	v_mul_f32_e32 v14, 0x3fb8aa3b, v14
	v_sub_f32_e32 v7, v7, v39
	v_exp_f32_e32 v14, v14
	v_mul_f32_e32 v7, 0x3fb8aa3b, v7
	v_sub_f32_e32 v6, v6, v39
	v_exp_f32_e32 v7, v7
	v_mul_f32_e32 v6, 0x3fb8aa3b, v6
	v_sub_f32_e32 v45, v75, v39
	v_exp_f32_e32 v6, v6
	v_mul_f32_e32 v45, 0x3fb8aa3b, v45
	v_sub_f32_e32 v74, v74, v39
	v_add_f32_e32 v44, 0, v15
	v_exp_f32_e32 v45, v45
	v_mul_f32_e32 v74, 0x3fb8aa3b, v74
	v_sub_f32_e32 v71, v71, v39
	v_add_f32_e32 v44, v14, v44
	v_exp_f32_e32 v74, v74
	v_mul_f32_e32 v71, 0x3fb8aa3b, v71
	v_sub_f32_e32 v70, v70, v39
	v_add_f32_e32 v44, v7, v44
	v_exp_f32_e32 v71, v71
	v_mul_f32_e32 v70, 0x3fb8aa3b, v70
	v_sub_f32_e32 v73, v73, v39
	v_add_f32_e32 v44, v6, v44
	v_exp_f32_e32 v70, v70
	v_mul_f32_e32 v73, 0x3fb8aa3b, v73
	v_sub_f32_e32 v72, v72, v39
	v_add_f32_e32 v44, v45, v44
	v_exp_f32_e32 v75, v73
	v_mul_f32_e32 v72, 0x3fb8aa3b, v72
	v_sub_f32_e32 v67, v67, v39
	v_add_f32_e32 v44, v74, v44
	v_exp_f32_e32 v76, v72
	v_mul_f32_e32 v67, 0x3fb8aa3b, v67
	v_sub_f32_e32 v66, v66, v39
	v_add_f32_e32 v44, v71, v44
	v_exp_f32_e32 v67, v67
	v_mul_f32_e32 v66, 0x3fb8aa3b, v66
	v_sub_f32_e32 v69, v69, v39
	v_add_f32_e32 v44, v70, v44
	v_exp_f32_e32 v66, v66
	v_mul_f32_e32 v69, 0x3fb8aa3b, v69
	v_sub_f32_e32 v68, v68, v39
	v_add_f32_e32 v44, v75, v44
	v_exp_f32_e32 v69, v69
	v_mul_f32_e32 v68, 0x3fb8aa3b, v68
	v_sub_f32_e32 v63, v63, v39
	v_add_f32_e32 v44, v76, v44
	v_exp_f32_e32 v68, v68
	v_mul_f32_e32 v63, 0x3fb8aa3b, v63
	v_sub_f32_e32 v62, v62, v39
	v_add_f32_e32 v44, v67, v44
	v_exp_f32_e32 v63, v63
	v_mul_f32_e32 v62, 0x3fb8aa3b, v62
	v_sub_f32_e32 v65, v65, v39
	v_add_f32_e32 v44, v66, v44
	v_exp_f32_e32 v62, v62
	v_mul_f32_e32 v65, 0x3fb8aa3b, v65
	v_sub_f32_e32 v64, v64, v39
	v_sub_f32_e32 v58, v58, v39
	v_add_f32_e32 v44, v69, v44
	v_exp_f32_e32 v65, v65
	v_mul_f32_e32 v64, 0x3fb8aa3b, v64
	v_sub_f32_e32 v59, v59, v39
	v_mul_f32_e32 v58, 0x3fb8aa3b, v58
	v_add_f32_e32 v44, v68, v44
	v_exp_f32_e32 v64, v64
	v_mul_f32_e32 v59, 0x3fb8aa3b, v59
	v_exp_f32_e32 v93, v58
	v_sub_f32_e32 v58, v61, v39
	v_add_f32_e32 v44, v63, v44
	v_exp_f32_e32 v77, v59
	v_mul_f32_e32 v58, 0x3fb8aa3b, v58
	v_add_f32_e32 v44, v62, v44
	v_exp_f32_e32 v95, v58
	v_sub_f32_e32 v58, v60, v39
	v_sub_f32_e32 v54, v54, v39
	v_add_f32_e32 v44, v65, v44
	v_mul_f32_e32 v58, 0x3fb8aa3b, v58
	v_sub_f32_e32 v55, v55, v39
	v_mul_f32_e32 v54, 0x3fb8aa3b, v54
	v_add_f32_e32 v44, v64, v44
	v_exp_f32_e32 v97, v58
	v_mul_f32_e32 v55, 0x3fb8aa3b, v55
	v_exp_f32_e32 v101, v54
	v_sub_f32_e32 v54, v57, v39
	v_add_f32_e32 v44, v77, v44
	v_exp_f32_e32 v99, v55
	v_mul_f32_e32 v54, 0x3fb8aa3b, v54
	v_add_f32_e32 v44, v93, v44
	v_exp_f32_e32 v111, v54
	v_sub_f32_e32 v54, v56, v39
	v_sub_f32_e32 v50, v50, v39
	v_add_f32_e32 v44, v95, v44
	v_mul_f32_e32 v54, 0x3fb8aa3b, v54
	v_sub_f32_e32 v51, v51, v39
	v_mul_f32_e32 v50, 0x3fb8aa3b, v50
	v_add_f32_e32 v44, v97, v44
	v_exp_f32_e32 v112, v54
	v_mul_f32_e32 v51, 0x3fb8aa3b, v51
	v_exp_f32_e32 v114, v50
	v_sub_f32_e32 v50, v53, v39
	v_add_f32_e32 v44, v99, v44
	v_exp_f32_e32 v113, v51
	v_mul_f32_e32 v50, 0x3fb8aa3b, v50
	v_add_f32_e32 v44, v101, v44
	v_exp_f32_e32 v115, v50
	v_sub_f32_e32 v50, v52, v39
	v_sub_f32_e32 v46, v46, v39
	v_add_f32_e32 v44, v111, v44
	v_mul_f32_e32 v50, 0x3fb8aa3b, v50
	v_sub_f32_e32 v47, v47, v39
	v_mul_f32_e32 v46, 0x3fb8aa3b, v46
	v_add_f32_e32 v44, v112, v44
	v_exp_f32_e32 v116, v50
	v_mul_f32_e32 v47, 0x3fb8aa3b, v47
	v_exp_f32_e32 v118, v46
	v_sub_f32_e32 v46, v49, v39
	v_add_f32_e32 v44, v113, v44
	v_exp_f32_e32 v117, v47
	v_mul_f32_e32 v46, 0x3fb8aa3b, v46
	v_add_f32_e32 v44, v114, v44
	v_exp_f32_e32 v119, v46
	v_sub_f32_e32 v46, v48, v39
	v_add_f32_e32 v44, v115, v44
	v_mul_f32_e32 v46, 0x3fb8aa3b, v46
	v_sub_f32_e32 v43, v43, v39
	v_add_f32_e32 v44, v116, v44
	v_exp_f32_e32 v120, v46
	v_mul_f32_e32 v43, 0x3fb8aa3b, v43
	v_sub_f32_e32 v42, v42, v39
	v_sub_f32_e32 v38, v38, v39
	v_add_f32_e32 v44, v117, v44
	v_exp_f32_e32 v121, v43
	v_mul_f32_e32 v42, 0x3fb8aa3b, v42
	v_sub_f32_e32 v2, v2, v39
	v_mul_f32_e32 v38, 0x3fb8aa3b, v38
	v_add_f32_e32 v44, v118, v44
	v_exp_f32_e32 v122, v42
	v_mul_f32_e32 v2, 0x3fb8aa3b, v2
	v_exp_f32_e32 v124, v38
	v_sub_f32_e32 v38, v40, v39
	v_add_f32_e32 v44, v119, v44
	v_exp_f32_e32 v123, v2
	v_mul_f32_e32 v38, 0x3fb8aa3b, v38
	v_add_f32_e32 v44, v120, v44
	v_exp_f32_e32 v125, v38
	v_sub_f32_e32 v38, v41, v39
	v_add_f32_e32 v43, v121, v44
	v_mul_f32_e32 v38, 0x3fb8aa3b, v38
	v_add_f32_e32 v42, v122, v43
	v_exp_f32_e32 v126, v38
	v_add_f32_e32 v2, v123, v42
	v_add_f32_e32 v2, v124, v2
	v_add_f32_e32 v2, v125, v2
	v_add_f32_e32 v2, v126, v2
	ds_bpermute_b32 v38, v109, v2
	v_sub_f32_e32 v3, v3, v39
	v_mul_f32_e32 v3, 0x3fb8aa3b, v3
	v_exp_f32_e32 v3, v3
	v_bfe_u32 v40, v14, 16, 1
	s_waitcnt lgkmcnt(0)
	v_add_f32_e32 v2, v2, v38
	ds_bpermute_b32 v38, v110, v2
	v_bfe_u32 v42, v71, 16, 1
	v_add3_u32 v14, v14, v40, s91
	v_bfe_u32 v40, v7, 16, 1
	v_bfe_u32 v41, v45, 16, 1
	s_waitcnt lgkmcnt(0)
	v_add_f32_e32 v2, v2, v38
	v_add_f32_e32 v2, v3, v2
	v_bfe_u32 v3, v70, 16, 1
	v_add3_u32 v3, v70, v3, s91
	v_add3_u32 v42, v71, v42, s91
	v_add_u32_e32 v73, 0x9000, v91
	v_add_u32_e32 v72, 0xb000, v91
	v_add_u32_e32 v71, 0xd000, v91
	v_add_u32_e32 v70, 0xf000, v91
	v_add3_u32 v41, v45, v41, s91
	v_add3_u32 v7, v7, v40, s91
	v_lshrrev_b32_e32 v40, 16, v42
	ds_read2_b64 v[42:45], v73 offset1:4
	ds_read2_b64 v[46:49], v72 offset0:32 offset1:36
	ds_read2_b64 v[50:53], v71 offset0:64 offset1:68
	ds_read2_b64 v[54:57], v70 offset0:96 offset1:100
	v_bfe_u32 v39, v6, 16, 1
	v_add3_u32 v6, v6, v39, s91
	v_bfe_u32 v39, v15, 16, 1
	v_bfe_u32 v38, v74, 16, 1
	v_add3_u32 v15, v15, v39, s91
	v_add3_u32 v38, v74, v38, s91
	v_lshrrev_b32_e32 v15, 16, v15
	v_lshrrev_b32_e32 v7, 16, v7
	v_lshrrev_b32_e32 v39, 16, v41
	v_and_or_b32 v41, v3, s33, v40
	v_and_or_b32 v40, v38, s33, v39
	v_and_or_b32 v39, v6, s33, v7
	v_and_or_b32 v38, v14, s33, v15
	v_bfe_u32 v15, v75, 16, 1
	v_bfe_u32 v3, v62, 16, 1
	s_waitcnt lgkmcnt(3)
	v_mfma_f32_16x16x32_bf16 v[42:45], v[42:45], v[38:41], 0
	v_bfe_u32 v6, v68, 16, 1
	v_bfe_u32 v7, v66, 16, 1
	v_bfe_u32 v14, v76, 16, 1
	s_waitcnt lgkmcnt(2)
	v_mfma_f32_16x16x32_bf16 v[46:49], v[46:49], v[38:41], 0
	v_add3_u32 v15, v75, v15, s91
	v_add3_u32 v14, v76, v14, s91
	v_add3_u32 v7, v66, v7, s91
	s_waitcnt lgkmcnt(1)
	v_mfma_f32_16x16x32_bf16 v[50:53], v[50:53], v[38:41], 0
	v_add3_u32 v6, v68, v6, s91
	v_add3_u32 v3, v62, v3, s91
	v_lshrrev_b32_e32 v15, 16, v15
	s_waitcnt lgkmcnt(0)
	v_mfma_f32_16x16x32_bf16 v[38:41], v[54:57], v[38:41], 0
	v_bfe_u32 v55, v69, 16, 1
	v_add3_u32 v55, v69, v55, s91
	v_add_u32_e32 v69, 0x9000, v89
	ds_read2_b64 v[58:61], v69 offset1:4
	v_bfe_u32 v54, v67, 16, 1
	v_bfe_u32 v56, v63, 16, 1
	v_add3_u32 v56, v63, v56, s91
	v_add3_u32 v54, v67, v54, s91
	v_lshrrev_b32_e32 v54, 16, v54
	v_lshrrev_b32_e32 v55, 16, v55
	v_lshrrev_b32_e32 v56, 16, v56
	v_and_or_b32 v57, v3, s33, v56
	v_and_or_b32 v56, v6, s33, v55
	v_and_or_b32 v55, v7, s33, v54
	v_and_or_b32 v54, v14, s33, v15
	v_add_u32_e32 v68, 0xb000, v89
	v_add_u32_e32 v67, 0xd000, v89
	s_waitcnt lgkmcnt(0)
	v_mfma_f32_16x16x32_bf16 v[42:45], v[58:61], v[54:57], v[42:45]
	ds_read2_b64 v[58:61], v68 offset0:32 offset1:36
	v_add_u32_e32 v66, 0xf000, v89
	v_bfe_u32 v15, v65, 16, 1
	s_waitcnt lgkmcnt(0)
	v_mfma_f32_16x16x32_bf16 v[46:49], v[58:61], v[54:57], v[46:49]
	ds_read2_b64 v[58:61], v67 offset0:64 offset1:68
	v_add3_u32 v15, v65, v15, s91
	v_add_u32_e32 v65, 0x9000, v87
	s_waitcnt lgkmcnt(0)
	v_mfma_f32_16x16x32_bf16 v[50:53], v[58:61], v[54:57], v[50:53]
	ds_read2_b64 v[58:61], v66 offset0:96 offset1:100
	v_bfe_u32 v3, v101, 16, 1
	s_waitcnt lgkmcnt(0)
	v_mfma_f32_16x16x32_bf16 v[38:41], v[58:61], v[54:57], v[38:41]
	ds_read2_b64 v[58:61], v65 offset1:4
	v_bfe_u32 v54, v77, 16, 1
	v_bfe_u32 v55, v95, 16, 1
	v_bfe_u32 v56, v99, 16, 1
	v_bfe_u32 v6, v97, 16, 1
	v_bfe_u32 v7, v93, 16, 1
	v_bfe_u32 v14, v64, 16, 1
	v_add3_u32 v56, v99, v56, s91
	v_add3_u32 v55, v95, v55, s91
	v_add3_u32 v54, v77, v54, s91
	v_add3_u32 v14, v64, v14, s91
	v_add3_u32 v7, v93, v7, s91
	v_add3_u32 v6, v97, v6, s91
	v_add3_u32 v3, v101, v3, s91
	v_lshrrev_b32_e32 v15, 16, v15
	v_lshrrev_b32_e32 v54, 16, v54
	v_lshrrev_b32_e32 v55, 16, v55
	v_lshrrev_b32_e32 v56, 16, v56
	v_and_or_b32 v57, v3, s33, v56
	v_and_or_b32 v56, v6, s33, v55
	v_and_or_b32 v55, v7, s33, v54
	v_and_or_b32 v54, v14, s33, v15
	v_add_u32_e32 v64, 0xb000, v87
	v_add_u32_e32 v63, 0xd000, v87
	s_waitcnt lgkmcnt(0)
	v_mfma_f32_16x16x32_bf16 v[42:45], v[58:61], v[54:57], v[42:45]
	ds_read2_b64 v[58:61], v64 offset0:32 offset1:36
	v_add_u32_e32 v62, 0xf000, v87
	v_bfe_u32 v15, v111, 16, 1
	s_waitcnt lgkmcnt(0)
	v_mfma_f32_16x16x32_bf16 v[46:49], v[58:61], v[54:57], v[46:49]
	ds_read2_b64 v[58:61], v63 offset0:64 offset1:68
	v_bfe_u32 v3, v118, 16, 1
	v_bfe_u32 v6, v116, 16, 1
	s_waitcnt lgkmcnt(0)
	v_mfma_f32_16x16x32_bf16 v[50:53], v[58:61], v[54:57], v[50:53]
	ds_read2_b64 v[58:61], v62 offset0:96 offset1:100
	v_bfe_u32 v7, v114, 16, 1
	s_waitcnt lgkmcnt(0)
	v_mfma_f32_16x16x32_bf16 v[38:41], v[58:61], v[54:57], v[38:41]
	v_add_u32_e32 v61, 0x9000, v85
	ds_read2_b64 v[74:77], v61 offset1:4
	v_bfe_u32 v54, v113, 16, 1
	v_bfe_u32 v55, v115, 16, 1
	v_bfe_u32 v56, v117, 16, 1
	v_bfe_u32 v14, v112, 16, 1
	v_add3_u32 v56, v117, v56, s91
	v_add3_u32 v55, v115, v55, s91
	v_add3_u32 v54, v113, v54, s91
	v_add3_u32 v15, v111, v15, s91
	v_add3_u32 v14, v112, v14, s91
	v_add3_u32 v7, v114, v7, s91
	v_add3_u32 v6, v116, v6, s91
	v_add3_u32 v3, v118, v3, s91
	v_lshrrev_b32_e32 v15, 16, v15
	v_lshrrev_b32_e32 v54, 16, v54
	v_lshrrev_b32_e32 v55, 16, v55
	v_lshrrev_b32_e32 v56, 16, v56
	v_and_or_b32 v57, v3, s33, v56
	v_and_or_b32 v56, v6, s33, v55
	v_and_or_b32 v55, v7, s33, v54
	v_and_or_b32 v54, v14, s33, v15
	v_add_u32_e32 v60, 0xb000, v85
	v_add_u32_e32 v59, 0xd000, v85
	s_waitcnt lgkmcnt(0)
	v_mfma_f32_16x16x32_bf16 v[42:45], v[74:77], v[54:57], v[42:45]
	ds_read2_b64 v[74:77], v60 offset0:32 offset1:36
	v_add_u32_e32 v58, 0xf000, v85
	v_bfe_u32 v3, v126, 16, 1
	s_waitcnt lgkmcnt(0)
	v_mfma_f32_16x16x32_bf16 v[46:49], v[74:77], v[54:57], v[46:49]
	ds_read2_b64 v[74:77], v59 offset0:64 offset1:68
	v_bfe_u32 v6, v124, 16, 1
	v_bfe_u32 v7, v122, 16, 1
	s_waitcnt lgkmcnt(0)
	v_mfma_f32_16x16x32_bf16 v[74:77], v[74:77], v[54:57], v[50:53]
	s_nop 2
	ds_read2_b64 v[50:53], v58 offset0:96 offset1:100
	v_add3_u32 v7, v122, v7, s91
	s_waitcnt lgkmcnt(0)
	v_mfma_f32_16x16x32_bf16 v[38:41], v[50:53], v[54:57], v[38:41]
	v_bfe_u32 v50, v121, 16, 1
	v_bfe_u32 v51, v123, 16, 1
	v_bfe_u32 v52, v125, 16, 1
	v_add3_u32 v52, v125, v52, s91
	v_add3_u32 v51, v123, v51, s91
	v_add3_u32 v50, v121, v50, s91
	v_add3_u32 v6, v124, v6, s91
	v_add3_u32 v3, v126, v3, s91
	v_lshrrev_b32_e32 v50, 16, v50
	v_lshrrev_b32_e32 v51, 16, v51
	v_lshrrev_b32_e32 v52, 16, v52
	v_add_u32_e32 v57, 0x9000, v83
	v_and_or_b32 v115, v3, s33, v52
	v_and_or_b32 v114, v6, s33, v51
	v_and_or_b32 v113, v7, s33, v50
	ds_read2_b64 v[50:53], v57 offset1:4
	v_bfe_u32 v15, v119, 16, 1
	v_bfe_u32 v14, v120, 16, 1
	v_add3_u32 v15, v119, v15, s91
	v_add3_u32 v14, v120, v14, s91
	v_lshrrev_b32_e32 v15, 16, v15
	v_and_or_b32 v112, v14, s33, v15
	v_add_u32_e32 v56, 0xb000, v83
	v_div_scale_f32 v3, s[48:49], v2, v2, 1.0
	s_waitcnt lgkmcnt(0)
	v_mfma_f32_16x16x32_bf16 v[50:53], v[50:53], v[112:115], v[42:45]
	v_rcp_f32_e32 v6, v3
	v_add_u32_e32 v55, 0xd000, v83
	v_add_u32_e32 v54, 0xf000, v83
	ds_read2_b64 v[42:45], v56 offset0:32 offset1:36
	v_fma_f32 v7, -v3, v6, 1.0
	v_fmac_f32_e32 v6, v7, v6
	v_div_scale_f32 v7, vcc, 1.0, v2, 1.0
	v_mul_f32_e32 v14, v7, v6
	v_fma_f32 v15, -v3, v14, v7
	v_fmac_f32_e32 v14, v15, v6
	s_waitcnt lgkmcnt(0)
	v_mfma_f32_16x16x32_bf16 v[46:49], v[42:45], v[112:115], v[46:49]
	ds_read2_b64 v[42:45], v55 offset0:64 offset1:68
	v_fma_f32 v3, -v3, v14, v7
	v_div_fmas_f32 v3, v3, v6, v14
	v_div_fixup_f32 v6, v3, v2, 1.0
	v_mov_b32_e32 v14, v50
	v_mov_b32_e32 v15, v52
	v_pk_mul_f32 v[14:15], v[6:7], v[14:15] op_sel_hi:[0,1]
	v_mov_b32_e32 v52, v51
	v_pk_mul_f32 v[50:51], v[6:7], v[52:53] op_sel_hi:[0,1]
	v_and_b32_sdwa v7, v15, v218 dst_sel:DWORD dst_unused:UNUSED_PAD src0_sel:WORD_1 src1_sel:DWORD
	v_and_b32_sdwa v52, v14, v218 dst_sel:DWORD dst_unused:UNUSED_PAD src0_sel:WORD_1 src1_sel:DWORD
	v_add3_u32 v14, v14, v52, s91
	v_add3_u32 v7, v15, v7, s91
	v_and_b32_sdwa v15, v51, v218 dst_sel:DWORD dst_unused:UNUSED_PAD src0_sel:WORD_1 src1_sel:DWORD
	v_and_b32_sdwa v52, v50, v218 dst_sel:DWORD dst_unused:UNUSED_PAD src0_sel:WORD_1 src1_sel:DWORD
	v_add3_u32 v15, v51, v15, s91
	v_add3_u32 v50, v50, v52, s91
	v_and_b32_e32 v15, 0xffff0000, v15
	v_and_b32_e32 v50, 0xffff0000, v50
	v_lshl_add_u64 v[2:3], v[80:81], 0, s[92:93]
	v_or_b32_sdwa v15, v15, v7 dst_sel:DWORD dst_unused:UNUSED_PAD src0_sel:DWORD src1_sel:WORD_1
	v_or_b32_sdwa v14, v50, v14 dst_sel:DWORD dst_unused:UNUSED_PAD src0_sel:DWORD src1_sel:WORD_1
	s_waitcnt lgkmcnt(0)
	v_mfma_f32_16x16x32_bf16 v[42:45], v[42:45], v[112:115], v[74:77]
	s_mov_b64 s[92:93], s[42:43]
	v_readlane_b32 s11, v255, 9
	v_readlane_b32 s12, v255, 10
	ds_read2_b64 v[74:77], v54 offset0:96 offset1:100
	flat_store_dwordx2 v[2:3], v[14:15]
	v_mov_b32_e32 v14, v46
	v_mov_b32_e32 v15, v48
	v_pk_mul_f32 v[14:15], v[6:7], v[14:15] op_sel_hi:[0,1]
	v_mov_b32_e32 v48, v47
	v_pk_mul_f32 v[46:47], v[6:7], v[48:49] op_sel_hi:[0,1]
	v_and_b32_sdwa v7, v15, v218 dst_sel:DWORD dst_unused:UNUSED_PAD src0_sel:WORD_1 src1_sel:DWORD
	v_and_b32_sdwa v48, v14, v218 dst_sel:DWORD dst_unused:UNUSED_PAD src0_sel:WORD_1 src1_sel:DWORD
	v_add3_u32 v14, v14, v48, s91
	v_add3_u32 v7, v15, v7, s91
	v_and_b32_sdwa v15, v47, v218 dst_sel:DWORD dst_unused:UNUSED_PAD src0_sel:WORD_1 src1_sel:DWORD
	v_and_b32_sdwa v48, v46, v218 dst_sel:DWORD dst_unused:UNUSED_PAD src0_sel:WORD_1 src1_sel:DWORD
	v_add3_u32 v15, v47, v15, s91
	v_add3_u32 v46, v46, v48, s91
	v_and_b32_e32 v15, 0xffff0000, v15
	v_and_b32_e32 v46, 0xffff0000, v46
	v_or_b32_sdwa v15, v15, v7 dst_sel:DWORD dst_unused:UNUSED_PAD src0_sel:DWORD src1_sel:WORD_1
	v_or_b32_sdwa v14, v46, v14 dst_sel:DWORD dst_unused:UNUSED_PAD src0_sel:DWORD src1_sel:WORD_1
	flat_store_dwordx2 v[2:3], v[14:15] offset:32
	v_mov_b32_e32 v14, v42
	v_mov_b32_e32 v15, v44
	v_pk_mul_f32 v[14:15], v[6:7], v[14:15] op_sel_hi:[0,1]
	v_mov_b32_e32 v44, v43
	v_pk_mul_f32 v[42:43], v[6:7], v[44:45] op_sel_hi:[0,1]
	v_and_b32_sdwa v7, v15, v218 dst_sel:DWORD dst_unused:UNUSED_PAD src0_sel:WORD_1 src1_sel:DWORD
	v_and_b32_sdwa v44, v14, v218 dst_sel:DWORD dst_unused:UNUSED_PAD src0_sel:WORD_1 src1_sel:DWORD
	s_waitcnt lgkmcnt(0)
	v_mfma_f32_16x16x32_bf16 v[38:41], v[74:77], v[112:115], v[38:41]
	v_add3_u32 v14, v14, v44, s91
	v_add3_u32 v7, v15, v7, s91
	v_and_b32_sdwa v15, v43, v218 dst_sel:DWORD dst_unused:UNUSED_PAD src0_sel:WORD_1 src1_sel:DWORD
	v_and_b32_sdwa v44, v42, v218 dst_sel:DWORD dst_unused:UNUSED_PAD src0_sel:WORD_1 src1_sel:DWORD
	v_add3_u32 v15, v43, v15, s91
	v_add3_u32 v42, v42, v44, s91
	v_and_b32_e32 v15, 0xffff0000, v15
	v_and_b32_e32 v42, 0xffff0000, v42
	v_or_b32_sdwa v15, v15, v7 dst_sel:DWORD dst_unused:UNUSED_PAD src0_sel:DWORD src1_sel:WORD_1
	v_or_b32_sdwa v14, v42, v14 dst_sel:DWORD dst_unused:UNUSED_PAD src0_sel:DWORD src1_sel:WORD_1
	flat_store_dwordx2 v[2:3], v[14:15] offset:64
	v_mov_b32_e32 v14, v38
	v_mov_b32_e32 v15, v40
	v_pk_mul_f32 v[14:15], v[6:7], v[14:15] op_sel_hi:[0,1]
	v_mov_b32_e32 v40, v39
	v_pk_mul_f32 v[6:7], v[6:7], v[40:41] op_sel_hi:[0,1]
	v_and_b32_sdwa v38, v15, v218 dst_sel:DWORD dst_unused:UNUSED_PAD src0_sel:WORD_1 src1_sel:DWORD
	v_and_b32_sdwa v39, v14, v218 dst_sel:DWORD dst_unused:UNUSED_PAD src0_sel:WORD_1 src1_sel:DWORD
	v_add3_u32 v14, v14, v39, s91
	v_add3_u32 v15, v15, v38, s91
	v_and_b32_sdwa v38, v7, v218 dst_sel:DWORD dst_unused:UNUSED_PAD src0_sel:WORD_1 src1_sel:DWORD
	v_and_b32_sdwa v39, v6, v218 dst_sel:DWORD dst_unused:UNUSED_PAD src0_sel:WORD_1 src1_sel:DWORD
	v_add3_u32 v7, v7, v38, s91
	v_add3_u32 v6, v6, v39, s91
	v_and_b32_e32 v7, 0xffff0000, v7
	v_and_b32_e32 v6, 0xffff0000, v6
	v_or_b32_sdwa v7, v7, v15 dst_sel:DWORD dst_unused:UNUSED_PAD src0_sel:DWORD src1_sel:WORD_1
	v_or_b32_sdwa v6, v6, v14 dst_sel:DWORD dst_unused:UNUSED_PAD src0_sel:DWORD src1_sel:WORD_1
	flat_store_dwordx2 v[2:3], v[6:7] offset:96
	v_lshlrev_b32_e32 v14, 16, v36
	v_and_b32_e32 v2, 0xffff0000, v36
	v_lshlrev_b32_e32 v15, 16, v37
	v_and_b32_e32 v3, 0xffff0000, v37
	ds_read2_b64 v[36:39], v79 offset1:1
	v_lshlrev_b32_e32 v45, 16, v31
	v_and_b32_e32 v43, 0xffff0000, v31
	v_lshlrev_b32_e32 v41, 16, v35
	v_and_b32_e32 v35, 0xffff0000, v35
	s_waitcnt lgkmcnt(0)
	v_readfirstlane_b32 s48, v36
	v_readfirstlane_b32 s49, v37
	s_add_u32 s48, s48, s0
	s_addc_u32 s49, s49, s1
	s_nop 1
	v_lshl_add_u64 v[154:155], s[48:49], 0, v[0:1]
	global_load_dwordx4 v[156:159], v[154:155], off offset:144
	s_nop 1
	v_lshl_add_u64 v[148:149], s[48:49], 0, v[0:1]
	global_load_dwordx4 v[150:153], v[148:149], off offset:16
	v_mov_b32_e32 v46, v43
	v_mov_b32_e32 v47, v45
	v_lshlrev_b32_e32 v44, 16, v30
	v_and_b32_e32 v42, 0xffff0000, v30
	v_lshlrev_b32_e32 v30, 16, v32
	v_and_b32_e32 v6, 0xffff0000, v32
	v_lshlrev_b32_e32 v31, 16, v33
	v_and_b32_e32 v7, 0xffff0000, v33
	v_lshl_add_u64 v[32:33], s[48:49], 0, v[0:1]
	v_mov_b32_e32 v36, v35
	v_mov_b32_e32 v37, v41
	v_pk_mul_f32 v[46:47], v[46:47], v[46:47]
	flat_load_dwordx4 v[50:53], v[32:33] offset:128
	v_pk_fma_f32 v[36:37], v[36:37], v[36:37], v[46:47]
	flat_load_dwordx4 v[46:49], v[32:33]
	v_mov_b32_e32 v74, v7
	v_mov_b32_e32 v75, v31
	v_pk_mul_f32 v[74:75], v[74:75], v[74:75]
	v_lshlrev_b32_e32 v40, 16, v34
	v_and_b32_e32 v34, 0xffff0000, v34
	v_readlane_b32 s13, v255, 11
	v_readlane_b32 s16, v255, 12
	v_readlane_b32 s17, v255, 13
	v_readlane_b32 s76, v255, 16
	v_readlane_b32 s77, v255, 17
	v_readlane_b32 s78, v255, 18
	v_readlane_b32 s79, v255, 19
	s_mov_b64 s[42:43], s[4:5]
	v_readlane_b32 s4, v255, 20
	v_readlane_b32 s5, v255, 21
	v_readlane_b32 s7, v254, 62
	s_waitcnt vmcnt(0) lgkmcnt(0)
	v_mov_b32_e32 v118, v50
	v_mov_b32_e32 v119, v52
	v_mov_b32_e32 v52, v51
	v_mov_b32_e32 v50, v6
	v_mov_b32_e32 v51, v30
	v_mov_b32_e32 v116, v46
	v_mov_b32_e32 v117, v48
	v_mov_b32_e32 v48, v47
	v_mov_b32_e32 v46, v2
	v_mov_b32_e32 v47, v14
	v_pk_mul_f32 v[50:51], v[50:51], v[50:51]
	s_nop 0
	v_pk_fma_f32 v[46:47], v[46:47], v[46:47], v[50:51]
	v_mov_b32_e32 v50, v3
	v_mov_b32_e32 v51, v15
	v_pk_fma_f32 v[50:51], v[50:51], v[50:51], v[74:75]
	s_waitcnt vmcnt(0)
	s_nop 0
	v_mov_b32_e32 v74, v150
	v_mov_b32_e32 v75, v151
	v_mov_b32_e32 v76, v152
	v_mov_b32_e32 v77, v153
	s_nop 1
	s_waitcnt vmcnt(0)
	s_nop 0
	v_mov_b32_e32 v112, v156
	v_mov_b32_e32 v113, v157
	v_mov_b32_e32 v114, v158
	v_mov_b32_e32 v115, v159
	s_nop 1
	v_mul_f32_e32 v32, v34, v34
	v_mul_f32_e32 v33, v40, v40
	v_fmac_f32_e32 v32, v42, v42
	v_fmac_f32_e32 v33, v44, v44
	v_add_f32_e32 v32, v33, v32
	v_add_f32_e32 v32, v37, v32
	v_add_f32_e32 v32, v36, v32
	v_add_f32_e32 v32, v47, v32
	v_add_f32_e32 v32, v46, v32
	v_add_f32_e32 v32, v51, v32
	v_add_f32_e32 v32, v50, v32
	ds_bpermute_b32 v33, v109, v32
	s_waitcnt lgkmcnt(0)
	v_add_f32_e32 v32, v32, v33
	ds_bpermute_b32 v33, v110, v32
	s_waitcnt lgkmcnt(0)
	v_add_f32_e32 v32, v32, v33
	v_fmamk_f32 v32, v32, 0x3c800000, v219
	v_cmp_gt_f32_e32 vcc, s6, v32
	v_mul_f32_e32 v33, 0x4f800000, v32
	s_nop 0
	v_cndmask_b32_e32 v32, v32, v33, vcc
	v_sqrt_f32_e32 v33, v32
	s_nop 0
	v_add_u32_e32 v36, -1, v33
	v_fma_f32 v37, -v36, v33, v32
	v_cmp_ge_f32_e64 s[88:89], 0, v37
	v_add_u32_e32 v37, 1, v33
	s_nop 0
	v_cndmask_b32_e64 v36, v33, v36, s[88:89]
	v_fma_f32 v33, -v37, v33, v32
	v_cmp_lt_f32_e64 s[88:89], 0, v33
	s_nop 1
	v_cndmask_b32_e64 v33, v36, v37, s[88:89]
	v_mul_f32_e32 v36, 0x37800000, v33
	v_cndmask_b32_e32 v33, v33, v36, vcc
	v_cmp_class_f32_e32 vcc, v32, v221
	s_nop 1
	v_cndmask_b32_e32 v32, v33, v32, vcc
	v_div_scale_f32 v33, s[48:49], v32, v32, 1.0
	v_rcp_f32_e32 v36, v33
	v_readfirstlane_b32 s48, v38
	v_readfirstlane_b32 s49, v39
	s_add_u32 s48, s48, s2
	v_fma_f32 v37, -v33, v36, 1.0
	v_fmac_f32_e32 v36, v37, v36
	v_div_scale_f32 v37, vcc, 1.0, v32, 1.0
	v_mul_f32_e32 v46, v37, v36
	v_fma_f32 v47, -v33, v46, v37
	v_fmac_f32_e32 v46, v47, v36
	v_fma_f32 v33, -v33, v46, v37
	v_div_fmas_f32 v33, v33, v36, v46
	v_div_fixup_f32 v32, v33, v32, 1.0
	v_pk_mul_f32 v[34:35], v[32:33], v[34:35] op_sel_hi:[0,1]
	v_pk_mul_f32 v[34:35], v[34:35], v[48:49]
	v_pk_mul_f32 v[14:15], v[32:33], v[14:15] op_sel_hi:[0,1]
	v_pk_mul_f32 v[30:31], v[32:33], v[30:31] op_sel_hi:[0,1]
	v_pk_mul_f32 v[36:37], v[32:33], v[40:41] op_sel_hi:[0,1]
	v_pk_mul_f32 v[40:41], v[32:33], v[44:45] op_sel_hi:[0,1]
	v_pk_mul_f32 v[42:43], v[32:33], v[42:43] op_sel_hi:[0,1]
	v_pk_mul_f32 v[2:3], v[32:33], v[2:3] op_sel_hi:[0,1]
	v_pk_mul_f32 v[6:7], v[32:33], v[6:7] op_sel_hi:[0,1]
	v_pk_mul_f32 v[40:41], v[118:119], v[40:41]
	v_pk_mul_f32 v[36:37], v[116:117], v[36:37]
	v_pk_mul_f32 v[42:43], v[42:43], v[52:53]
	v_pk_mul_f32 v[44:45], v[102:103], v[40:41]
	s_waitcnt vmcnt(0)
	v_mov_b32_e32 v48, v74
	v_mov_b32_e32 v49, v76
	v_pk_mul_f32 v[14:15], v[14:15], v[48:49]
	v_mov_b32_e32 v48, v112
	v_mov_b32_e32 v49, v114
	v_pk_mul_f32 v[30:31], v[30:31], v[48:49]
	v_mov_b32_e32 v114, v113
	v_pk_mul_f32 v[32:33], v[10:11], v[30:31]
	v_mov_b32_e32 v76, v75
	v_pk_mul_f32 v[6:7], v[6:7], v[114:115]
	v_pk_fma_f32 v[32:33], v[18:19], v[14:15], v[32:33]
	v_pk_mul_f32 v[2:3], v[2:3], v[76:77]
	v_pk_mul_f32 v[48:49], v[32:33], s[86:87] op_sel_hi:[1,0]
	v_pk_mul_f32 v[32:33], v[8:9], v[6:7]
	v_pk_fma_f32 v[44:45], v[104:105], v[36:37], v[44:45]
	v_pk_fma_f32 v[32:33], v[16:17], v[2:3], v[32:33]
	v_pk_mul_f32 v[46:47], v[12:13], v[42:43]
	v_pk_mul_f32 v[50:51], v[32:33], s[86:87] op_sel_hi:[1,0]
	v_pk_mul_f32 v[32:33], v[104:105], v[40:41]
	v_pk_fma_f32 v[46:47], v[20:21], v[34:35], v[46:47]
	v_pk_fma_f32 v[32:33], v[102:103], v[36:37], v[32:33] neg_lo:[0,0,1] neg_hi:[0,0,1]
	v_pk_mul_f32 v[36:37], v[20:21], v[42:43]
	v_pk_mul_f32 v[30:31], v[18:19], v[30:31]
	v_pk_fma_f32 v[34:35], v[12:13], v[34:35], v[36:37] neg_lo:[0,0,1] neg_hi:[0,0,1]
	v_pk_fma_f32 v[14:15], v[10:11], v[14:15], v[30:31] neg_lo:[0,0,1] neg_hi:[0,0,1]
	v_pk_mul_f32 v[34:35], v[34:35], s[86:87] op_sel_hi:[1,0]
	v_pk_mul_f32 v[6:7], v[16:17], v[6:7]
	v_pk_mul_f32 v[14:15], v[14:15], s[86:87] op_sel_hi:[1,0]
	v_pk_fma_f32 v[2:3], v[8:9], v[2:3], v[6:7] neg_lo:[0,0,1] neg_hi:[0,0,1]
	v_bfe_u32 v30, v35, 16, 1
	v_bfe_u32 v31, v34, 16, 1
	v_pk_mul_f32 v[2:3], v[2:3], s[86:87] op_sel_hi:[1,0]
	v_add3_u32 v34, v34, v31, s91
	v_add3_u32 v30, v35, v30, s91
	v_bfe_u32 v31, v14, 16, 1
	v_bfe_u32 v35, v15, 16, 1
	ds_read_b128 v[38:41], v100
	v_pk_mul_f32 v[32:33], v[32:33], s[86:87] op_sel_hi:[1,0]
	v_bfe_u32 v6, v3, 16, 1
	v_bfe_u32 v7, v2, 16, 1
	v_add3_u32 v15, v15, v35, s91
	v_add3_u32 v14, v14, v31, s91
	v_pk_mul_f32 v[44:45], v[44:45], s[86:87] op_sel_hi:[1,0]
	v_add3_u32 v2, v2, v7, s91
	v_add3_u32 v3, v3, v6, s91
	v_bfe_u32 v6, v32, 16, 1
	v_bfe_u32 v7, v33, 16, 1
	v_lshrrev_b32_e32 v14, 16, v14
	v_lshrrev_b32_e32 v15, 16, v15
	v_add3_u32 v7, v33, v7, s91
	v_add3_u32 v6, v32, v6, s91
	v_and_or_b32 v33, v3, s33, v15
	v_and_or_b32 v32, v2, s33, v14
	v_bfe_u32 v14, v44, 16, 1
	v_bfe_u32 v15, v45, 16, 1
	v_add3_u32 v15, v45, v15, s91
	v_add3_u32 v14, v44, v14, s91
	ds_read_b128 v[42:45], v100 offset:64
	v_lshrrev_b32_e32 v6, 16, v6
	v_lshrrev_b32_e32 v7, 16, v7
	v_and_or_b32 v31, v30, s33, v7
	v_and_or_b32 v30, v34, s33, v6
	v_pk_mul_f32 v[46:47], v[46:47], s[86:87] op_sel_hi:[1,0]
	v_bfe_u32 v34, v48, 16, 1
	v_bfe_u32 v35, v49, 16, 1
	s_waitcnt lgkmcnt(1)
	v_mfma_f32_16x16x32_bf16 v[38:41], v[38:41], v[30:33], 0
	v_bfe_u32 v2, v51, 16, 1
	v_bfe_u32 v3, v50, 16, 1
	v_bfe_u32 v6, v47, 16, 1
	v_bfe_u32 v7, v46, 16, 1
	v_add3_u32 v35, v49, v35, s91
	v_add3_u32 v34, v48, v34, s91
	v_add3_u32 v7, v46, v7, s91
	v_add3_u32 v6, v47, v6, s91
	v_add3_u32 v3, v50, v3, s91
	v_add3_u32 v2, v51, v2, s91
	v_lshrrev_b32_e32 v14, 16, v14
	v_lshrrev_b32_e32 v15, 16, v15
	v_lshrrev_b32_e32 v34, 16, v34
	v_lshrrev_b32_e32 v35, 16, v35
	v_and_or_b32 v37, v2, s33, v35
	v_and_or_b32 v36, v3, s33, v34
	v_and_or_b32 v35, v6, s33, v15
	v_and_or_b32 v34, v7, s33, v14
	ds_read_b128 v[46:49], v98 offset:64
	s_addc_u32 s49, s49, s3
	s_nop 1
	v_mov_b64_e32 v[160:161], s[48:49]
	global_load_dword v162, v[160:161], off offset:4
	s_waitcnt lgkmcnt(1)
	v_mfma_f32_16x16x32_bf16 v[38:41], v[42:45], v[34:37], v[38:41]
	ds_read_b128 v[42:45], v98
	v_mov_b64_e32 v[2:3], s[48:49]
	s_waitcnt vmcnt(0)
	s_nop 0
	v_mov_b32_e32 v2, v162
	s_nop 1
	s_waitcnt lgkmcnt(0)
	v_mfma_f32_16x16x32_bf16 v[42:45], v[42:45], v[30:33], 0
	ds_read_b128 v[50:53], v96 offset:64
	ds_read_b128 v[74:77], v94 offset:64
	v_mfma_f32_16x16x32_bf16 v[42:45], v[46:49], v[34:37], v[42:45]
	ds_read_b128 v[46:49], v96
	v_mov_b32_e32 v6, s94
	v_cndmask_b32_e64 v3, v38, v6, s[8:9]
	s_waitcnt lgkmcnt(0)
	v_mfma_f32_16x16x32_bf16 v[46:49], v[46:49], v[30:33], 0
	v_cndmask_b32_e64 v7, v39, v227, s[40:41]
	s_mov_b64 s[40:41], s[80:81]
	v_max3_f32 v6, v3, s94, v7
	v_mfma_f32_16x16x32_bf16 v[46:49], v[50:53], v[34:37], v[46:49]
	ds_read_b128 v[50:53], v94
	ds_read_b128 v[112:115], v92 offset:64
	s_waitcnt lgkmcnt(0)
	v_mfma_f32_16x16x32_bf16 v[50:53], v[50:53], v[30:33], 0
	ds_read_b128 v[116:119], v90 offset:64
	v_cndmask_b32_e64 v14, v40, v227, s[40:41]
	v_cndmask_b32_e64 v15, v41, v227, s[92:93]
	v_mfma_f32_16x16x32_bf16 v[50:53], v[74:77], v[34:37], v[50:53]
	ds_read_b128 v[74:77], v92
	v_readlane_b32 s80, v255, 14
	v_readlane_b32 s81, v255, 15
	s_waitcnt lgkmcnt(0)
	v_mfma_f32_16x16x32_bf16 v[74:77], v[74:77], v[30:33], 0
	v_cndmask_b32_e64 v40, v47, v227, s[80:81]
	v_cndmask_b32_e64 v41, v49, v227, s[84:85]
	v_mfma_f32_16x16x32_bf16 v[74:77], v[112:115], v[34:37], v[74:77]
	ds_read_b128 v[112:115], v90
	ds_read_b128 v[120:123], v88 offset:64
	s_waitcnt lgkmcnt(0)
	v_mfma_f32_16x16x32_bf16 v[112:115], v[112:115], v[30:33], 0
	ds_read_b128 v[124:127], v86 offset:64
	s_nop 2
	v_cndmask_b32_e64 v49, v77, v227, s[26:27]
	v_mfma_f32_16x16x32_bf16 v[112:115], v[116:119], v[34:37], v[112:115]
	ds_read_b128 v[116:119], v88
	s_waitcnt lgkmcnt(0)
	v_mfma_f32_16x16x32_bf16 v[116:119], v[116:119], v[30:33], 0
	v_mfma_f32_16x16x32_bf16 v[116:119], v[120:123], v[34:37], v[116:119]
	ds_read_b128 v[120:123], v86
	ds_read_b128 v[128:131], v84 offset:64
	s_waitcnt lgkmcnt(0)
	v_mfma_f32_16x16x32_bf16 v[120:123], v[120:123], v[30:33], 0
	s_nop 3
	v_cndmask_b32_e64 v77, v119, v227, s[52:53]
	v_mfma_f32_16x16x32_bf16 v[120:123], v[124:127], v[34:37], v[120:123]
	ds_read_b128 v[124:127], v84
	s_waitcnt lgkmcnt(0)
	v_mfma_f32_16x16x32_bf16 v[124:127], v[124:127], v[30:33], 0
	s_nop 4
	v_cndmask_b32_e64 v87, v121, v227, s[56:57]
	v_cndmask_b32_e64 v89, v123, v227, s[60:61]
	v_mfma_f32_16x16x32_bf16 v[124:127], v[128:131], v[34:37], v[124:127]
	ds_read_b128 v[128:131], v82
	s_waitcnt lgkmcnt(0)
	v_mfma_f32_16x16x32_bf16 v[30:33], v[128:131], v[30:33], 0
	ds_read_b128 v[128:131], v82 offset:64
	s_nop 3
	v_cndmask_b32_e64 v95, v125, v227, s[64:65]
	v_cndmask_b32_e64 v97, v127, v227, s[68:69]
	s_waitcnt lgkmcnt(0)
	v_mfma_f32_16x16x32_bf16 v[30:33], v[128:131], v[34:37], v[30:33]
	v_max3_f32 v34, v6, v14, v15
	v_mov_b32_e32 v6, s94
	v_cndmask_b32_e64 v35, v42, v6, s[18:19]
	v_cndmask_b32_e64 v36, v43, v227, s[10:11]
	v_max3_f32 v6, v34, v35, v36
	v_cndmask_b32_e64 v34, v44, v227, s[12:13]
	v_cndmask_b32_e64 v37, v45, v227, s[44:45]
	v_max3_f32 v38, v6, v34, v37
	v_mov_b32_e32 v6, s94
	v_cndmask_b32_e64 v39, v46, v6, s[16:17]
	v_max3_f32 v6, v38, v39, v40
	v_cndmask_b32_e64 v38, v48, v227, s[82:83]
	v_max3_f32 v42, v6, v38, v41
	v_mov_b32_e32 v6, s94
	v_cndmask_b32_e64 v43, v50, v6, s[20:21]
	v_cndmask_b32_e64 v44, v51, v227, s[76:77]
	v_max3_f32 v6, v42, v43, v44
	v_cndmask_b32_e64 v42, v52, v227, s[78:79]
	v_cndmask_b32_e64 v45, v53, v227, s[14:15]
	v_max3_f32 v46, v6, v42, v45
	v_mov_b32_e32 v6, s94
	v_cndmask_b32_e64 v47, v74, v6, s[28:29]
	v_cndmask_b32_e64 v48, v75, v227, s[42:43]
	v_max3_f32 v6, v46, v47, v48
	v_cndmask_b32_e64 v46, v76, v227, s[22:23]
	v_max3_f32 v50, v6, v46, v49
	v_mov_b32_e32 v6, s94
	v_cndmask_b32_e64 v51, v112, v6, s[38:39]
	v_cndmask_b32_e64 v52, v113, v227, s[30:31]
	v_max3_f32 v6, v50, v51, v52
	v_cndmask_b32_e64 v50, v114, v227, s[34:35]
	v_cndmask_b32_e64 v53, v115, v227, s[36:37]
	v_max3_f32 v74, v6, v50, v53
	v_mov_b32_e32 v6, s94
	v_cndmask_b32_e64 v75, v116, v6, s[54:55]
	v_cndmask_b32_e64 v76, v117, v227, s[46:47]
	v_max3_f32 v6, v74, v75, v76
	v_cndmask_b32_e64 v74, v118, v227, s[50:51]
	v_max3_f32 v83, v6, v74, v77
	v_mov_b32_e32 v6, s94
	v_cndmask_b32_e64 v85, v120, v6, s[62:63]
	v_max3_f32 v6, v83, v85, v87
	v_cndmask_b32_e64 v83, v122, v227, s[58:59]
	v_max3_f32 v91, v6, v83, v89
	v_mov_b32_e32 v6, s94
	v_cndmask_b32_e64 v93, v124, v6, s[4:5]
	v_max3_f32 v6, v91, v93, v95
	v_cndmask_b32_e64 v91, v126, v227, s[66:67]
	v_max3_f32 v99, v6, v91, v97
	v_mov_b32_e32 v6, s94
	v_cndmask_b32_e64 v6, v30, v6, s[24:25]
	v_cndmask_b32_e64 v30, v31, v227, s[70:71]
	v_max3_f32 v31, v99, v6, v30
	v_cndmask_b32_e64 v32, v32, v227, s[72:73]
	v_cndmask_b32_e64 v33, v33, v227, s[74:75]
	v_max3_f32 v31, v31, v32, v33
	ds_bpermute_b32 v99, v109, v31
	s_lshl_b32 s94, s7, 1
	s_waitcnt lgkmcnt(0)
	v_max_f32_e32 v99, v99, v99
	v_max_f32_e32 v31, v31, v99
	ds_bpermute_b32 v99, v110, v31
	s_waitcnt vmcnt(0) lgkmcnt(0)
	v_max3_f32 v31, v31, v99, v2
	v_sub_f32_e32 v3, v3, v31
	v_mul_f32_e32 v3, 0x3fb8aa3b, v3
	v_sub_f32_e32 v7, v7, v31
	v_exp_f32_e32 v3, v3
	v_mul_f32_e32 v7, 0x3fb8aa3b, v7
	v_sub_f32_e32 v14, v14, v31
	v_exp_f32_e32 v7, v7
	v_mul_f32_e32 v14, 0x3fb8aa3b, v14
	v_sub_f32_e32 v15, v15, v31
	v_exp_f32_e32 v14, v14
	v_mul_f32_e32 v15, 0x3fb8aa3b, v15
	v_sub_f32_e32 v35, v35, v31
	v_exp_f32_e32 v15, v15
	v_mul_f32_e32 v35, 0x3fb8aa3b, v35
	v_sub_f32_e32 v36, v36, v31
	v_add_f32_e32 v99, 0, v3
	v_exp_f32_e32 v35, v35
	v_mul_f32_e32 v36, 0x3fb8aa3b, v36
	v_sub_f32_e32 v34, v34, v31
	v_add_f32_e32 v99, v7, v99
	v_exp_f32_e32 v36, v36
	v_mul_f32_e32 v34, 0x3fb8aa3b, v34
	v_sub_f32_e32 v37, v37, v31
	v_add_f32_e32 v99, v14, v99
	v_exp_f32_e32 v34, v34
	v_mul_f32_e32 v37, 0x3fb8aa3b, v37
	v_sub_f32_e32 v39, v39, v31
	v_add_f32_e32 v99, v15, v99
	v_exp_f32_e32 v37, v37
	v_mul_f32_e32 v39, 0x3fb8aa3b, v39
	v_add_f32_e32 v99, v35, v99
	v_exp_f32_e32 v101, v39
	v_add_f32_e32 v99, v36, v99
	v_add_f32_e32 v99, v34, v99
	v_sub_f32_e32 v40, v40, v31
	v_add_f32_e32 v99, v37, v99
	v_mul_f32_e32 v40, 0x3fb8aa3b, v40
	v_sub_f32_e32 v38, v38, v31
	v_add_f32_e32 v39, v101, v99
	v_exp_f32_e32 v99, v40
	v_mul_f32_e32 v38, 0x3fb8aa3b, v38
	v_exp_f32_e32 v111, v38
	v_sub_f32_e32 v6, v6, v31
	v_add_f32_e32 v39, v99, v39
	v_mul_f32_e32 v6, 0x3fb8aa3b, v6
	v_add_f32_e32 v38, v111, v39
	v_sub_f32_e32 v39, v41, v31
	v_mul_f32_e32 v39, 0x3fb8aa3b, v39
	v_exp_f32_e32 v112, v39
	v_sub_f32_e32 v39, v43, v31
	v_mul_f32_e32 v39, 0x3fb8aa3b, v39
	v_exp_f32_e32 v113, v39
	v_sub_f32_e32 v39, v44, v31
	v_mul_f32_e32 v39, 0x3fb8aa3b, v39
	v_exp_f32_e32 v114, v39
	v_sub_f32_e32 v39, v42, v31
	v_mul_f32_e32 v39, 0x3fb8aa3b, v39
	v_exp_f32_e32 v115, v39
	v_sub_f32_e32 v39, v45, v31
	v_mul_f32_e32 v39, 0x3fb8aa3b, v39
	v_exp_f32_e32 v116, v39
	v_sub_f32_e32 v39, v47, v31
	v_mul_f32_e32 v39, 0x3fb8aa3b, v39
	v_exp_f32_e32 v117, v39
	v_sub_f32_e32 v39, v48, v31
	v_mul_f32_e32 v39, 0x3fb8aa3b, v39
	v_exp_f32_e32 v118, v39
	v_sub_f32_e32 v39, v46, v31
	v_mul_f32_e32 v39, 0x3fb8aa3b, v39
	v_exp_f32_e32 v119, v39
	v_sub_f32_e32 v39, v49, v31
	v_mul_f32_e32 v39, 0x3fb8aa3b, v39
	v_exp_f32_e32 v120, v39
	v_sub_f32_e32 v39, v51, v31
	v_mul_f32_e32 v39, 0x3fb8aa3b, v39
	v_exp_f32_e32 v121, v39
	v_sub_f32_e32 v39, v52, v31
	v_mul_f32_e32 v39, 0x3fb8aa3b, v39
	v_exp_f32_e32 v122, v39
	v_sub_f32_e32 v39, v50, v31
	v_mul_f32_e32 v39, 0x3fb8aa3b, v39
	v_exp_f32_e32 v123, v39
	v_sub_f32_e32 v39, v53, v31
	v_mul_f32_e32 v39, 0x3fb8aa3b, v39
	v_exp_f32_e32 v124, v39
	v_sub_f32_e32 v39, v75, v31
	v_mul_f32_e32 v39, 0x3fb8aa3b, v39
	v_exp_f32_e32 v75, v39
	v_sub_f32_e32 v39, v76, v31
	v_mul_f32_e32 v39, 0x3fb8aa3b, v39
	v_add_f32_e32 v38, v112, v38
	v_exp_f32_e32 v76, v39
	v_sub_f32_e32 v39, v74, v31
	v_add_f32_e32 v38, v113, v38
	v_mul_f32_e32 v39, 0x3fb8aa3b, v39
	v_add_f32_e32 v38, v114, v38
	v_exp_f32_e32 v74, v39
	v_sub_f32_e32 v39, v77, v31
	v_add_f32_e32 v38, v115, v38
	v_mul_f32_e32 v39, 0x3fb8aa3b, v39
	v_add_f32_e32 v38, v116, v38
	v_exp_f32_e32 v77, v39
	v_sub_f32_e32 v39, v85, v31
	v_add_f32_e32 v38, v117, v38
	v_mul_f32_e32 v39, 0x3fb8aa3b, v39
	v_add_f32_e32 v38, v118, v38
	v_exp_f32_e32 v85, v39
	v_sub_f32_e32 v39, v87, v31
	v_add_f32_e32 v38, v119, v38
	v_mul_f32_e32 v39, 0x3fb8aa3b, v39
	v_add_f32_e32 v38, v120, v38
	v_exp_f32_e32 v87, v39
	v_sub_f32_e32 v39, v83, v31
	v_add_f32_e32 v38, v121, v38
	v_mul_f32_e32 v39, 0x3fb8aa3b, v39
	v_add_f32_e32 v38, v122, v38
	v_exp_f32_e32 v83, v39
	v_sub_f32_e32 v39, v89, v31
	v_add_f32_e32 v38, v123, v38
	v_mul_f32_e32 v39, 0x3fb8aa3b, v39
	v_add_f32_e32 v38, v124, v38
	v_exp_f32_e32 v89, v39
	v_sub_f32_e32 v39, v93, v31
	v_add_f32_e32 v38, v75, v38
	v_mul_f32_e32 v39, 0x3fb8aa3b, v39
	v_add_f32_e32 v38, v76, v38
	v_exp_f32_e32 v93, v39
	v_sub_f32_e32 v39, v95, v31
	v_add_f32_e32 v38, v74, v38
	v_mul_f32_e32 v39, 0x3fb8aa3b, v39
	v_add_f32_e32 v38, v77, v38
	v_exp_f32_e32 v95, v39
	v_sub_f32_e32 v39, v91, v31
	v_add_f32_e32 v38, v85, v38
	v_mul_f32_e32 v39, 0x3fb8aa3b, v39
	v_add_f32_e32 v38, v87, v38
	v_exp_f32_e32 v91, v39
	v_sub_f32_e32 v39, v97, v31
	v_add_f32_e32 v38, v83, v38
	v_mul_f32_e32 v39, 0x3fb8aa3b, v39
	v_add_f32_e32 v38, v89, v38
	v_exp_f32_e32 v97, v39
	v_sub_f32_e32 v30, v30, v31
	v_sub_f32_e32 v32, v32, v31
	v_add_f32_e32 v38, v93, v38
	v_exp_f32_e32 v6, v6
	v_mul_f32_e32 v30, 0x3fb8aa3b, v30
	v_mul_f32_e32 v32, 0x3fb8aa3b, v32
	v_add_f32_e32 v38, v95, v38
	v_exp_f32_e32 v125, v30
	v_exp_f32_e32 v126, v32
	v_sub_f32_e32 v32, v33, v31
	v_add_f32_e32 v38, v91, v38
	v_mul_f32_e32 v32, 0x3fb8aa3b, v32
	v_add_f32_e32 v38, v97, v38
	v_exp_f32_e32 v127, v32
	v_add_f32_e32 v38, v6, v38
	v_add_f32_e32 v30, v125, v38
	v_add_f32_e32 v30, v126, v30
	v_add_f32_e32 v30, v127, v30
	ds_bpermute_b32 v32, v109, v30
	v_sub_f32_e32 v2, v2, v31
	v_mul_f32_e32 v2, 0x3fb8aa3b, v2
	v_exp_f32_e32 v2, v2
	v_bfe_u32 v31, v36, 16, 1
	s_waitcnt lgkmcnt(0)
	v_add_f32_e32 v30, v30, v32
	ds_bpermute_b32 v32, v110, v30
	v_bfe_u32 v33, v7, 16, 1
	v_add3_u32 v31, v36, v31, s91
	v_bfe_u32 v36, v35, 16, 1
	v_add3_u32 v7, v7, v33, s91
	s_waitcnt lgkmcnt(0)
	v_add_f32_e32 v30, v30, v32
	v_add_f32_e32 v2, v2, v30
	v_bfe_u32 v30, v37, 16, 1
	v_bfe_u32 v32, v15, 16, 1
	v_add3_u32 v30, v37, v30, s91
	v_bfe_u32 v37, v34, 16, 1
	v_add3_u32 v15, v15, v32, s91
	v_bfe_u32 v32, v3, 16, 1
	v_bfe_u32 v33, v14, 16, 1
	v_add3_u32 v34, v34, v37, s91
	v_add3_u32 v35, v35, v36, s91
	v_add3_u32 v14, v14, v33, s91
	v_add3_u32 v3, v3, v32, s91
	v_lshrrev_b32_e32 v32, 16, v35
	v_lshrrev_b32_e32 v33, 16, v34
	ds_read2_b64 v[34:37], v73 offset1:4
	ds_read2_b64 v[38:41], v72 offset0:32 offset1:36
	ds_read2_b64 v[42:45], v71 offset0:64 offset1:68
	ds_read2_b64 v[46:49], v70 offset0:96 offset1:100
	ds_read2_b64 v[50:53], v69 offset1:4
	v_lshrrev_b32_e32 v3, 16, v3
	v_lshrrev_b32_e32 v14, 16, v14
	v_and_or_b32 v33, v30, s33, v33
	v_and_or_b32 v32, v31, s33, v32
	v_and_or_b32 v31, v15, s33, v14
	v_and_or_b32 v30, v7, s33, v3
	v_bfe_u32 v3, v116, 16, 1
	v_bfe_u32 v7, v114, 16, 1
	s_waitcnt lgkmcnt(4)
	v_mfma_f32_16x16x32_bf16 v[34:37], v[34:37], v[30:33], 0
	v_bfe_u32 v14, v112, 16, 1
	v_bfe_u32 v15, v99, 16, 1
	v_add3_u32 v15, v99, v15, s91
	s_waitcnt lgkmcnt(3)
	v_mfma_f32_16x16x32_bf16 v[38:41], v[38:41], v[30:33], 0
	v_add3_u32 v14, v112, v14, s91
	v_add3_u32 v7, v114, v7, s91
	v_add3_u32 v3, v116, v3, s91
	s_waitcnt lgkmcnt(2)
	v_mfma_f32_16x16x32_bf16 v[42:45], v[42:45], v[30:33], 0
	s_waitcnt lgkmcnt(1)
	v_mfma_f32_16x16x32_bf16 v[30:33], v[46:49], v[30:33], 0
	v_bfe_u32 v46, v101, 16, 1
	v_bfe_u32 v47, v111, 16, 1
	v_bfe_u32 v48, v113, 16, 1
	v_bfe_u32 v49, v115, 16, 1
	v_add3_u32 v49, v115, v49, s91
	v_add3_u32 v48, v113, v48, s91
	v_add3_u32 v47, v111, v47, s91
	v_add3_u32 v46, v101, v46, s91
	v_lshrrev_b32_e32 v46, 16, v46
	v_lshrrev_b32_e32 v47, 16, v47
	v_lshrrev_b32_e32 v48, 16, v48
	v_lshrrev_b32_e32 v49, 16, v49
	v_and_or_b32 v49, v3, s33, v49
	v_and_or_b32 v48, v7, s33, v48
	v_and_or_b32 v47, v14, s33, v47
	v_and_or_b32 v46, v15, s33, v46
	v_bfe_u32 v3, v124, 16, 1
	v_bfe_u32 v7, v122, 16, 1
	s_waitcnt lgkmcnt(0)
	v_mfma_f32_16x16x32_bf16 v[34:37], v[50:53], v[46:49], v[34:37]
	ds_read2_b64 v[50:53], v68 offset0:32 offset1:36
	v_bfe_u32 v14, v120, 16, 1
	v_bfe_u32 v15, v118, 16, 1
	s_waitcnt lgkmcnt(0)
	v_mfma_f32_16x16x32_bf16 v[38:41], v[50:53], v[46:49], v[38:41]
	ds_read2_b64 v[50:53], v67 offset0:64 offset1:68
	v_add3_u32 v15, v118, v15, s91
	v_add3_u32 v14, v120, v14, s91
	s_waitcnt lgkmcnt(0)
	v_mfma_f32_16x16x32_bf16 v[42:45], v[50:53], v[46:49], v[42:45]
	ds_read2_b64 v[50:53], v66 offset0:96 offset1:100
	v_add3_u32 v7, v122, v7, s91
	s_waitcnt lgkmcnt(0)
	v_mfma_f32_16x16x32_bf16 v[30:33], v[50:53], v[46:49], v[30:33]
	ds_read2_b64 v[50:53], v65 offset1:4
	v_bfe_u32 v46, v117, 16, 1
	v_bfe_u32 v47, v119, 16, 1
	v_bfe_u32 v48, v121, 16, 1
	v_bfe_u32 v49, v123, 16, 1
	v_add3_u32 v49, v123, v49, s91
	v_add3_u32 v48, v121, v48, s91
	v_add3_u32 v47, v119, v47, s91
	v_add3_u32 v46, v117, v46, s91
	v_add3_u32 v3, v124, v3, s91
	v_lshrrev_b32_e32 v46, 16, v46
	v_lshrrev_b32_e32 v47, 16, v47
	v_lshrrev_b32_e32 v48, 16, v48
	v_lshrrev_b32_e32 v49, 16, v49
	v_and_or_b32 v49, v3, s33, v49
	v_and_or_b32 v48, v7, s33, v48
	v_and_or_b32 v47, v14, s33, v47
	v_and_or_b32 v46, v15, s33, v46
	v_bfe_u32 v3, v89, 16, 1
	v_bfe_u32 v7, v87, 16, 1
	s_waitcnt lgkmcnt(0)
	v_mfma_f32_16x16x32_bf16 v[34:37], v[50:53], v[46:49], v[34:37]
	ds_read2_b64 v[50:53], v64 offset0:32 offset1:36
	v_bfe_u32 v14, v77, 16, 1
	v_bfe_u32 v15, v76, 16, 1
	s_waitcnt lgkmcnt(0)
	v_mfma_f32_16x16x32_bf16 v[38:41], v[50:53], v[46:49], v[38:41]
	ds_read2_b64 v[50:53], v63 offset0:64 offset1:68
	v_add3_u32 v15, v76, v15, s91
	v_add3_u32 v14, v77, v14, s91
	s_waitcnt lgkmcnt(0)
	v_mfma_f32_16x16x32_bf16 v[42:45], v[50:53], v[46:49], v[42:45]
	ds_read2_b64 v[50:53], v62 offset0:96 offset1:100
	v_add3_u32 v7, v87, v7, s91
	s_waitcnt lgkmcnt(0)
	v_mfma_f32_16x16x32_bf16 v[30:33], v[50:53], v[46:49], v[30:33]
	ds_read2_b64 v[50:53], v61 offset1:4
	v_bfe_u32 v46, v75, 16, 1
	v_bfe_u32 v47, v74, 16, 1
	v_bfe_u32 v48, v85, 16, 1
	v_bfe_u32 v49, v83, 16, 1
	v_add3_u32 v49, v83, v49, s91
	v_add3_u32 v48, v85, v48, s91
	v_add3_u32 v47, v74, v47, s91
	v_add3_u32 v46, v75, v46, s91
	v_add3_u32 v3, v89, v3, s91
	v_lshrrev_b32_e32 v46, 16, v46
	v_lshrrev_b32_e32 v47, 16, v47
	v_lshrrev_b32_e32 v48, 16, v48
	v_lshrrev_b32_e32 v49, 16, v49
	v_and_or_b32 v49, v3, s33, v49
	v_and_or_b32 v48, v7, s33, v48
	v_and_or_b32 v47, v14, s33, v47
	v_and_or_b32 v46, v15, s33, v46
	v_bfe_u32 v3, v127, 16, 1
	v_bfe_u32 v14, v97, 16, 1
	s_waitcnt lgkmcnt(0)
	v_mfma_f32_16x16x32_bf16 v[34:37], v[50:53], v[46:49], v[34:37]
	ds_read2_b64 v[50:53], v60 offset0:32 offset1:36
	v_bfe_u32 v15, v95, 16, 1
	v_add3_u32 v15, v95, v15, s91
	s_waitcnt lgkmcnt(0)
	v_mfma_f32_16x16x32_bf16 v[38:41], v[50:53], v[46:49], v[38:41]
	ds_read2_b64 v[50:53], v59 offset0:64 offset1:68
	v_add3_u32 v14, v97, v14, s91
	v_add3_u32 v3, v127, v3, s91
	s_waitcnt lgkmcnt(0)
	v_mfma_f32_16x16x32_bf16 v[50:53], v[50:53], v[46:49], v[42:45]
	s_nop 2
	ds_read2_b64 v[42:45], v58 offset0:96 offset1:100
	v_bfe_u32 v7, v125, 16, 1
	s_waitcnt lgkmcnt(0)
	v_mfma_f32_16x16x32_bf16 v[30:33], v[42:45], v[46:49], v[30:33]
	v_bfe_u32 v42, v93, 16, 1
	v_bfe_u32 v43, v91, 16, 1
	v_bfe_u32 v45, v126, 16, 1
	v_bfe_u32 v44, v6, 16, 1
	v_add3_u32 v45, v126, v45, s91
	v_add3_u32 v43, v91, v43, s91
	v_add3_u32 v42, v93, v42, s91
	v_add3_u32 v6, v6, v44, s91
	v_lshrrev_b32_e32 v42, 16, v42
	v_lshrrev_b32_e32 v43, 16, v43
	v_lshrrev_b32_e32 v44, 16, v45
	v_and_or_b32 v49, v3, s33, v44
	v_and_or_b32 v47, v14, s33, v43
	v_and_or_b32 v46, v15, s33, v42
	ds_read2_b64 v[42:45], v57 offset1:4
	v_add3_u32 v7, v125, v7, s91
	v_lshrrev_b32_e32 v6, 16, v6
	v_and_or_b32 v48, v7, s33, v6
	v_div_scale_f32 v3, s[48:49], v2, v2, 1.0
	s_waitcnt lgkmcnt(0)
	v_mfma_f32_16x16x32_bf16 v[42:45], v[42:45], v[46:49], v[34:37]
	s_nop 2
	ds_read2_b64 v[34:37], v56 offset0:32 offset1:36
	v_rcp_f32_e32 v6, v3
	s_waitcnt lgkmcnt(0)
	v_mfma_f32_16x16x32_bf16 v[38:41], v[34:37], v[46:49], v[38:41]
	v_fma_f32 v7, -v3, v6, 1.0
	v_fmac_f32_e32 v6, v7, v6
	v_div_scale_f32 v7, vcc, 1.0, v2, 1.0
	v_mul_f32_e32 v14, v7, v6
	v_fma_f32 v15, -v3, v14, v7
	v_fmac_f32_e32 v14, v15, v6
	ds_read2_b64 v[34:37], v55 offset0:64 offset1:68
	v_fma_f32 v3, -v3, v14, v7
	v_div_fmas_f32 v3, v3, v6, v14
	v_div_fixup_f32 v2, v3, v2, 1.0
	v_mov_b32_e32 v14, v42
	v_mov_b32_e32 v15, v44
	v_pk_mul_f32 v[14:15], v[2:3], v[14:15] op_sel_hi:[0,1]
	v_mov_b32_e32 v44, v43
	v_pk_mul_f32 v[42:43], v[2:3], v[44:45] op_sel_hi:[0,1]
	v_and_b32_sdwa v3, v15, v218 dst_sel:DWORD dst_unused:UNUSED_PAD src0_sel:WORD_1 src1_sel:DWORD
	v_and_b32_sdwa v44, v14, v218 dst_sel:DWORD dst_unused:UNUSED_PAD src0_sel:WORD_1 src1_sel:DWORD
	v_add3_u32 v14, v14, v44, s91
	v_add3_u32 v3, v15, v3, s91
	v_and_b32_sdwa v15, v43, v218 dst_sel:DWORD dst_unused:UNUSED_PAD src0_sel:WORD_1 src1_sel:DWORD
	v_and_b32_sdwa v44, v42, v218 dst_sel:DWORD dst_unused:UNUSED_PAD src0_sel:WORD_1 src1_sel:DWORD
	v_add3_u32 v15, v43, v15, s91
	v_add3_u32 v42, v42, v44, s91
	v_and_b32_e32 v15, 0xffff0000, v15
	v_and_b32_e32 v42, 0xffff0000, v42
	v_lshl_add_u64 v[6:7], v[80:81], 0, s[94:95]
	v_or_b32_sdwa v15, v15, v3 dst_sel:DWORD dst_unused:UNUSED_PAD src0_sel:DWORD src1_sel:WORD_1
	v_or_b32_sdwa v14, v42, v14 dst_sel:DWORD dst_unused:UNUSED_PAD src0_sel:DWORD src1_sel:WORD_1
	s_waitcnt lgkmcnt(0)
	v_mfma_f32_16x16x32_bf16 v[34:37], v[34:37], v[46:49], v[50:53]
	v_lshlrev_b32_e32 v44, 16, v22
	v_lshlrev_b32_e32 v45, 16, v23
	v_and_b32_e32 v42, 0xffff0000, v28
	ds_read2_b64 v[50:53], v54 offset0:96 offset1:100
	flat_store_dwordx2 v[6:7], v[14:15]
	v_mov_b32_e32 v14, v38
	v_mov_b32_e32 v15, v40
	v_pk_mul_f32 v[14:15], v[2:3], v[14:15] op_sel_hi:[0,1]
	v_mov_b32_e32 v40, v39
	v_pk_mul_f32 v[38:39], v[2:3], v[40:41] op_sel_hi:[0,1]
	v_and_b32_sdwa v3, v15, v218 dst_sel:DWORD dst_unused:UNUSED_PAD src0_sel:WORD_1 src1_sel:DWORD
	v_and_b32_sdwa v40, v14, v218 dst_sel:DWORD dst_unused:UNUSED_PAD src0_sel:WORD_1 src1_sel:DWORD
	v_add3_u32 v14, v14, v40, s91
	v_add3_u32 v3, v15, v3, s91
	v_and_b32_sdwa v15, v39, v218 dst_sel:DWORD dst_unused:UNUSED_PAD src0_sel:WORD_1 src1_sel:DWORD
	v_and_b32_sdwa v40, v38, v218 dst_sel:DWORD dst_unused:UNUSED_PAD src0_sel:WORD_1 src1_sel:DWORD
	v_add3_u32 v15, v39, v15, s91
	v_add3_u32 v38, v38, v40, s91
	v_and_b32_e32 v15, 0xffff0000, v15
	v_and_b32_e32 v38, 0xffff0000, v38
	v_or_b32_sdwa v15, v15, v3 dst_sel:DWORD dst_unused:UNUSED_PAD src0_sel:DWORD src1_sel:WORD_1
	v_or_b32_sdwa v14, v38, v14 dst_sel:DWORD dst_unused:UNUSED_PAD src0_sel:DWORD src1_sel:WORD_1
	flat_store_dwordx2 v[6:7], v[14:15] offset:32
	v_mov_b32_e32 v14, v34
	v_mov_b32_e32 v15, v36
	v_pk_mul_f32 v[14:15], v[2:3], v[14:15] op_sel_hi:[0,1]
	v_mov_b32_e32 v36, v35
	v_pk_mul_f32 v[34:35], v[2:3], v[36:37] op_sel_hi:[0,1]
	v_and_b32_sdwa v3, v15, v218 dst_sel:DWORD dst_unused:UNUSED_PAD src0_sel:WORD_1 src1_sel:DWORD
	v_and_b32_sdwa v36, v14, v218 dst_sel:DWORD dst_unused:UNUSED_PAD src0_sel:WORD_1 src1_sel:DWORD
	s_waitcnt lgkmcnt(0)
	v_mfma_f32_16x16x32_bf16 v[30:33], v[50:53], v[46:49], v[30:33]
	v_add3_u32 v14, v14, v36, s91
	v_add3_u32 v3, v15, v3, s91
	v_and_b32_sdwa v15, v35, v218 dst_sel:DWORD dst_unused:UNUSED_PAD src0_sel:WORD_1 src1_sel:DWORD
	v_and_b32_sdwa v36, v34, v218 dst_sel:DWORD dst_unused:UNUSED_PAD src0_sel:WORD_1 src1_sel:DWORD
	v_add3_u32 v15, v35, v15, s91
	v_add3_u32 v34, v34, v36, s91
	v_and_b32_e32 v15, 0xffff0000, v15
	v_and_b32_e32 v34, 0xffff0000, v34
	v_or_b32_sdwa v15, v15, v3 dst_sel:DWORD dst_unused:UNUSED_PAD src0_sel:DWORD src1_sel:WORD_1
	v_or_b32_sdwa v14, v34, v14 dst_sel:DWORD dst_unused:UNUSED_PAD src0_sel:DWORD src1_sel:WORD_1
	flat_store_dwordx2 v[6:7], v[14:15] offset:64
	v_mov_b32_e32 v14, v30
	v_mov_b32_e32 v15, v32
	v_pk_mul_f32 v[14:15], v[2:3], v[14:15] op_sel_hi:[0,1]
	v_mov_b32_e32 v32, v31
	v_pk_mul_f32 v[2:3], v[2:3], v[32:33] op_sel_hi:[0,1]
	v_and_b32_sdwa v30, v15, v218 dst_sel:DWORD dst_unused:UNUSED_PAD src0_sel:WORD_1 src1_sel:DWORD
	v_and_b32_sdwa v31, v14, v218 dst_sel:DWORD dst_unused:UNUSED_PAD src0_sel:WORD_1 src1_sel:DWORD
	v_add3_u32 v14, v14, v31, s91
	v_add3_u32 v15, v15, v30, s91
	v_and_b32_sdwa v30, v3, v218 dst_sel:DWORD dst_unused:UNUSED_PAD src0_sel:WORD_1 src1_sel:DWORD
	v_and_b32_sdwa v31, v2, v218 dst_sel:DWORD dst_unused:UNUSED_PAD src0_sel:WORD_1 src1_sel:DWORD
	v_add3_u32 v3, v3, v30, s91
	v_add3_u32 v2, v2, v31, s91
	v_and_b32_e32 v3, 0xffff0000, v3
	v_and_b32_e32 v2, 0xffff0000, v2
	v_or_b32_sdwa v3, v3, v15 dst_sel:DWORD dst_unused:UNUSED_PAD src0_sel:DWORD src1_sel:WORD_1
	v_or_b32_sdwa v2, v2, v14 dst_sel:DWORD dst_unused:UNUSED_PAD src0_sel:DWORD src1_sel:WORD_1
	flat_store_dwordx2 v[6:7], v[2:3] offset:96
	v_and_b32_e32 v46, 0xffff0000, v22
	v_and_b32_e32 v47, 0xffff0000, v23
	v_lshlrev_b32_e32 v48, 16, v24
	v_and_b32_e32 v50, 0xffff0000, v24
	v_lshlrev_b32_e32 v49, 16, v25
	v_and_b32_e32 v51, 0xffff0000, v25
	ds_read2_b64 v[22:25], v79 offset1:1
	v_lshlrev_b32_e32 v3, 16, v27
	v_and_b32_e32 v7, 0xffff0000, v27
	v_lshlrev_b32_e32 v14, 16, v28
	v_lshlrev_b32_e32 v15, 16, v29
	s_waitcnt lgkmcnt(0)
	v_readfirstlane_b32 s48, v22
	v_readfirstlane_b32 s49, v23
	s_add_u32 s0, s48, s0
	v_and_b32_e32 v43, 0xffff0000, v29
	s_addc_u32 s1, s49, s1
	s_nop 1
	v_lshl_add_u64 v[154:155], s[0:1], 0, v[0:1]
	global_load_dwordx4 v[156:159], v[154:155], off offset:144
	s_nop 1
	v_lshl_add_u64 v[148:149], s[0:1], 0, v[0:1]
	global_load_dwordx4 v[150:153], v[148:149], off offset:16
	v_mov_b32_e32 v28, v47
	v_mov_b32_e32 v29, v45
	v_lshlrev_b32_e32 v2, 16, v26
	v_and_b32_e32 v6, 0xffff0000, v26
	v_lshl_add_u64 v[22:23], s[0:1], 0, v[0:1]
	v_mov_b32_e32 v26, v7
	v_mov_b32_e32 v27, v3
	v_pk_mul_f32 v[28:29], v[28:29], v[28:29]
	flat_load_dwordx4 v[30:33], v[22:23] offset:128
	v_pk_fma_f32 v[52:53], v[26:27], v[26:27], v[28:29]
	flat_load_dwordx4 v[26:29], v[22:23]
	v_mov_b32_e32 v34, v51
	v_mov_b32_e32 v35, v49
	v_pk_mul_f32 v[34:35], v[34:35], v[34:35]
	v_mul_f32_e32 v0, v6, v6
	v_fmac_f32_e32 v0, v46, v46
	s_waitcnt vmcnt(0) lgkmcnt(0)
	v_mov_b32_e32 v76, v30
	v_mov_b32_e32 v77, v32
	v_mov_b32_e32 v32, v31
	v_mov_b32_e32 v30, v50
	v_mov_b32_e32 v31, v48
	v_mov_b32_e32 v74, v26
	v_mov_b32_e32 v75, v28
	v_mov_b32_e32 v28, v27
	v_mov_b32_e32 v26, v42
	v_mov_b32_e32 v27, v14
	v_pk_mul_f32 v[30:31], v[30:31], v[30:31]
	s_nop 0
	v_pk_fma_f32 v[26:27], v[26:27], v[26:27], v[30:31]
	v_mov_b32_e32 v30, v43
	v_mov_b32_e32 v31, v15
	v_pk_fma_f32 v[30:31], v[30:31], v[30:31], v[34:35]
	s_waitcnt vmcnt(0)
	s_nop 0
	v_mov_b32_e32 v34, v150
	v_mov_b32_e32 v35, v151
	v_mov_b32_e32 v36, v152
	v_mov_b32_e32 v37, v153
	s_nop 1
	s_waitcnt vmcnt(0)
	s_nop 0
	v_mov_b32_e32 v38, v156
	v_mov_b32_e32 v39, v157
	v_mov_b32_e32 v40, v158
	v_mov_b32_e32 v41, v159
	s_nop 1
	v_mul_f32_e32 v22, v2, v2
	v_fmac_f32_e32 v22, v44, v44
	v_add_f32_e32 v0, v22, v0
	v_add_f32_e32 v0, v53, v0
	v_add_f32_e32 v0, v52, v0
	v_add_f32_e32 v0, v27, v0
	v_add_f32_e32 v0, v26, v0
	v_add_f32_e32 v0, v31, v0
	v_add_f32_e32 v0, v30, v0
	ds_bpermute_b32 v22, v109, v0
	s_waitcnt lgkmcnt(0)
	v_add_f32_e32 v0, v0, v22
	ds_bpermute_b32 v22, v110, v0
	s_waitcnt lgkmcnt(0)
	v_add_f32_e32 v0, v0, v22
	v_fmamk_f32 v0, v0, 0x3c800000, v219
	v_cmp_gt_f32_e32 vcc, s6, v0
	v_mul_f32_e32 v22, 0x4f800000, v0
	s_nop 0
	v_cndmask_b32_e32 v0, v0, v22, vcc
	v_sqrt_f32_e32 v22, v0
	s_nop 0
	v_add_u32_e32 v23, -1, v22
	v_fma_f32 v26, -v23, v22, v0
	v_cmp_ge_f32_e64 s[88:89], 0, v26
	v_add_u32_e32 v26, 1, v22
	s_nop 0
	v_cndmask_b32_e64 v23, v22, v23, s[88:89]
	v_fma_f32 v22, -v26, v22, v0
	v_cmp_lt_f32_e64 s[88:89], 0, v22
	s_nop 1
	v_cndmask_b32_e64 v22, v23, v26, s[88:89]
	v_mul_f32_e32 v23, 0x37800000, v22
	v_cndmask_b32_e32 v22, v22, v23, vcc
	v_cmp_class_f32_e32 vcc, v0, v221
	s_mov_b32 s89, 0xf149f2ca
	s_movk_i32 s88, 0x90
	v_cndmask_b32_e32 v0, v22, v0, vcc
	v_div_scale_f32 v22, s[0:1], v0, v0, 1.0
	v_rcp_f32_e32 v23, v22
	v_readfirstlane_b32 s0, v24
	v_readfirstlane_b32 s1, v25
	s_add_u32 s0, s0, s2
	v_fma_f32 v26, -v22, v23, 1.0
	v_fmac_f32_e32 v23, v26, v23
	v_div_scale_f32 v26, vcc, 1.0, v0, 1.0
	v_mul_f32_e32 v27, v26, v23
	v_fma_f32 v30, -v22, v27, v26
	v_fmac_f32_e32 v27, v30, v23
	v_fma_f32 v22, -v22, v27, v26
	v_div_fmas_f32 v22, v22, v23, v27
	v_div_fixup_f32 v0, v22, v0, 1.0
	v_pk_mul_f32 v[26:27], v[0:1], v[46:47] op_sel_hi:[0,1]
	v_pk_mul_f32 v[6:7], v[0:1], v[6:7] op_sel_hi:[0,1]
	v_pk_mul_f32 v[26:27], v[26:27], v[32:33]
	v_pk_mul_f32 v[14:15], v[0:1], v[14:15] op_sel_hi:[0,1]
	v_pk_mul_f32 v[22:23], v[0:1], v[44:45] op_sel_hi:[0,1]
	v_pk_mul_f32 v[6:7], v[6:7], v[28:29]
	v_pk_mul_f32 v[30:31], v[12:13], v[26:27]
	v_pk_mul_f32 v[42:43], v[0:1], v[42:43] op_sel_hi:[0,1]
	v_pk_fma_f32 v[30:31], v[20:21], v[6:7], v[30:31]
	v_pk_mul_f32 v[20:21], v[20:21], v[26:27]
	v_pk_mul_f32 v[2:3], v[0:1], v[2:3] op_sel_hi:[0,1]
	v_pk_fma_f32 v[6:7], v[12:13], v[6:7], v[20:21] neg_lo:[0,0,1] neg_hi:[0,0,1]
	v_pk_mul_f32 v[22:23], v[76:77], v[22:23]
	v_pk_mul_f32 v[2:3], v[74:75], v[2:3]
	v_pk_mul_f32 v[28:29], v[102:103], v[22:23]
	s_waitcnt vmcnt(0)
	v_mov_b32_e32 v32, v34
	v_mov_b32_e32 v33, v36
	v_pk_mul_f32 v[14:15], v[14:15], v[32:33]
	v_pk_mul_f32 v[32:33], v[0:1], v[48:49] op_sel_hi:[0,1]
	v_mov_b32_e32 v44, v38
	v_mov_b32_e32 v45, v40
	v_mov_b32_e32 v36, v35
	v_pk_mul_f32 v[32:33], v[32:33], v[44:45]
	v_pk_mul_f32 v[34:35], v[42:43], v[36:37]
	v_pk_mul_f32 v[36:37], v[0:1], v[50:51] op_sel_hi:[0,1]
	v_mov_b32_e32 v40, v39
	v_pk_mul_f32 v[36:37], v[36:37], v[40:41]
	v_pk_mul_f32 v[12:13], v[18:19], v[32:33]
	v_pk_mul_f32 v[38:39], v[10:11], v[32:33]
	v_pk_fma_f32 v[10:11], v[10:11], v[14:15], v[12:13] neg_lo:[0,0,1] neg_hi:[0,0,1]
	v_pk_mul_f32 v[12:13], v[16:17], v[36:37]
	v_pk_mul_f32 v[40:41], v[8:9], v[36:37]
	v_pk_mul_f32 v[22:23], v[104:105], v[22:23]
	v_pk_mul_f32 v[6:7], v[6:7], s[86:87] op_sel_hi:[1,0]
	v_pk_fma_f32 v[8:9], v[8:9], v[34:35], v[12:13] neg_lo:[0,0,1] neg_hi:[0,0,1]
	v_pk_fma_f32 v[28:29], v[104:105], v[2:3], v[28:29]
	v_pk_fma_f32 v[38:39], v[18:19], v[14:15], v[38:39]
	v_pk_fma_f32 v[2:3], v[102:103], v[2:3], v[22:23] neg_lo:[0,0,1] neg_hi:[0,0,1]
	v_pk_mul_f32 v[10:11], v[10:11], s[86:87] op_sel_hi:[1,0]
	v_pk_mul_f32 v[8:9], v[8:9], s[86:87] op_sel_hi:[1,0]
	v_bfe_u32 v13, v7, 16, 1
	v_bfe_u32 v14, v6, 16, 1
	v_pk_mul_f32 v[2:3], v[2:3], s[86:87] op_sel_hi:[1,0]
	v_bfe_u32 v0, v9, 16, 1
	v_add3_u32 v6, v6, v14, s91
	v_add3_u32 v7, v7, v13, s91
	v_bfe_u32 v13, v10, 16, 1
	v_bfe_u32 v14, v11, 16, 1
	v_pk_mul_f32 v[28:29], v[28:29], s[86:87] op_sel_hi:[1,0]
	v_bfe_u32 v12, v8, 16, 1
	v_add3_u32 v0, v9, v0, s91
	v_bfe_u32 v9, v2, 16, 1
	v_add3_u32 v11, v11, v14, s91
	v_add3_u32 v10, v10, v13, s91
	v_pk_mul_f32 v[30:31], v[30:31], s[86:87] op_sel_hi:[1,0]
	v_pk_mul_f32 v[38:39], v[38:39], s[86:87] op_sel_hi:[1,0]
	v_add3_u32 v8, v8, v12, s91
	v_bfe_u32 v12, v3, 16, 1
	v_add3_u32 v2, v2, v9, s91
	v_lshrrev_b32_e32 v10, 16, v10
	v_lshrrev_b32_e32 v9, 16, v11
	v_bfe_u32 v11, v28, 16, 1
	v_add3_u32 v3, v3, v12, s91
	v_and_or_b32 v8, v8, s33, v10
	v_bfe_u32 v10, v30, 16, 1
	v_bfe_u32 v12, v29, 16, 1
	v_bfe_u32 v13, v38, 16, 1
	v_bfe_u32 v14, v39, 16, 1
	v_add3_u32 v11, v28, v11, s91
	v_add3_u32 v10, v30, v10, s91
	v_add3_u32 v14, v39, v14, s91
	v_add3_u32 v13, v38, v13, s91
	v_add3_u32 v12, v29, v12, s91
	v_lshrrev_b32_e32 v15, 16, v11
	v_pk_fma_f32 v[40:41], v[16:17], v[34:35], v[40:41]
	v_lshrrev_b32_e32 v11, 16, v12
	v_lshrrev_b32_e32 v12, 16, v13
	v_lshrrev_b32_e32 v13, 16, v14
	v_and_or_b32 v10, v10, s33, v15
	ds_read_b128 v[14:17], v100
	ds_read_b128 v[18:21], v100 offset:64
	v_lshrrev_b32_e32 v2, 16, v2
	v_lshrrev_b32_e32 v3, 16, v3
	v_and_or_b32 v9, v0, s33, v9
	v_and_or_b32 v7, v7, s33, v3
	v_and_or_b32 v6, v6, s33, v2
	v_pk_mul_f32 v[40:41], v[40:41], s[86:87] op_sel_hi:[1,0]
	v_bfe_u32 v3, v31, 16, 1
	s_waitcnt lgkmcnt(1)
	v_mfma_f32_16x16x32_bf16 v[14:17], v[14:17], v[6:9], 0
	v_bfe_u32 v0, v41, 16, 1
	v_bfe_u32 v2, v40, 16, 1
	v_add3_u32 v3, v31, v3, s91
	v_add3_u32 v2, v40, v2, s91
	v_add3_u32 v0, v41, v0, s91
	v_and_or_b32 v13, v0, s33, v13
	v_and_or_b32 v12, v2, s33, v12
	v_and_or_b32 v11, v3, s33, v11
	ds_read_b128 v[22:25], v98 offset:64
	s_addc_u32 s1, s1, s3
	s_nop 1
	v_mov_b64_e32 v[160:161], s[0:1]
	global_load_dword v162, v[160:161], off offset:8
	s_waitcnt lgkmcnt(1)
	v_mfma_f32_16x16x32_bf16 v[14:17], v[18:21], v[10:13], v[14:17]
	ds_read_b128 v[18:21], v98
	v_mov_b64_e32 v[2:3], s[0:1]
	s_waitcnt vmcnt(0)
	s_nop 0
	v_mov_b32_e32 v0, v162
	s_nop 1
	s_waitcnt lgkmcnt(0)
	v_mfma_f32_16x16x32_bf16 v[18:21], v[18:21], v[6:9], 0
	ds_read_b128 v[26:29], v96 offset:64
	ds_read_b128 v[30:33], v94 offset:64
	v_mfma_f32_16x16x32_bf16 v[18:21], v[22:25], v[10:13], v[18:21]
	ds_read_b128 v[22:25], v96
	v_readlane_b32 s0, v255, 22
	v_mov_b32_e32 v2, s89
	s_waitcnt lgkmcnt(0)
	v_mfma_f32_16x16x32_bf16 v[22:25], v[22:25], v[6:9], 0
	v_readlane_b32 s1, v255, 23
	v_cndmask_b32_e64 v3, v14, v2, s[8:9]
	v_mfma_f32_16x16x32_bf16 v[22:25], v[26:29], v[10:13], v[22:25]
	ds_read_b128 v[26:29], v94
	ds_read_b128 v[34:37], v92 offset:64
	s_waitcnt lgkmcnt(0)
	v_mfma_f32_16x16x32_bf16 v[26:29], v[26:29], v[6:9], 0
	ds_read_b128 v[38:41], v90 offset:64
	v_mfma_f32_16x16x32_bf16 v[26:29], v[30:33], v[10:13], v[26:29]
	ds_read_b128 v[30:33], v92
	s_waitcnt lgkmcnt(0)
	v_mfma_f32_16x16x32_bf16 v[30:33], v[30:33], v[6:9], 0
	v_mfma_f32_16x16x32_bf16 v[30:33], v[34:37], v[10:13], v[30:33]
	ds_read_b128 v[34:37], v90
	ds_read_b128 v[42:45], v88 offset:64
	s_waitcnt lgkmcnt(0)
	v_mfma_f32_16x16x32_bf16 v[34:37], v[34:37], v[6:9], 0
	ds_read_b128 v[46:49], v86 offset:64
	v_mfma_f32_16x16x32_bf16 v[34:37], v[38:41], v[10:13], v[34:37]
	ds_read_b128 v[38:41], v88
	s_waitcnt lgkmcnt(0)
	v_mfma_f32_16x16x32_bf16 v[38:41], v[38:41], v[6:9], 0
	s_nop 4
	v_cndmask_b32_e64 v37, v37, v227, s[36:37]
	v_mfma_f32_16x16x32_bf16 v[38:41], v[42:45], v[10:13], v[38:41]
	ds_read_b128 v[42:45], v86
	ds_read_b128 v[50:53], v84 offset:64
	s_waitcnt lgkmcnt(0)
	v_mfma_f32_16x16x32_bf16 v[42:45], v[42:45], v[6:9], 0
	s_nop 3
	v_cndmask_b32_e64 v39, v39, v227, s[46:47]
	v_cndmask_b32_e64 v40, v40, v227, s[50:51]
	v_cndmask_b32_e64 v41, v41, v227, s[52:53]
	v_mfma_f32_16x16x32_bf16 v[42:45], v[46:49], v[10:13], v[42:45]
	ds_read_b128 v[46:49], v84
	s_waitcnt lgkmcnt(0)
	v_mfma_f32_16x16x32_bf16 v[46:49], v[46:49], v[6:9], 0
	s_nop 4
	v_cndmask_b32_e64 v43, v43, v227, s[56:57]
	v_cndmask_b32_e64 v44, v44, v227, s[58:59]
	v_cndmask_b32_e64 v45, v45, v227, s[60:61]
	v_mfma_f32_16x16x32_bf16 v[46:49], v[50:53], v[10:13], v[46:49]
	ds_read_b128 v[50:53], v82
	s_waitcnt lgkmcnt(0)
	v_mfma_f32_16x16x32_bf16 v[6:9], v[50:53], v[6:9], 0
	ds_read_b128 v[50:53], v82 offset:64
	s_nop 3
	v_cndmask_b32_e64 v47, v47, v227, s[64:65]
	v_cndmask_b32_e64 v48, v48, v227, s[66:67]
	s_waitcnt lgkmcnt(0)
	v_mfma_f32_16x16x32_bf16 v[6:9], v[50:53], v[10:13], v[6:9]
	v_cndmask_b32_e64 v10, v15, v227, s[0:1]
	v_max3_f32 v2, v3, s89, v10
	v_cndmask_b32_e64 v11, v16, v227, s[40:41]
	v_cndmask_b32_e64 v12, v17, v227, s[92:93]
	v_max3_f32 v13, v2, v11, v12
	v_mov_b32_e32 v2, s89
	v_cndmask_b32_e64 v14, v18, v2, s[18:19]
	v_cndmask_b32_e64 v15, v19, v227, s[10:11]
	v_max3_f32 v2, v13, v14, v15
	v_cndmask_b32_e64 v13, v20, v227, s[12:13]
	v_cndmask_b32_e64 v16, v21, v227, s[44:45]
	v_max3_f32 v17, v2, v13, v16
	v_mov_b32_e32 v2, s89
	v_cndmask_b32_e64 v18, v22, v2, s[16:17]
	v_cndmask_b32_e64 v19, v23, v227, s[80:81]
	v_max3_f32 v2, v17, v18, v19
	v_cndmask_b32_e64 v17, v24, v227, s[82:83]
	v_cndmask_b32_e64 v20, v25, v227, s[84:85]
	v_max3_f32 v21, v2, v17, v20
	v_mov_b32_e32 v2, s89
	v_cndmask_b32_e64 v22, v26, v2, s[20:21]
	v_cndmask_b32_e64 v23, v27, v227, s[76:77]
	v_max3_f32 v2, v21, v22, v23
	v_cndmask_b32_e64 v21, v28, v227, s[78:79]
	v_cndmask_b32_e64 v24, v29, v227, s[14:15]
	v_max3_f32 v25, v2, v21, v24
	v_mov_b32_e32 v2, s89
	v_cndmask_b32_e64 v26, v30, v2, s[28:29]
	v_cndmask_b32_e64 v27, v31, v227, s[42:43]
	v_max3_f32 v2, v25, v26, v27
	v_cndmask_b32_e64 v25, v32, v227, s[22:23]
	v_cndmask_b32_e64 v50, v33, v227, s[26:27]
	v_max3_f32 v28, v2, v25, v50
	v_mov_b32_e32 v2, s89
	v_cndmask_b32_e64 v51, v34, v2, s[38:39]
	v_cndmask_b32_e64 v52, v35, v227, s[30:31]
	v_max3_f32 v2, v28, v51, v52
	v_cndmask_b32_e64 v53, v36, v227, s[34:35]
	v_max3_f32 v28, v2, v53, v37
	v_mov_b32_e32 v2, s89
	v_cndmask_b32_e64 v38, v38, v2, s[54:55]
	v_max3_f32 v2, v28, v38, v39
	v_max3_f32 v28, v2, v40, v41
	v_mov_b32_e32 v2, s89
	v_cndmask_b32_e64 v42, v42, v2, s[62:63]
	v_max3_f32 v2, v28, v42, v43
	v_max3_f32 v28, v2, v44, v45
	v_mov_b32_e32 v2, s89
	v_cndmask_b32_e64 v46, v46, v2, s[4:5]
	v_max3_f32 v2, v28, v46, v47
	v_cndmask_b32_e64 v49, v49, v227, s[68:69]
	v_max3_f32 v28, v2, v48, v49
	v_mov_b32_e32 v2, s89
	v_cndmask_b32_e64 v74, v6, v2, s[24:25]
	v_cndmask_b32_e64 v75, v7, v227, s[70:71]
	v_max3_f32 v2, v28, v74, v75
	v_cndmask_b32_e64 v76, v8, v227, s[72:73]
	v_cndmask_b32_e64 v77, v9, v227, s[74:75]
	v_max3_f32 v2, v2, v76, v77
	ds_bpermute_b32 v6, v109, v2
	v_readlane_b32 s40, v254, 60
	s_mov_b32 s85, 0xf800000
	s_waitcnt lgkmcnt(0)
	v_max_f32_e32 v6, v6, v6
	v_max_f32_e32 v2, v2, v6
	ds_bpermute_b32 v6, v110, v2
	s_waitcnt vmcnt(0) lgkmcnt(0)
	v_max3_f32 v79, v2, v6, v0
	v_sub_f32_e32 v2, v3, v79
	v_sub_f32_e32 v3, v10, v79
	v_mul_f32_e32 v3, 0x3fb8aa3b, v3
	v_exp_f32_e32 v82, v3
	v_sub_f32_e32 v3, v11, v79
	v_mul_f32_e32 v3, 0x3fb8aa3b, v3
	v_exp_f32_e32 v83, v3
	v_sub_f32_e32 v3, v12, v79
	v_mul_f32_e32 v3, 0x3fb8aa3b, v3
	v_exp_f32_e32 v84, v3
	v_sub_f32_e32 v3, v14, v79
	v_mul_f32_e32 v3, 0x3fb8aa3b, v3
	v_exp_f32_e32 v85, v3
	v_sub_f32_e32 v3, v15, v79
	v_mul_f32_e32 v3, 0x3fb8aa3b, v3
	v_exp_f32_e32 v86, v3
	v_sub_f32_e32 v3, v13, v79
	v_mul_f32_e32 v3, 0x3fb8aa3b, v3
	v_exp_f32_e32 v87, v3
	v_sub_f32_e32 v3, v16, v79
	v_mul_f32_e32 v3, 0x3fb8aa3b, v3
	v_exp_f32_e32 v88, v3
	v_sub_f32_e32 v3, v18, v79
	v_mul_f32_e32 v3, 0x3fb8aa3b, v3
	v_exp_f32_e32 v28, v3
	v_sub_f32_e32 v3, v19, v79
	v_mul_f32_e32 v3, 0x3fb8aa3b, v3
	v_exp_f32_e32 v30, v3
	v_sub_f32_e32 v3, v17, v79
	v_mul_f32_e32 v3, 0x3fb8aa3b, v3
	v_exp_f32_e32 v29, v3
	v_sub_f32_e32 v3, v20, v79
	v_mul_f32_e32 v3, 0x3fb8aa3b, v3
	v_exp_f32_e32 v31, v3
	v_sub_f32_e32 v3, v22, v79
	v_mul_f32_e32 v3, 0x3fb8aa3b, v3
	v_exp_f32_e32 v32, v3
	v_sub_f32_e32 v3, v23, v79
	v_mul_f32_e32 v3, 0x3fb8aa3b, v3
	v_exp_f32_e32 v33, v3
	v_sub_f32_e32 v3, v21, v79
	v_mul_f32_e32 v3, 0x3fb8aa3b, v3
	v_exp_f32_e32 v34, v3
	v_sub_f32_e32 v3, v24, v79
	v_mul_f32_e32 v3, 0x3fb8aa3b, v3
	v_mul_f32_e32 v2, 0x3fb8aa3b, v2
	v_exp_f32_e32 v35, v3
	v_sub_f32_e32 v3, v26, v79
	v_exp_f32_e32 v36, v2
	v_mul_f32_e32 v3, 0x3fb8aa3b, v3
	v_exp_f32_e32 v20, v3
	v_sub_f32_e32 v3, v27, v79
	v_mul_f32_e32 v3, 0x3fb8aa3b, v3
	v_exp_f32_e32 v22, v3
	v_sub_f32_e32 v3, v25, v79
	v_add_f32_e32 v2, 0, v36
	v_mul_f32_e32 v3, 0x3fb8aa3b, v3
	v_add_f32_e32 v2, v82, v2
	v_exp_f32_e32 v21, v3
	v_sub_f32_e32 v3, v50, v79
	v_add_f32_e32 v2, v83, v2
	v_mul_f32_e32 v3, 0x3fb8aa3b, v3
	v_add_f32_e32 v2, v84, v2
	v_exp_f32_e32 v23, v3
	v_sub_f32_e32 v3, v51, v79
	v_add_f32_e32 v2, v85, v2
	v_mul_f32_e32 v3, 0x3fb8aa3b, v3
	v_add_f32_e32 v2, v86, v2
	v_exp_f32_e32 v24, v3
	v_sub_f32_e32 v3, v52, v79
	v_add_f32_e32 v2, v87, v2
	v_mul_f32_e32 v3, 0x3fb8aa3b, v3
	v_add_f32_e32 v2, v88, v2
	v_exp_f32_e32 v25, v3
	v_sub_f32_e32 v3, v53, v79
	v_add_f32_e32 v2, v28, v2
	v_mul_f32_e32 v3, 0x3fb8aa3b, v3
	v_add_f32_e32 v2, v30, v2
	v_exp_f32_e32 v26, v3
	v_sub_f32_e32 v3, v37, v79
	v_add_f32_e32 v2, v29, v2
	v_mul_f32_e32 v3, 0x3fb8aa3b, v3
	v_add_f32_e32 v2, v31, v2
	v_exp_f32_e32 v27, v3
	v_sub_f32_e32 v3, v38, v79
	v_add_f32_e32 v2, v32, v2
	v_mul_f32_e32 v3, 0x3fb8aa3b, v3
	v_add_f32_e32 v2, v33, v2
	v_exp_f32_e32 v12, v3
	v_sub_f32_e32 v3, v39, v79
	v_add_f32_e32 v2, v34, v2
	v_mul_f32_e32 v3, 0x3fb8aa3b, v3
	v_add_f32_e32 v2, v35, v2
	v_exp_f32_e32 v14, v3
	v_sub_f32_e32 v3, v40, v79
	v_add_f32_e32 v2, v20, v2
	v_mul_f32_e32 v3, 0x3fb8aa3b, v3
	v_add_f32_e32 v2, v22, v2
	v_exp_f32_e32 v13, v3
	v_sub_f32_e32 v3, v41, v79
	v_add_f32_e32 v2, v21, v2
	v_mul_f32_e32 v3, 0x3fb8aa3b, v3
	v_add_f32_e32 v2, v23, v2
	v_exp_f32_e32 v15, v3
	v_sub_f32_e32 v3, v42, v79
	v_add_f32_e32 v2, v24, v2
	v_mul_f32_e32 v3, 0x3fb8aa3b, v3
	v_add_f32_e32 v2, v25, v2
	v_exp_f32_e32 v16, v3
	v_sub_f32_e32 v3, v43, v79
	v_add_f32_e32 v2, v26, v2
	v_mul_f32_e32 v3, 0x3fb8aa3b, v3
	v_add_f32_e32 v2, v27, v2
	v_exp_f32_e32 v17, v3
	v_sub_f32_e32 v3, v44, v79
	v_add_f32_e32 v2, v12, v2
	v_mul_f32_e32 v3, 0x3fb8aa3b, v3
	v_add_f32_e32 v2, v14, v2
	v_exp_f32_e32 v18, v3
	v_sub_f32_e32 v3, v45, v79
	v_add_f32_e32 v2, v13, v2
	v_mul_f32_e32 v3, 0x3fb8aa3b, v3
	v_add_f32_e32 v2, v15, v2
	v_exp_f32_e32 v19, v3
	v_add_f32_e32 v2, v16, v2
	v_add_f32_e32 v2, v17, v2
	v_add_f32_e32 v2, v18, v2
	v_add_f32_e32 v3, v19, v2
	v_sub_f32_e32 v2, v46, v79
	v_mul_f32_e32 v2, 0x3fb8aa3b, v2
	v_sub_f32_e32 v6, v47, v79
	v_exp_f32_e32 v2, v2
	v_mul_f32_e32 v6, 0x3fb8aa3b, v6
	v_exp_f32_e32 v6, v6
	v_sub_f32_e32 v8, v49, v79
	v_add_f32_e32 v3, v2, v3
	v_mul_f32_e32 v8, 0x3fb8aa3b, v8
	v_add_f32_e32 v7, v6, v3
	v_sub_f32_e32 v3, v48, v79
	v_mul_f32_e32 v3, 0x3fb8aa3b, v3
	v_exp_f32_e32 v3, v3
	v_exp_f32_e32 v8, v8
	v_sub_f32_e32 v10, v75, v79
	v_mul_f32_e32 v10, 0x3fb8aa3b, v10
	v_add_f32_e32 v7, v3, v7
	v_add_f32_e32 v9, v8, v7
	v_sub_f32_e32 v7, v74, v79
	v_mul_f32_e32 v7, 0x3fb8aa3b, v7
	v_exp_f32_e32 v7, v7
	v_exp_f32_e32 v10, v10
	v_sub_f32_e32 v0, v0, v79
	v_mul_f32_e32 v0, 0x3fb8aa3b, v0
	v_add_f32_e32 v9, v7, v9
	v_add_f32_e32 v11, v10, v9
	v_sub_f32_e32 v9, v76, v79
	v_mul_f32_e32 v9, 0x3fb8aa3b, v9
	v_exp_f32_e32 v9, v9
	v_exp_f32_e32 v0, v0
	v_bfe_u32 v39, v84, 16, 1
	v_add3_u32 v41, v84, v39, s91
	v_add_f32_e32 v37, v9, v11
	v_sub_f32_e32 v11, v77, v79
	v_mul_f32_e32 v11, 0x3fb8aa3b, v11
	v_exp_f32_e32 v11, v11
	v_bfe_u32 v39, v36, 16, 1
	v_bfe_u32 v42, v83, 16, 1
	v_bfe_u32 v43, v85, 16, 1
	v_add_f32_e32 v37, v11, v37
	ds_bpermute_b32 v38, v109, v37
	v_bfe_u32 v44, v87, 16, 1
	v_bfe_u32 v40, v82, 16, 1
	v_add3_u32 v44, v87, v44, s91
	v_add3_u32 v43, v85, v43, s91
	s_waitcnt lgkmcnt(0)
	v_add_f32_e32 v37, v37, v38
	ds_bpermute_b32 v38, v110, v37
	v_add3_u32 v42, v83, v42, s91
	v_add3_u32 v36, v36, v39, s91
	v_add3_u32 v40, v82, v40, s91
	v_lshrrev_b32_e32 v36, 16, v36
	s_waitcnt lgkmcnt(0)
	v_add_f32_e32 v37, v37, v38
	v_add_f32_e32 v0, v0, v37
	v_bfe_u32 v37, v88, 16, 1
	v_bfe_u32 v38, v86, 16, 1
	v_add3_u32 v38, v86, v38, s91
	v_add3_u32 v37, v88, v37, s91
	v_lshrrev_b32_e32 v42, 16, v42
	v_lshrrev_b32_e32 v43, 16, v43
	v_lshrrev_b32_e32 v39, 16, v44
	v_and_or_b32 v39, v37, s33, v39
	v_and_or_b32 v38, v38, s33, v43
	v_and_or_b32 v37, v41, s33, v42
	v_and_or_b32 v36, v40, s33, v36
	ds_read2_b64 v[40:43], v73 offset1:4
	ds_read2_b64 v[44:47], v72 offset0:32 offset1:36
	ds_read2_b64 v[48:51], v71 offset0:64 offset1:68
	ds_read2_b64 v[70:73], v70 offset0:96 offset1:100
	s_waitcnt lgkmcnt(3)
	v_mfma_f32_16x16x32_bf16 v[40:43], v[40:43], v[36:39], 0
	v_bfe_u32 v52, v35, 16, 1
	v_bfe_u32 v53, v33, 16, 1
	s_waitcnt lgkmcnt(2)
	v_mfma_f32_16x16x32_bf16 v[44:47], v[44:47], v[36:39], 0
	s_waitcnt lgkmcnt(1)
	v_mfma_f32_16x16x32_bf16 v[48:51], v[48:51], v[36:39], 0
	s_waitcnt lgkmcnt(0)
	v_mfma_f32_16x16x32_bf16 v[36:39], v[70:73], v[36:39], 0
	v_bfe_u32 v70, v31, 16, 1
	v_bfe_u32 v71, v30, 16, 1
	v_add3_u32 v71, v30, v71, s91
	v_add3_u32 v70, v31, v70, s91
	v_add3_u32 v30, v33, v53, s91
	v_add3_u32 v31, v35, v52, s91
	v_bfe_u32 v52, v32, 16, 1
	v_bfe_u32 v53, v34, 16, 1
	v_bfe_u32 v33, v28, 16, 1
	v_add3_u32 v34, v34, v53, s91
	v_add3_u32 v32, v32, v52, s91
	v_bfe_u32 v35, v29, 16, 1
	v_add3_u32 v28, v28, v33, s91
	v_lshrrev_b32_e32 v32, 16, v32
	v_lshrrev_b32_e32 v33, 16, v34
	v_add3_u32 v29, v29, v35, s91
	v_and_or_b32 v31, v31, s33, v33
	v_and_or_b32 v30, v30, s33, v32
	ds_read2_b64 v[32:35], v69 offset1:4
	v_lshrrev_b32_e32 v28, 16, v28
	v_lshrrev_b32_e32 v29, 16, v29
	v_and_or_b32 v29, v70, s33, v29
	v_and_or_b32 v28, v71, s33, v28
	s_waitcnt lgkmcnt(0)
	s_nop 0
	v_mfma_f32_16x16x32_bf16 v[32:35], v[32:35], v[28:31], v[40:43]
	s_nop 2
	ds_read2_b64 v[40:43], v68 offset0:32 offset1:36
	s_waitcnt lgkmcnt(0)
	v_mfma_f32_16x16x32_bf16 v[40:43], v[40:43], v[28:31], v[44:47]
	s_nop 2
	ds_read2_b64 v[44:47], v67 offset0:64 offset1:68
	s_waitcnt lgkmcnt(0)
	v_mfma_f32_16x16x32_bf16 v[44:47], v[44:47], v[28:31], v[48:51]
	s_nop 2
	ds_read2_b64 v[48:51], v66 offset0:96 offset1:100
	s_waitcnt lgkmcnt(0)
	v_mfma_f32_16x16x32_bf16 v[28:31], v[48:51], v[28:31], v[36:39]
	s_nop 2
	v_bfe_u32 v36, v27, 16, 1
	v_bfe_u32 v37, v25, 16, 1
	v_bfe_u32 v38, v23, 16, 1
	v_bfe_u32 v39, v22, 16, 1
	v_add3_u32 v39, v22, v39, s91
	v_add3_u32 v38, v23, v38, s91
	v_add3_u32 v22, v25, v37, s91
	v_add3_u32 v23, v27, v36, s91
	v_bfe_u32 v36, v24, 16, 1
	v_bfe_u32 v37, v26, 16, 1
	v_bfe_u32 v25, v20, 16, 1
	v_add3_u32 v26, v26, v37, s91
	v_add3_u32 v24, v24, v36, s91
	v_bfe_u32 v27, v21, 16, 1
	v_add3_u32 v20, v20, v25, s91
	v_lshrrev_b32_e32 v24, 16, v24
	v_lshrrev_b32_e32 v25, 16, v26
	v_add3_u32 v21, v21, v27, s91
	v_and_or_b32 v23, v23, s33, v25
	v_and_or_b32 v22, v22, s33, v24
	ds_read2_b64 v[24:27], v65 offset1:4
	v_lshrrev_b32_e32 v20, 16, v20
	v_lshrrev_b32_e32 v21, 16, v21
	v_and_or_b32 v21, v38, s33, v21
	v_and_or_b32 v20, v39, s33, v20
	ds_read2_b64 v[36:39], v63 offset0:64 offset1:68
	s_waitcnt lgkmcnt(1)
	v_mfma_f32_16x16x32_bf16 v[24:27], v[24:27], v[20:23], v[32:35]
	s_nop 2
	ds_read2_b64 v[32:35], v64 offset0:32 offset1:36
	s_waitcnt lgkmcnt(0)
	v_mfma_f32_16x16x32_bf16 v[32:35], v[32:35], v[20:23], v[40:43]
	s_nop 2
	ds_read2_b64 v[40:43], v62 offset0:96 offset1:100
	v_mfma_f32_16x16x32_bf16 v[36:39], v[36:39], v[20:23], v[44:47]
	s_waitcnt lgkmcnt(0)
	v_mfma_f32_16x16x32_bf16 v[20:23], v[40:43], v[20:23], v[28:31]
	s_nop 2
	v_bfe_u32 v28, v19, 16, 1
	v_bfe_u32 v29, v17, 16, 1
	v_bfe_u32 v30, v15, 16, 1
	v_bfe_u32 v31, v14, 16, 1
	v_add3_u32 v31, v14, v31, s91
	v_add3_u32 v30, v15, v30, s91
	v_add3_u32 v14, v17, v29, s91
	v_add3_u32 v15, v19, v28, s91
	v_bfe_u32 v28, v16, 16, 1
	v_bfe_u32 v29, v18, 16, 1
	v_bfe_u32 v17, v12, 16, 1
	v_add3_u32 v18, v18, v29, s91
	v_add3_u32 v16, v16, v28, s91
	v_bfe_u32 v19, v13, 16, 1
	v_add3_u32 v12, v12, v17, s91
	v_lshrrev_b32_e32 v16, 16, v16
	v_lshrrev_b32_e32 v17, 16, v18
	v_add3_u32 v13, v13, v19, s91
	v_and_or_b32 v15, v15, s33, v17
	v_and_or_b32 v14, v14, s33, v16
	ds_read2_b64 v[16:19], v61 offset1:4
	v_lshrrev_b32_e32 v12, 16, v12
	v_lshrrev_b32_e32 v13, 16, v13
	v_and_or_b32 v13, v30, s33, v13
	v_and_or_b32 v12, v31, s33, v12
	ds_read2_b64 v[28:31], v59 offset0:64 offset1:68
	s_waitcnt lgkmcnt(1)
	v_mfma_f32_16x16x32_bf16 v[16:19], v[16:19], v[12:15], v[24:27]
	s_nop 2
	ds_read2_b64 v[24:27], v60 offset0:32 offset1:36
	s_waitcnt lgkmcnt(0)
	v_mfma_f32_16x16x32_bf16 v[24:27], v[24:27], v[12:15], v[32:35]
	s_nop 2
	ds_read2_b64 v[32:35], v58 offset0:96 offset1:100
	v_mfma_f32_16x16x32_bf16 v[28:31], v[28:31], v[12:15], v[36:39]
	s_waitcnt lgkmcnt(0)
	v_mfma_f32_16x16x32_bf16 v[12:15], v[32:35], v[12:15], v[20:23]
	s_nop 2
	v_bfe_u32 v20, v11, 16, 1
	v_bfe_u32 v21, v10, 16, 1
	v_bfe_u32 v22, v8, 16, 1
	v_add3_u32 v22, v8, v22, s91
	v_add3_u32 v8, v10, v21, s91
	v_add3_u32 v10, v11, v20, s91
	v_bfe_u32 v20, v3, 16, 1
	v_bfe_u32 v21, v7, 16, 1
	v_bfe_u32 v23, v6, 16, 1
	v_add3_u32 v7, v7, v21, s91
	v_add3_u32 v3, v3, v20, s91
	v_add3_u32 v6, v6, v23, s91
	v_bfe_u32 v23, v9, 16, 1
	v_lshrrev_b32_e32 v3, 16, v3
	v_lshrrev_b32_e32 v7, 16, v7
	v_add3_u32 v9, v9, v23, s91
	v_and_or_b32 v8, v8, s33, v7
	v_and_or_b32 v7, v22, s33, v3
	ds_read2_b64 v[20:23], v57 offset1:4
	v_bfe_u32 v11, v2, 16, 1
	v_add3_u32 v2, v2, v11, s91
	v_lshrrev_b32_e32 v2, 16, v2
	v_lshrrev_b32_e32 v9, 16, v9
	v_and_or_b32 v9, v10, s33, v9
	v_and_or_b32 v6, v6, s33, v2
	v_div_scale_f32 v2, s[0:1], v0, v0, 1.0
	s_waitcnt lgkmcnt(0)
	v_mfma_f32_16x16x32_bf16 v[16:19], v[20:23], v[6:9], v[16:19]
	ds_read2_b64 v[20:23], v56 offset0:32 offset1:36
	v_rcp_f32_e32 v3, v2
	v_readlane_b32 s0, v254, 63
	s_waitcnt lgkmcnt(0)
	v_mfma_f32_16x16x32_bf16 v[20:23], v[20:23], v[6:9], v[24:27]
	s_nop 2
	ds_read2_b64 v[24:27], v55 offset0:64 offset1:68
	v_fma_f32 v10, -v2, v3, 1.0
	v_fmac_f32_e32 v3, v10, v3
	s_waitcnt lgkmcnt(0)
	v_mfma_f32_16x16x32_bf16 v[24:27], v[24:27], v[6:9], v[28:31]
	s_nop 2
	ds_read2_b64 v[28:31], v54 offset0:96 offset1:100
	v_div_scale_f32 v10, vcc, 1.0, v0, 1.0
	v_mul_f32_e32 v11, v10, v3
	s_waitcnt lgkmcnt(0)
	v_mfma_f32_16x16x32_bf16 v[6:9], v[28:31], v[6:9], v[12:15]
	s_nop 2
	v_fma_f32 v12, -v2, v11, v10
	v_fmac_f32_e32 v11, v12, v3
	v_fma_f32 v2, -v2, v11, v10
	v_div_fmas_f32 v2, v2, v3, v11
	v_div_fixup_f32 v0, v2, v0, 1.0
	v_mov_b32_e32 v10, v16
	v_mov_b32_e32 v11, v18
	v_pk_mul_f32 v[10:11], v[0:1], v[10:11] op_sel_hi:[0,1]
	v_mov_b32_e32 v18, v17
	v_pk_mul_f32 v[12:13], v[0:1], v[18:19] op_sel_hi:[0,1]
	v_and_b32_sdwa v14, v11, v218 dst_sel:DWORD dst_unused:UNUSED_PAD src0_sel:WORD_1 src1_sel:DWORD
	v_and_b32_sdwa v15, v10, v218 dst_sel:DWORD dst_unused:UNUSED_PAD src0_sel:WORD_1 src1_sel:DWORD
	v_add3_u32 v10, v10, v15, s91
	v_add3_u32 v11, v11, v14, s91
	v_and_b32_sdwa v14, v13, v218 dst_sel:DWORD dst_unused:UNUSED_PAD src0_sel:WORD_1 src1_sel:DWORD
	v_and_b32_sdwa v15, v12, v218 dst_sel:DWORD dst_unused:UNUSED_PAD src0_sel:WORD_1 src1_sel:DWORD
	v_add3_u32 v13, v13, v14, s91
	v_add3_u32 v12, v12, v15, s91
	s_lshl_b32 s94, s0, 1
	v_and_b32_e32 v13, 0xffff0000, v13
	v_and_b32_e32 v12, 0xffff0000, v12
	v_lshl_add_u64 v[2:3], v[80:81], 0, s[94:95]
	v_or_b32_sdwa v11, v13, v11 dst_sel:DWORD dst_unused:UNUSED_PAD src0_sel:DWORD src1_sel:WORD_1
	v_or_b32_sdwa v10, v12, v10 dst_sel:DWORD dst_unused:UNUSED_PAD src0_sel:DWORD src1_sel:WORD_1
	flat_store_dwordx2 v[2:3], v[10:11]
	v_mov_b32_e32 v10, v20
	v_mov_b32_e32 v11, v22
	v_pk_mul_f32 v[10:11], v[0:1], v[10:11] op_sel_hi:[0,1]
	v_mov_b32_e32 v22, v21
	v_pk_mul_f32 v[12:13], v[0:1], v[22:23] op_sel_hi:[0,1]
	v_and_b32_sdwa v14, v11, v218 dst_sel:DWORD dst_unused:UNUSED_PAD src0_sel:WORD_1 src1_sel:DWORD
	v_and_b32_sdwa v15, v10, v218 dst_sel:DWORD dst_unused:UNUSED_PAD src0_sel:WORD_1 src1_sel:DWORD
	v_add3_u32 v10, v10, v15, s91
	v_add3_u32 v11, v11, v14, s91
	v_and_b32_sdwa v14, v13, v218 dst_sel:DWORD dst_unused:UNUSED_PAD src0_sel:WORD_1 src1_sel:DWORD
	v_and_b32_sdwa v15, v12, v218 dst_sel:DWORD dst_unused:UNUSED_PAD src0_sel:WORD_1 src1_sel:DWORD
	v_add3_u32 v13, v13, v14, s91
	v_add3_u32 v12, v12, v15, s91
	v_and_b32_e32 v13, 0xffff0000, v13
	v_and_b32_e32 v12, 0xffff0000, v12
	v_or_b32_sdwa v11, v13, v11 dst_sel:DWORD dst_unused:UNUSED_PAD src0_sel:DWORD src1_sel:WORD_1
	v_or_b32_sdwa v10, v12, v10 dst_sel:DWORD dst_unused:UNUSED_PAD src0_sel:DWORD src1_sel:WORD_1
	flat_store_dwordx2 v[2:3], v[10:11] offset:32
	v_mov_b32_e32 v10, v24
	v_mov_b32_e32 v11, v26
	v_pk_mul_f32 v[10:11], v[0:1], v[10:11] op_sel_hi:[0,1]
	v_mov_b32_e32 v26, v25
	v_pk_mul_f32 v[12:13], v[0:1], v[26:27] op_sel_hi:[0,1]
	v_and_b32_sdwa v14, v11, v218 dst_sel:DWORD dst_unused:UNUSED_PAD src0_sel:WORD_1 src1_sel:DWORD
	v_and_b32_sdwa v15, v10, v218 dst_sel:DWORD dst_unused:UNUSED_PAD src0_sel:WORD_1 src1_sel:DWORD
	v_add3_u32 v10, v10, v15, s91
	v_add3_u32 v11, v11, v14, s91
	v_and_b32_sdwa v14, v13, v218 dst_sel:DWORD dst_unused:UNUSED_PAD src0_sel:WORD_1 src1_sel:DWORD
	v_and_b32_sdwa v15, v12, v218 dst_sel:DWORD dst_unused:UNUSED_PAD src0_sel:WORD_1 src1_sel:DWORD
	v_add3_u32 v13, v13, v14, s91
	v_add3_u32 v12, v12, v15, s91
	v_and_b32_e32 v13, 0xffff0000, v13
	v_and_b32_e32 v12, 0xffff0000, v12
	v_or_b32_sdwa v11, v13, v11 dst_sel:DWORD dst_unused:UNUSED_PAD src0_sel:DWORD src1_sel:WORD_1
	v_or_b32_sdwa v10, v12, v10 dst_sel:DWORD dst_unused:UNUSED_PAD src0_sel:DWORD src1_sel:WORD_1
	flat_store_dwordx2 v[2:3], v[10:11] offset:64
	v_mov_b32_e32 v10, v6
	v_mov_b32_e32 v11, v8
	v_pk_mul_f32 v[10:11], v[0:1], v[10:11] op_sel_hi:[0,1]
	v_mov_b32_e32 v8, v7
	v_pk_mul_f32 v[6:7], v[0:1], v[8:9] op_sel_hi:[0,1]
	v_and_b32_sdwa v8, v10, v218 dst_sel:DWORD dst_unused:UNUSED_PAD src0_sel:WORD_1 src1_sel:DWORD
	v_add3_u32 v8, v10, v8, s91
	v_and_b32_sdwa v9, v7, v218 dst_sel:DWORD dst_unused:UNUSED_PAD src0_sel:WORD_1 src1_sel:DWORD
	v_and_b32_sdwa v10, v6, v218 dst_sel:DWORD dst_unused:UNUSED_PAD src0_sel:WORD_1 src1_sel:DWORD
	v_and_b32_sdwa v0, v11, v218 dst_sel:DWORD dst_unused:UNUSED_PAD src0_sel:WORD_1 src1_sel:DWORD
	v_add3_u32 v7, v7, v9, s91
	v_add3_u32 v6, v6, v10, s91
	v_add3_u32 v0, v11, v0, s91
	v_and_b32_e32 v7, 0xffff0000, v7
	v_and_b32_e32 v6, 0xffff0000, v6
	v_or_b32_sdwa v7, v7, v0 dst_sel:DWORD dst_unused:UNUSED_PAD src0_sel:DWORD src1_sel:WORD_1
	v_or_b32_sdwa v6, v6, v8 dst_sel:DWORD dst_unused:UNUSED_PAD src0_sel:DWORD src1_sel:WORD_1
	flat_store_dwordx2 v[2:3], v[6:7] offset:96
	s_waitcnt lgkmcnt(0)
	s_barrier

.LBB0_406:
	s_nop 1
	global_load_dword v148, v[8:9], off
	flat_load_dword v13, v[10:11]
	v_add_u32_e32 v7, 8, v7
	s_waitcnt vmcnt(0) lgkmcnt(0)
	v_mul_f32_e32 v14, v13, v13
	ds_bpermute_b32 v14, v5, v14
	s_waitcnt lgkmcnt(0)
	v_fmac_f32_e32 v14, v13, v13
	ds_bpermute_b32 v15, v106, v14
	s_waitcnt lgkmcnt(0)
	v_add_f32_e32 v14, v14, v15
	ds_bpermute_b32 v15, v107, v14
	s_waitcnt lgkmcnt(0)
	v_add_f32_e32 v14, v14, v15
	ds_bpermute_b32 v15, v108, v14
	s_waitcnt lgkmcnt(0)
	v_add_f32_e32 v14, v14, v15
	ds_bpermute_b32 v15, v109, v14
	s_waitcnt lgkmcnt(0)
	v_add_f32_e32 v14, v14, v15
	ds_bpermute_b32 v15, v110, v14
	s_waitcnt lgkmcnt(0)
	v_add_f32_e32 v14, v14, v15
	v_fmamk_f32 v14, v14, 0x3c800000, v219
	v_cmp_gt_f32_e32 vcc, s85, v14
	v_mul_f32_e32 v15, 0x4f800000, v14
	s_nop 0
	v_cndmask_b32_e32 v14, v14, v15, vcc
	v_sqrt_f32_e32 v15, v14
	s_nop 0
	v_add_u32_e32 v16, -1, v15
	v_fma_f32 v17, -v16, v15, v14
	v_cmp_ge_f32_e64 s[6:7], 0, v17
	v_add_u32_e32 v17, 1, v15
	s_nop 0
	v_cndmask_b32_e64 v16, v15, v16, s[6:7]
	v_fma_f32 v15, -v17, v15, v14
	v_cmp_lt_f32_e64 s[6:7], 0, v15
	s_nop 1
	v_cndmask_b32_e64 v15, v16, v17, s[6:7]
	v_mul_f32_e32 v16, 0x37800000, v15
	v_cndmask_b32_e32 v15, v15, v16, vcc
	v_cmp_class_f32_e32 vcc, v14, v221
	s_nop 1
	v_cndmask_b32_e32 v14, v15, v14, vcc
	v_div_scale_f32 v15, s[6:7], v14, v14, 1.0
	v_rcp_f32_e32 v16, v15
	s_mov_b64 s[6:7], 0x800
	v_lshl_add_u64 v[10:11], v[10:11], 0, s[6:7]
	v_fma_f32 v17, -v15, v16, 1.0
	v_fmac_f32_e32 v16, v17, v16
	v_div_scale_f32 v17, vcc, 1.0, v14, 1.0
	v_mul_f32_e32 v18, v17, v16
	v_fma_f32 v19, -v15, v18, v17
	v_fmac_f32_e32 v18, v19, v16
	v_fma_f32 v15, -v15, v18, v17
	v_div_fmas_f32 v15, v15, v16, v18
	v_div_fixup_f32 v14, v15, v14, 1.0
	v_mul_f32_e32 v13, v13, v14
	s_waitcnt vmcnt(0)
	s_nop 0
	v_mov_b32_e32 v14, v148
	s_nop 1
	v_cmp_lt_i32_e32 vcc, -5, v7
	s_or_b64 s[2:3], vcc, s[2:3]
	s_waitcnt vmcnt(0) lgkmcnt(0)
	v_mul_f32_e32 v13, v14, v13
	v_mul_f32_e32 v13, 0x3e000000, v13
	ds_write_b32 v12, v13
	v_add_u32_e32 v12, 0x800, v12
	s_andn2_b64 exec, exec, s[2:3]
	s_cbranch_execnz .LBB0_406

.LBB0_443:
	s_nop 1
	global_load_dword v150, v[12:13], off
	s_nop 1
	global_load_dword v149, v[10:11], off
	s_nop 1
	global_load_dword v148, v[8:9], off
	v_ashrrev_i32_e32 v15, 31, v14
	v_lshl_add_u64 v[18:19], v[14:15], 2, s[10:11]
	flat_load_dword v15, v[18:19]
	v_add_u32_e32 v3, 8, v3
	v_add_u32_e32 v14, 0x200, v14
	s_waitcnt vmcnt(0) lgkmcnt(0)
	v_mul_f32_e32 v17, v15, v15
	ds_bpermute_b32 v17, v5, v17
	s_waitcnt lgkmcnt(0)
	v_fmac_f32_e32 v17, v15, v15
	ds_bpermute_b32 v18, v106, v17
	s_waitcnt lgkmcnt(0)
	v_add_f32_e32 v17, v17, v18
	ds_bpermute_b32 v18, v107, v17
	s_waitcnt lgkmcnt(0)
	v_add_f32_e32 v17, v17, v18
	ds_bpermute_b32 v18, v108, v17
	s_waitcnt lgkmcnt(0)
	v_add_f32_e32 v17, v17, v18
	ds_bpermute_b32 v18, v109, v17
	s_waitcnt lgkmcnt(0)
	v_add_f32_e32 v17, v17, v18
	ds_bpermute_b32 v18, v110, v17
	s_waitcnt lgkmcnt(0)
	v_add_f32_e32 v17, v17, v18
	v_fmamk_f32 v17, v17, 0x3c800000, v219
	v_cmp_gt_f32_e32 vcc, s85, v17
	v_mul_f32_e32 v18, 0x4f800000, v17
	s_nop 0
	v_cndmask_b32_e32 v17, v17, v18, vcc
	v_sqrt_f32_e32 v18, v17
	s_nop 0
	v_add_u32_e32 v19, -1, v18
	v_fma_f32 v20, -v19, v18, v17
	v_cmp_ge_f32_e64 s[8:9], 0, v20
	v_add_u32_e32 v20, 1, v18
	s_nop 0
	v_cndmask_b32_e64 v19, v18, v19, s[8:9]
	v_fma_f32 v18, -v20, v18, v17
	v_cmp_lt_f32_e64 s[8:9], 0, v18
	s_nop 1
	v_cndmask_b32_e64 v18, v19, v20, s[8:9]
	v_mul_f32_e32 v19, 0x37800000, v18
	v_cndmask_b32_e32 v18, v18, v19, vcc
	v_cmp_class_f32_e32 vcc, v17, v221
	s_nop 1
	v_cndmask_b32_e32 v17, v18, v17, vcc
	v_div_scale_f32 v18, s[8:9], v17, v17, 1.0
	v_rcp_f32_e32 v19, v18
	s_nop 0
	v_fma_f32 v20, -v18, v19, 1.0
	v_fmac_f32_e32 v19, v20, v19
	v_div_scale_f32 v20, vcc, 1.0, v17, 1.0
	v_mul_f32_e32 v21, v20, v19
	v_fma_f32 v23, -v18, v21, v20
	v_fmac_f32_e32 v21, v23, v19
	v_fma_f32 v18, -v18, v21, v20
	v_div_fmas_f32 v18, v18, v19, v21
	v_div_fixup_f32 v17, v18, v17, 1.0
	v_mul_f32_e32 v15, v15, v17
	s_waitcnt vmcnt(0)
	s_nop 0
	v_mov_b32_e32 v17, v148
	s_nop 1
	s_waitcnt vmcnt(0)
	s_nop 0
	v_mov_b32_e32 v18, v149
	s_nop 1
	s_waitcnt vmcnt(0)
	s_nop 0
	v_mov_b32_e32 v19, v150
	s_nop 1
	v_cmp_lt_i32_e32 vcc, 3, v3
	s_or_b64 s[18:19], vcc, s[18:19]
	s_waitcnt vmcnt(0) lgkmcnt(0)
	v_mul_f32_e32 v15, v17, v15
	ds_bpermute_b32 v17, v110, v15
	s_waitcnt lgkmcnt(0)
	v_mul_f32_e32 v17, v19, v17
	v_cndmask_b32_e64 v17, v17, -v17, s[6:7]
	v_fmac_f32_e32 v17, v18, v15
	v_mul_f32_e32 v15, 0x3e000000, v17
	ds_write_b32 v7, v15
	v_add_u32_e32 v7, 0x800, v7
	s_andn2_b64 exec, exec, s[18:19]
	s_cbranch_execnz .LBB0_443
.LBB0_444:
	s_or_b64 exec, exec, s[16:17]
	v_cmp_gt_i32_e32 vcc, 4, v2
	s_and_saveexec_b64 s[8:9], vcc
	s_cbranch_execz .LBB0_447
	s_nop 1
	v_and_b32_e32 v152, 0xffffffc0, v78
	v_or_b32_e32 v148, v152, v22
	v_add_u32_e32 v150, 0x500, v148
	v_ashrrev_i32_e32 v151, 31, v150
	v_lshl_add_u64 v[150:151], v[150:151], 2, s[10:11]
	global_load_dword v149, v[150:151], off
	v_and_b32_e32 v8, 0xffffffc0, v78
	v_or_b32_e32 v3, v8, v22
	v_add_u32_e32 v10, 0x400, v3
	v_ashrrev_i32_e32 v11, 31, v10
	v_lshl_add_u64 v[10:11], v[10:11], 2, s[10:11]
	flat_load_dword v9, v[10:11]
	v_readlane_b32 s6, v254, 15
	s_nop 1
	v_mov_b32_e32 v7, s6
	ds_read_b64 v[10:11], v7
	v_mov_b32_e32 v7, v1
	s_waitcnt lgkmcnt(0)
	v_readfirstlane_b32 s6, v10
	v_readfirstlane_b32 s7, v11
	s_nop 1
	v_lshl_add_u64 v[10:11], s[6:7], 0, v[0:1]
	flat_load_dword v12, v[10:11]
	v_lshl_add_u64 v[10:11], s[12:13], 0, v[6:7]
	v_lshl_add_u64 v[6:7], s[14:15], 0, v[6:7]
	flat_load_dword v10, v[10:11]
	s_nop 0
	flat_load_dword v11, v[6:7]
	v_add_u32_e32 v6, 0x500, v3
	v_ashrrev_i32_e32 v7, 31, v6
	v_lshl_add_u64 v[6:7], v[6:7], 2, s[10:11]
	s_waitcnt vmcnt(0)
	v_mul_f32_e32 v3, v9, v9
	ds_bpermute_b32 v13, v5, v3
	s_waitcnt vmcnt(0)
	s_nop 0
	v_mov_b32_e32 v3, v149
	s_nop 1
	s_waitcnt lgkmcnt(0)
	v_fmac_f32_e32 v13, v9, v9
	ds_bpermute_b32 v6, v106, v13
	s_waitcnt lgkmcnt(0)
	v_add_f32_e32 v6, v13, v6
	ds_bpermute_b32 v7, v107, v6
	s_waitcnt lgkmcnt(0)
	v_add_f32_e32 v6, v6, v7
	ds_bpermute_b32 v7, v108, v6
	s_waitcnt lgkmcnt(0)
	v_add_f32_e32 v6, v6, v7
	ds_bpermute_b32 v7, v109, v6
	s_waitcnt lgkmcnt(0)
	v_add_f32_e32 v6, v6, v7
	ds_bpermute_b32 v7, v110, v6
	s_waitcnt lgkmcnt(0)
	v_add_f32_e32 v6, v6, v7
	v_fmamk_f32 v6, v6, 0x3c800000, v219
	v_mul_f32_e32 v7, 0x4f800000, v6
	v_cmp_gt_f32_e32 vcc, s85, v6
	s_nop 1
	v_cndmask_b32_e32 v6, v6, v7, vcc
	v_sqrt_f32_e32 v7, v6
	s_nop 0
	v_add_u32_e32 v13, -1, v7
	v_add_u32_e32 v14, 1, v7
	v_fma_f32 v15, -v13, v7, v6
	v_fma_f32 v17, -v14, v7, v6
	v_cmp_ge_f32_e64 s[6:7], 0, v15
	s_nop 1
	v_cndmask_b32_e64 v7, v7, v13, s[6:7]
	v_cmp_lt_f32_e64 s[6:7], 0, v17
	s_nop 1
	v_cndmask_b32_e64 v7, v7, v14, s[6:7]
	v_mul_f32_e32 v13, 0x37800000, v7
	v_cndmask_b32_e32 v7, v7, v13, vcc
	v_cmp_class_f32_e32 vcc, v6, v221
	s_nop 1
	v_cndmask_b32_e32 v6, v7, v6, vcc
	v_div_scale_f32 v7, s[6:7], v6, v6, 1.0
	v_rcp_f32_e32 v13, v7
	v_div_scale_f32 v14, vcc, 1.0, v6, 1.0
	v_readlane_b32 s6, v254, 49
	v_fma_f32 v15, -v7, v13, 1.0
	v_fmac_f32_e32 v13, v15, v13
	v_mul_f32_e32 v15, v14, v13
	v_fma_f32 v17, -v7, v15, v14
	v_fmac_f32_e32 v15, v17, v13
	v_fma_f32 v7, -v7, v15, v14
	v_div_fmas_f32 v7, v7, v13, v15
	v_div_fixup_f32 v6, v7, v6, 1.0
	v_mul_f32_e32 v6, v9, v6
	v_mul_f32_e32 v7, v12, v6
	ds_bpermute_b32 v6, v110, v7
	v_cmp_gt_u32_e32 vcc, 32, v22
	v_lshl_add_u32 v9, v78, 2, 0
	v_readlane_b32 s7, v254, 50
	v_add_u32_e32 v9, 0xc0, v9
	s_waitcnt lgkmcnt(0)
	v_mul_f32_e32 v6, v11, v6
	v_cndmask_b32_e64 v6, v6, -v6, vcc
	v_fmac_f32_e32 v6, v10, v7
	s_andn2_b64 vcc, exec, s[6:7]
	s_waitcnt vmcnt(0)
	ds_write2st64_b32 v9, v6, v3 offset0:60 offset1:64
	s_cbranch_vccnz .LBB0_447
	v_readlane_b32 s6, v254, 8
	v_ashrrev_i32_e32 v9, 31, v8
	s_nop 0
	v_mov_b32_e32 v7, s6
	ds_read_b64 v[10:11], v7
	s_lshl_b64 s[6:7], s[94:95], 10
	s_waitcnt lgkmcnt(0)
	v_readfirstlane_b32 s10, v10
	v_readfirstlane_b32 s11, v11
	s_add_u32 s6, s10, s6
	s_addc_u32 s7, s11, s7
	v_lshl_add_u64 v[8:9], v[8:9], 2, s[6:7]
	v_lshl_add_u64 v[8:9], v[8:9], 0, v[0:1]
	v_add_co_u32_e32 v10, vcc, 0x6558000, v8
	s_nop 1
	v_addc_co_u32_e32 v11, vcc, 0, v9, vcc
	flat_store_dword v[10:11], v6
	v_add_co_u32_e32 v6, vcc, 0x6578000, v8
	s_nop 1
	v_addc_co_u32_e32 v7, vcc, 0, v9, vcc
	flat_store_dword v[6:7], v3

.LBB0_459:
	v_add_u32_e32 v28, s4, v30
	v_mad_i64_i32 v[6:7], s[4:5], s14, v28, 0
	v_lshl_add_u64 v[10:11], v[6:7], 1, v[2:3]
	v_mov_b32_e32 v14, s9
	flat_load_dwordx4 v[6:9], v[10:11] nt
	s_nop 0
	flat_load_dwordx4 v[10:13], v[10:11] offset:64 nt
	ds_read_b64 v[14:15], v14
	s_lshl_b64 s[4:5], s[12:13], 2
	v_ashrrev_i32_e32 v29, 31, v28
	s_waitcnt lgkmcnt(0)
	v_readfirstlane_b32 s6, v14
	v_readfirstlane_b32 s7, v15
	s_add_u32 s4, s6, s4
	s_addc_u32 s5, s7, s5
	s_nop 1
	v_lshl_add_u64 v[160:161], s[4:5], 0, v[0:1]
	global_load_dwordx4 v[162:165], v[160:161], off offset:144
	s_nop 1
	v_lshl_add_u64 v[154:155], s[4:5], 0, v[0:1]
	global_load_dwordx4 v[156:159], v[154:155], off offset:16
	s_nop 1
	v_lshl_add_u64 v[148:149], s[4:5], 0, v[0:1]
	global_load_dwordx4 v[150:153], v[148:149], off
	v_lshl_add_u64 v[18:19], s[4:5], 0, v[0:1]
	flat_load_dwordx4 v[14:17], v[18:19] offset:128
	s_waitcnt vmcnt(0)
	v_lshlrev_b32_e32 v37, 16, v7
	v_lshlrev_b32_e32 v21, 16, v11
	v_lshlrev_b32_e32 v20, 16, v10
	v_and_b32_e32 v23, 0xffff0000, v11
	v_and_b32_e32 v22, 0xffff0000, v10
	v_and_b32_e32 v35, 0xffff0000, v13
	v_and_b32_e32 v34, 0xffff0000, v12
	v_lshlrev_b32_e32 v36, 16, v6
	v_and_b32_e32 v39, 0xffff0000, v7
	v_and_b32_e32 v38, 0xffff0000, v6
	v_mov_b32_e32 v6, v23
	v_mov_b32_e32 v7, v21
	s_waitcnt lgkmcnt(0)
	v_mov_b32_e32 v24, v14
	v_mov_b32_e32 v25, v16
	v_mov_b32_e32 v16, v15
	v_lshlrev_b32_e32 v15, 16, v13
	v_lshlrev_b32_e32 v14, 16, v12
	s_waitcnt vmcnt(0)
	s_nop 0
	v_mov_b32_e32 v10, v150
	v_mov_b32_e32 v11, v151
	v_mov_b32_e32 v12, v152
	v_mov_b32_e32 v13, v153
	s_nop 1
	v_pk_mul_f32 v[6:7], v[6:7], v[6:7]
	v_mov_b32_e32 v40, v39
	v_mov_b32_e32 v41, v37
	v_pk_fma_f32 v[40:41], v[40:41], v[40:41], v[6:7]
	v_and_b32_e32 v45, 0xffff0000, v9
	v_and_b32_e32 v44, 0xffff0000, v8
	v_mul_f32_e32 v27, v38, v38
	v_mul_f32_e32 v33, v36, v36
	v_fmac_f32_e32 v27, v22, v22
	v_fmac_f32_e32 v33, v20, v20
	v_mov_b32_e32 v46, v34
	v_mov_b32_e32 v47, v14
	v_add_f32_e32 v27, v33, v27
	v_pk_mul_f32 v[46:47], v[46:47], v[46:47]
	v_mov_b32_e32 v48, v44
	v_add_f32_e32 v27, v41, v27
	v_add_f32_e32 v27, v40, v27
	v_mov_b32_e32 v50, v45
	s_waitcnt vmcnt(0) lgkmcnt(0)
	v_mov_b32_e32 v42, v10
	v_mov_b32_e32 v43, v12
	v_mov_b32_e32 v12, v11
	v_lshlrev_b32_e32 v11, 16, v9
	v_lshlrev_b32_e32 v10, 16, v8
	s_waitcnt vmcnt(0)
	s_nop 0
	v_mov_b32_e32 v6, v156
	v_mov_b32_e32 v7, v157
	v_mov_b32_e32 v8, v158
	v_mov_b32_e32 v9, v159
	s_nop 1
	v_mov_b32_e32 v49, v10
	v_pk_fma_f32 v[46:47], v[48:49], v[48:49], v[46:47]
	v_mov_b32_e32 v48, v35
	v_mov_b32_e32 v49, v15
	v_pk_mul_f32 v[48:49], v[48:49], v[48:49]
	v_mov_b32_e32 v51, v11
	v_add_f32_e32 v27, v47, v27
	v_pk_fma_f32 v[48:49], v[50:51], v[50:51], v[48:49]
	v_add_f32_e32 v27, v46, v27
	v_add_f32_e32 v27, v49, v27
	v_add_f32_e32 v27, v48, v27
	ds_bpermute_b32 v33, v109, v27
	s_waitcnt lgkmcnt(0)
	v_add_f32_e32 v27, v27, v33
	ds_bpermute_b32 v33, v110, v27
	s_waitcnt lgkmcnt(0)
	v_add_f32_e32 v27, v27, v33
	v_fmamk_f32 v27, v27, 0x3c800000, v219
	v_cmp_gt_f32_e32 vcc, s85, v27
	v_mul_f32_e32 v33, 0x4f800000, v27
	s_nop 0
	v_cndmask_b32_e32 v27, v27, v33, vcc
	v_sqrt_f32_e32 v33, v27
	s_nop 0
	v_add_u32_e32 v40, -1, v33
	v_fma_f32 v41, -v40, v33, v27
	v_cmp_ge_f32_e64 s[4:5], 0, v41
	v_add_u32_e32 v41, 1, v33
	s_nop 0
	v_cndmask_b32_e64 v40, v33, v40, s[4:5]
	v_fma_f32 v33, -v41, v33, v27
	v_cmp_lt_f32_e64 s[4:5], 0, v33
	s_nop 1
	v_cndmask_b32_e64 v33, v40, v41, s[4:5]
	v_mul_f32_e32 v40, 0x37800000, v33
	v_cndmask_b32_e32 v33, v33, v40, vcc
	v_cmp_class_f32_e32 vcc, v27, v221
	s_nop 1
	v_cndmask_b32_e32 v27, v33, v27, vcc
	v_div_scale_f32 v33, s[4:5], v27, v27, s86
	v_rcp_f32_e32 v40, v33
	s_nop 0
	v_fma_f32 v41, -v33, v40, 1.0
	v_fmac_f32_e32 v40, v41, v40
	v_div_scale_f32 v41, vcc, s86, v27, s86
	v_mul_f32_e32 v46, v41, v40
	v_fma_f32 v47, -v33, v46, v41
	v_fmac_f32_e32 v46, v47, v40
	v_fma_f32 v33, -v33, v46, v41
	v_div_fmas_f32 v33, v33, v40, v46
	v_div_fixup_f32 v40, v33, v27, s86
	v_pk_mul_f32 v[38:39], v[40:41], v[38:39] op_sel_hi:[0,1]
	v_pk_mul_f32 v[12:13], v[12:13], v[38:39]
	v_pk_mul_f32 v[10:11], v[40:41], v[10:11] op_sel_hi:[0,1]
	v_pk_mul_f32 v[36:37], v[40:41], v[36:37] op_sel_hi:[0,1]
	v_pk_mul_f32 v[36:37], v[42:43], v[36:37]
	v_bfe_u32 v27, v13, 16, 1
	v_bfe_u32 v33, v12, 16, 1
	v_add3_u32 v12, v12, v33, s91
	v_add3_u32 v13, v13, v27, s91
	v_pk_mul_f32 v[14:15], v[40:41], v[14:15] op_sel_hi:[0,1]
	s_waitcnt vmcnt(0)
	v_mov_b32_e32 v38, v6
	v_mov_b32_e32 v39, v8
	v_pk_mul_f32 v[10:11], v[38:39], v[10:11]
	v_pk_mul_f32 v[38:39], v[40:41], v[44:45] op_sel_hi:[0,1]
	v_mov_b32_e32 v8, v7
	v_pk_mul_f32 v[6:7], v[8:9], v[38:39]
	v_bfe_u32 v27, v10, 16, 1
	v_bfe_u32 v8, v7, 16, 1
	v_bfe_u32 v9, v6, 16, 1
	v_add3_u32 v6, v6, v9, s91
	v_add3_u32 v7, v7, v8, s91
	v_bfe_u32 v8, v36, 16, 1
	v_bfe_u32 v9, v37, 16, 1
	v_bfe_u32 v33, v11, 16, 1
	v_add3_u32 v11, v11, v33, s91
	v_add3_u32 v10, v10, v27, s91
	v_add3_u32 v9, v37, v9, s91
	v_add3_u32 v8, v36, v8, s91
	v_lshrrev_b32_e32 v27, 16, v8
	v_lshrrev_b32_e32 v33, 16, v9
	v_lshrrev_b32_e32 v8, 16, v10
	v_lshrrev_b32_e32 v9, 16, v11
	v_pk_mul_f32 v[10:11], v[40:41], v[20:21] op_sel_hi:[0,1]
	v_pk_mul_f32 v[20:21], v[24:25], v[10:11]
	v_pk_mul_f32 v[10:11], v[40:41], v[22:23] op_sel_hi:[0,1]
	v_and_or_b32 v9, v7, s33, v9
	v_and_or_b32 v8, v6, s33, v8
	v_and_or_b32 v7, v13, s33, v33
	v_and_or_b32 v6, v12, s33, v27
	v_pk_mul_f32 v[16:17], v[16:17], v[10:11]
	s_waitcnt vmcnt(0)
	s_nop 0
	v_mov_b32_e32 v10, v162
	v_mov_b32_e32 v11, v163
	v_mov_b32_e32 v12, v164
	v_mov_b32_e32 v13, v165
	s_nop 1
	s_waitcnt vmcnt(0) lgkmcnt(0)
	v_mov_b32_e32 v18, v10
	v_mov_b32_e32 v19, v12
	v_pk_mul_f32 v[14:15], v[18:19], v[14:15]
	v_pk_mul_f32 v[18:19], v[40:41], v[34:35] op_sel_hi:[0,1]
	v_mov_b32_e32 v12, v11
	v_pk_mul_f32 v[10:11], v[18:19], v[12:13]
	v_bfe_u32 v18, v17, 16, 1
	v_bfe_u32 v12, v11, 16, 1
	v_bfe_u32 v13, v10, 16, 1
	v_bfe_u32 v19, v16, 16, 1
	v_add3_u32 v16, v16, v19, s91
	v_add3_u32 v17, v17, v18, s91
	v_add3_u32 v10, v10, v13, s91
	v_add3_u32 v11, v11, v12, s91
	v_bfe_u32 v12, v20, 16, 1
	v_bfe_u32 v13, v21, 16, 1
	v_bfe_u32 v18, v14, 16, 1
	v_bfe_u32 v19, v15, 16, 1
	v_add3_u32 v15, v15, v19, s91
	v_add3_u32 v14, v14, v18, s91
	v_add3_u32 v13, v21, v13, s91
	v_add3_u32 v12, v20, v12, s91
	v_lshrrev_b32_e32 v18, 16, v12
	v_lshrrev_b32_e32 v19, 16, v13
	v_lshrrev_b32_e32 v12, 16, v14
	v_lshrrev_b32_e32 v13, 16, v15
	v_and_or_b32 v13, v11, s33, v13
	v_and_or_b32 v12, v10, s33, v12
	v_and_or_b32 v11, v17, s33, v19
	v_and_or_b32 v10, v16, s33, v18
	ds_read_b128 v[14:17], v31
	ds_read_b128 v[18:21], v31 offset:64
	s_waitcnt lgkmcnt(1)
	v_mfma_f32_16x16x32_bf16 v[14:17], v[14:17], v[6:9], 0
	s_waitcnt lgkmcnt(0)
	v_mfma_f32_16x16x32_bf16 v[34:37], v[18:21], v[10:13], v[14:17]
	ds_read_b128 v[18:21], v31 offset:2368
	s_nop 4
	ds_read_b128 v[14:17], v31 offset:2304
	s_waitcnt lgkmcnt(0)
	v_mfma_f32_16x16x32_bf16 v[14:17], v[14:17], v[6:9], 0
	v_mfma_f32_16x16x32_bf16 v[38:41], v[18:21], v[10:13], v[14:17]
	ds_read_b128 v[18:21], v31 offset:4672
	s_nop 5
	ds_read_b128 v[14:17], v31 offset:4608
	s_waitcnt lgkmcnt(0)
	v_mfma_f32_16x16x32_bf16 v[14:17], v[14:17], v[6:9], 0
	v_mfma_f32_16x16x32_bf16 v[42:45], v[18:21], v[10:13], v[14:17]
	ds_read_b128 v[18:21], v31 offset:6976
	s_nop 5
	ds_read_b128 v[14:17], v31 offset:6912
	s_waitcnt lgkmcnt(0)
	v_mfma_f32_16x16x32_bf16 v[14:17], v[14:17], v[6:9], 0
	v_mfma_f32_16x16x32_bf16 v[50:53], v[18:21], v[10:13], v[14:17]
	ds_read_b128 v[18:21], v31 offset:9280
	s_nop 5
	ds_read_b128 v[14:17], v31 offset:9216
	s_waitcnt lgkmcnt(0)
	v_mfma_f32_16x16x32_bf16 v[14:17], v[14:17], v[6:9], 0
	v_mfma_f32_16x16x32_bf16 v[56:59], v[18:21], v[10:13], v[14:17]
	ds_read_b128 v[18:21], v31 offset:11584
	s_nop 5
	ds_read_b128 v[14:17], v31 offset:11520
	s_waitcnt lgkmcnt(0)
	v_mfma_f32_16x16x32_bf16 v[14:17], v[14:17], v[6:9], 0
	v_mfma_f32_16x16x32_bf16 v[66:69], v[18:21], v[10:13], v[14:17]
	ds_read_b128 v[18:21], v31 offset:13888
	s_nop 5
	ds_read_b128 v[14:17], v31 offset:13824
	s_waitcnt lgkmcnt(0)
	v_mfma_f32_16x16x32_bf16 v[14:17], v[14:17], v[6:9], 0
	v_mfma_f32_16x16x32_bf16 v[74:77], v[18:21], v[10:13], v[14:17]
	ds_read_b128 v[18:21], v31 offset:16192
	s_nop 5
	ds_read_b128 v[14:17], v31 offset:16128
	s_waitcnt lgkmcnt(0)
	v_mfma_f32_16x16x32_bf16 v[14:17], v[14:17], v[6:9], 0
	v_mfma_f32_16x16x32_bf16 v[80:83], v[18:21], v[10:13], v[14:17]
	ds_read_b128 v[18:21], v31 offset:18496
	s_nop 5
	ds_read_b128 v[14:17], v31 offset:18432
	s_waitcnt lgkmcnt(0)
	v_mfma_f32_16x16x32_bf16 v[14:17], v[14:17], v[6:9], 0
	v_mfma_f32_16x16x32_bf16 v[84:87], v[18:21], v[10:13], v[14:17]
	ds_read_b128 v[18:21], v31 offset:20800
	s_nop 5
	ds_read_b128 v[14:17], v31 offset:20736
	s_waitcnt lgkmcnt(0)
	v_mfma_f32_16x16x32_bf16 v[14:17], v[14:17], v[6:9], 0
	v_mfma_f32_16x16x32_bf16 v[88:91], v[18:21], v[10:13], v[14:17]
	ds_read_b128 v[18:21], v31 offset:23104
	s_nop 5
	ds_read_b128 v[14:17], v31 offset:23040
	s_waitcnt lgkmcnt(0)
	v_mfma_f32_16x16x32_bf16 v[14:17], v[14:17], v[6:9], 0
	v_mfma_f32_16x16x32_bf16 v[92:95], v[18:21], v[10:13], v[14:17]
	ds_read_b128 v[18:21], v31 offset:25408
	s_nop 5
	ds_read_b128 v[14:17], v31 offset:25344
	s_waitcnt lgkmcnt(0)
	v_mfma_f32_16x16x32_bf16 v[14:17], v[14:17], v[6:9], 0
	v_mfma_f32_16x16x32_bf16 v[96:99], v[18:21], v[10:13], v[14:17]
	ds_read_b128 v[18:21], v31 offset:27712
	s_nop 5
	ds_read_b128 v[14:17], v31 offset:27648
	s_waitcnt lgkmcnt(0)
	v_mfma_f32_16x16x32_bf16 v[14:17], v[14:17], v[6:9], 0
	v_mfma_f32_16x16x32_bf16 v[22:25], v[18:21], v[10:13], v[14:17]
	ds_read_b128 v[18:21], v31 offset:30016
	s_nop 5
	ds_read_b128 v[14:17], v31 offset:29952
	s_waitcnt lgkmcnt(0)
	v_mfma_f32_16x16x32_bf16 v[14:17], v[14:17], v[6:9], 0
	ds_read_b128 v[46:49], v31 offset:32320
	v_mfma_f32_16x16x32_bf16 v[18:21], v[18:21], v[10:13], v[14:17]
	s_nop 5
	ds_read_b128 v[14:17], v31 offset:32256
	s_waitcnt lgkmcnt(0)
	v_mfma_f32_16x16x32_bf16 v[14:17], v[14:17], v[6:9], 0
	v_mfma_f32_16x16x32_bf16 v[14:17], v[46:49], v[10:13], v[14:17]
	ds_read_b128 v[46:49], v31 offset:34560
	s_waitcnt lgkmcnt(0)
	v_mfma_f32_16x16x32_bf16 v[6:9], v[46:49], v[6:9], 0
	ds_read_b128 v[46:49], v31 offset:34624
	s_waitcnt lgkmcnt(0)
	v_mfma_f32_16x16x32_bf16 v[6:9], v[46:49], v[10:13], v[6:9]
	v_max3_f32 v10, v34, s89, v35
	v_max3_f32 v10, v10, v36, v37
	v_max3_f32 v10, v10, v38, v39
	v_max3_f32 v10, v10, v40, v41
	v_max3_f32 v10, v10, v42, v43
	v_max3_f32 v10, v10, v44, v45
	v_max3_f32 v10, v10, v50, v51
	v_max3_f32 v10, v10, v52, v53
	v_max3_f32 v10, v10, v56, v57
	v_max3_f32 v10, v10, v58, v59
	v_max3_f32 v10, v10, v66, v67
	v_max3_f32 v10, v10, v68, v69
	v_max3_f32 v10, v10, v74, v75
	v_max3_f32 v10, v10, v76, v77
	v_max3_f32 v10, v10, v80, v81
	v_max3_f32 v10, v10, v82, v83
	v_max3_f32 v10, v10, v84, v85
	v_max3_f32 v10, v10, v86, v87
	v_max3_f32 v10, v10, v88, v89
	v_max3_f32 v10, v10, v90, v91
	v_max3_f32 v10, v10, v92, v93
	v_max3_f32 v10, v10, v94, v95
	v_max3_f32 v10, v10, v96, v97
	v_max3_f32 v10, v10, v98, v99
	v_max3_f32 v10, v10, v22, v23
	v_max3_f32 v10, v10, v24, v25
	v_max3_f32 v10, v10, v18, v19
	v_max3_f32 v10, v10, v20, v21
	v_max3_f32 v10, v10, v14, v15
	v_max3_f32 v10, v10, v16, v17
	v_max3_f32 v10, v10, v6, v7
	v_max3_f32 v10, v10, v8, v9
	ds_bpermute_b32 v11, v109, v10
	s_waitcnt lgkmcnt(0)
	v_max_f32_e32 v11, v11, v11
	v_max_f32_e32 v10, v10, v11
	ds_bpermute_b32 v11, v110, v10
	s_waitcnt lgkmcnt(0)
	v_max_f32_e32 v11, v11, v11
	v_max_f32_e32 v73, v10, v11
	v_sub_f32_e32 v11, v35, v73
	v_mul_f32_e32 v11, 0x3fb8aa3b, v11
	v_exp_f32_e32 v100, v11
	v_sub_f32_e32 v11, v36, v73
	v_mul_f32_e32 v11, 0x3fb8aa3b, v11
	v_exp_f32_e32 v101, v11
	v_sub_f32_e32 v11, v37, v73
	v_mul_f32_e32 v11, 0x3fb8aa3b, v11
	v_exp_f32_e32 v102, v11
	v_sub_f32_e32 v11, v38, v73
	v_mul_f32_e32 v11, 0x3fb8aa3b, v11
	v_exp_f32_e32 v103, v11
	v_sub_f32_e32 v11, v39, v73
	v_mul_f32_e32 v11, 0x3fb8aa3b, v11
	v_exp_f32_e32 v104, v11
	v_sub_f32_e32 v11, v40, v73
	v_mul_f32_e32 v11, 0x3fb8aa3b, v11
	v_exp_f32_e32 v105, v11
	v_sub_f32_e32 v11, v41, v73
	v_mul_f32_e32 v11, 0x3fb8aa3b, v11
	v_exp_f32_e32 v111, v11
	v_sub_f32_e32 v11, v42, v73
	v_mul_f32_e32 v11, 0x3fb8aa3b, v11
	v_sub_f32_e32 v10, v34, v73
	v_exp_f32_e32 v34, v11
	v_sub_f32_e32 v11, v43, v73
	v_mul_f32_e32 v11, 0x3fb8aa3b, v11
	v_exp_f32_e32 v46, v11
	v_sub_f32_e32 v11, v44, v73
	v_mul_f32_e32 v11, 0x3fb8aa3b, v11
	v_exp_f32_e32 v39, v11
	v_sub_f32_e32 v11, v45, v73
	v_mul_f32_e32 v11, 0x3fb8aa3b, v11
	v_exp_f32_e32 v55, v11
	v_sub_f32_e32 v11, v50, v73
	v_mul_f32_e32 v11, 0x3fb8aa3b, v11
	v_exp_f32_e32 v50, v11
	v_sub_f32_e32 v11, v51, v73
	v_mul_f32_e32 v11, 0x3fb8aa3b, v11
	v_exp_f32_e32 v65, v11
	v_sub_f32_e32 v11, v52, v73
	v_mul_f32_e32 v11, 0x3fb8aa3b, v11
	v_exp_f32_e32 v62, v11
	v_sub_f32_e32 v11, v53, v73
	v_mul_f32_e32 v11, 0x3fb8aa3b, v11
	v_exp_f32_e32 v72, v11
	v_sub_f32_e32 v11, v56, v73
	v_mul_f32_e32 v11, 0x3fb8aa3b, v11
	v_exp_f32_e32 v33, v11
	v_sub_f32_e32 v11, v57, v73
	v_mul_f32_e32 v11, 0x3fb8aa3b, v11
	v_exp_f32_e32 v44, v11
	v_sub_f32_e32 v11, v58, v73
	v_mul_f32_e32 v11, 0x3fb8aa3b, v11
	v_exp_f32_e32 v38, v11
	v_sub_f32_e32 v11, v59, v73
	v_mul_f32_e32 v11, 0x3fb8aa3b, v11
	v_exp_f32_e32 v54, v11
	v_sub_f32_e32 v11, v66, v73
	v_mul_f32_e32 v11, 0x3fb8aa3b, v11
	v_exp_f32_e32 v49, v11
	v_sub_f32_e32 v11, v67, v73
	v_mul_f32_e32 v11, 0x3fb8aa3b, v11
	v_exp_f32_e32 v64, v11
	v_sub_f32_e32 v11, v68, v73
	v_mul_f32_e32 v11, 0x3fb8aa3b, v11
	v_exp_f32_e32 v60, v11
	v_sub_f32_e32 v11, v69, v73
	v_mul_f32_e32 v11, 0x3fb8aa3b, v11
	v_exp_f32_e32 v71, v11
	v_sub_f32_e32 v11, v74, v73
	v_mul_f32_e32 v11, 0x3fb8aa3b, v11
	v_mul_f32_e32 v10, 0x3fb8aa3b, v10
	v_exp_f32_e32 v27, v11
	v_sub_f32_e32 v11, v75, v73
	v_exp_f32_e32 v79, v10
	v_mul_f32_e32 v11, 0x3fb8aa3b, v11
	v_exp_f32_e32 v43, v11
	v_sub_f32_e32 v11, v76, v73
	v_mul_f32_e32 v11, 0x3fb8aa3b, v11
	v_exp_f32_e32 v37, v11
	v_sub_f32_e32 v11, v77, v73
	v_add_f32_e32 v10, 0, v79
	v_mul_f32_e32 v11, 0x3fb8aa3b, v11
	v_add_f32_e32 v10, v100, v10
	v_exp_f32_e32 v53, v11
	v_sub_f32_e32 v11, v80, v73
	v_add_f32_e32 v10, v101, v10
	v_mul_f32_e32 v11, 0x3fb8aa3b, v11
	v_add_f32_e32 v10, v102, v10
	v_exp_f32_e32 v48, v11
	v_sub_f32_e32 v11, v81, v73
	v_add_f32_e32 v10, v103, v10
	v_mul_f32_e32 v11, 0x3fb8aa3b, v11
	v_add_f32_e32 v10, v104, v10
	v_exp_f32_e32 v63, v11
	v_sub_f32_e32 v11, v82, v73
	v_add_f32_e32 v10, v105, v10
	v_mul_f32_e32 v11, 0x3fb8aa3b, v11
	v_add_f32_e32 v10, v111, v10
	v_exp_f32_e32 v58, v11
	v_sub_f32_e32 v11, v83, v73
	v_add_f32_e32 v10, v34, v10
	v_mul_f32_e32 v11, 0x3fb8aa3b, v11
	v_add_f32_e32 v10, v46, v10
	v_exp_f32_e32 v70, v11
	v_sub_f32_e32 v11, v84, v73
	v_add_f32_e32 v10, v39, v10
	v_mul_f32_e32 v11, 0x3fb8aa3b, v11
	v_add_f32_e32 v10, v55, v10
	v_exp_f32_e32 v13, v11
	v_sub_f32_e32 v11, v85, v73
	v_add_f32_e32 v10, v50, v10
	v_mul_f32_e32 v11, 0x3fb8aa3b, v11
	v_add_f32_e32 v10, v65, v10
	v_exp_f32_e32 v42, v11
	v_sub_f32_e32 v11, v86, v73
	v_add_f32_e32 v10, v62, v10
	v_mul_f32_e32 v11, 0x3fb8aa3b, v11
	v_add_f32_e32 v10, v72, v10
	v_exp_f32_e32 v36, v11
	v_sub_f32_e32 v11, v87, v73
	v_add_f32_e32 v10, v33, v10
	v_mul_f32_e32 v11, 0x3fb8aa3b, v11
	v_add_f32_e32 v10, v44, v10
	v_exp_f32_e32 v52, v11
	v_sub_f32_e32 v11, v88, v73
	v_add_f32_e32 v10, v38, v10
	v_mul_f32_e32 v11, 0x3fb8aa3b, v11
	v_add_f32_e32 v10, v54, v10
	v_exp_f32_e32 v47, v11
	v_sub_f32_e32 v11, v89, v73
	v_add_f32_e32 v10, v49, v10
	v_mul_f32_e32 v11, 0x3fb8aa3b, v11
	v_add_f32_e32 v10, v64, v10
	v_exp_f32_e32 v61, v11
	v_sub_f32_e32 v11, v90, v73
	v_add_f32_e32 v10, v60, v10
	v_mul_f32_e32 v11, 0x3fb8aa3b, v11
	v_add_f32_e32 v10, v71, v10
	v_exp_f32_e32 v57, v11
	v_sub_f32_e32 v11, v91, v73
	v_add_f32_e32 v10, v27, v10
	v_mul_f32_e32 v11, 0x3fb8aa3b, v11
	v_add_f32_e32 v10, v43, v10
	v_exp_f32_e32 v69, v11
	v_sub_f32_e32 v11, v92, v73
	v_add_f32_e32 v10, v37, v10
	v_mul_f32_e32 v11, 0x3fb8aa3b, v11
	v_add_f32_e32 v10, v53, v10
	v_exp_f32_e32 v12, v11
	v_sub_f32_e32 v11, v93, v73
	v_add_f32_e32 v10, v48, v10
	v_mul_f32_e32 v11, 0x3fb8aa3b, v11
	v_add_f32_e32 v10, v63, v10
	v_exp_f32_e32 v41, v11
	v_sub_f32_e32 v11, v94, v73
	v_add_f32_e32 v10, v58, v10
	v_mul_f32_e32 v11, 0x3fb8aa3b, v11
	v_add_f32_e32 v10, v70, v10
	v_exp_f32_e32 v35, v11
	v_sub_f32_e32 v11, v95, v73
	v_add_f32_e32 v10, v13, v10
	v_mul_f32_e32 v11, 0x3fb8aa3b, v11
	v_add_f32_e32 v10, v42, v10
	v_exp_f32_e32 v51, v11
	v_sub_f32_e32 v11, v96, v73
	v_add_f32_e32 v10, v36, v10
	v_mul_f32_e32 v11, 0x3fb8aa3b, v11
	v_add_f32_e32 v10, v52, v10
	v_exp_f32_e32 v45, v11
	v_sub_f32_e32 v11, v97, v73
	v_add_f32_e32 v10, v47, v10
	v_mul_f32_e32 v11, 0x3fb8aa3b, v11
	v_add_f32_e32 v10, v61, v10
	v_exp_f32_e32 v59, v11
	v_sub_f32_e32 v11, v98, v73
	v_add_f32_e32 v10, v57, v10
	v_mul_f32_e32 v11, 0x3fb8aa3b, v11
	v_add_f32_e32 v10, v69, v10
	v_exp_f32_e32 v56, v11
	v_sub_f32_e32 v11, v99, v73
	v_add_f32_e32 v10, v12, v10
	v_mul_f32_e32 v11, 0x3fb8aa3b, v11
	v_add_f32_e32 v10, v41, v10
	v_exp_f32_e32 v68, v11
	v_sub_f32_e32 v11, v22, v73
	v_sub_f32_e32 v22, v23, v73
	v_add_f32_e32 v10, v35, v10
	v_mul_f32_e32 v22, 0x3fb8aa3b, v22
	v_add_f32_e32 v10, v51, v10
	v_mul_f32_e32 v11, 0x3fb8aa3b, v11
	v_exp_f32_e32 v40, v22
	v_sub_f32_e32 v22, v24, v73
	v_add_f32_e32 v10, v45, v10
	v_exp_f32_e32 v11, v11
	v_mul_f32_e32 v22, 0x3fb8aa3b, v22
	v_add_f32_e32 v10, v59, v10
	v_exp_f32_e32 v23, v22
	v_sub_f32_e32 v22, v25, v73
	v_sub_f32_e32 v19, v19, v73
	v_add_f32_e32 v10, v56, v10
	v_mul_f32_e32 v22, 0x3fb8aa3b, v22
	v_sub_f32_e32 v18, v18, v73
	v_mul_f32_e32 v19, 0x3fb8aa3b, v19
	v_add_f32_e32 v10, v68, v10
	v_exp_f32_e32 v24, v22
	v_mul_f32_e32 v18, 0x3fb8aa3b, v18
	v_exp_f32_e32 v25, v19
	v_sub_f32_e32 v19, v20, v73
	v_add_f32_e32 v10, v11, v10
	v_exp_f32_e32 v18, v18
	v_mul_f32_e32 v19, 0x3fb8aa3b, v19
	v_add_f32_e32 v10, v40, v10
	v_exp_f32_e32 v20, v19
	v_sub_f32_e32 v19, v21, v73
	v_add_f32_e32 v10, v23, v10
	v_mul_f32_e32 v19, 0x3fb8aa3b, v19
	v_add_f32_e32 v10, v24, v10
	v_exp_f32_e32 v67, v19
	v_add_f32_e32 v10, v18, v10
	v_add_f32_e32 v10, v25, v10
	v_add_f32_e32 v10, v20, v10
	v_add_f32_e32 v19, v67, v10
	v_sub_f32_e32 v10, v14, v73
	v_mul_f32_e32 v10, 0x3fb8aa3b, v10
	v_sub_f32_e32 v15, v15, v73
	v_exp_f32_e32 v10, v10
	v_mul_f32_e32 v15, 0x3fb8aa3b, v15
	v_exp_f32_e32 v15, v15
	v_sub_f32_e32 v17, v17, v73
	v_add_f32_e32 v14, v10, v19
	v_mul_f32_e32 v17, 0x3fb8aa3b, v17
	v_add_f32_e32 v19, v15, v14
	v_sub_f32_e32 v14, v16, v73
	v_mul_f32_e32 v14, 0x3fb8aa3b, v14
	v_exp_f32_e32 v14, v14
	v_exp_f32_e32 v17, v17
	v_sub_f32_e32 v6, v6, v73
	v_mul_f32_e32 v6, 0x3fb8aa3b, v6
	v_add_f32_e32 v16, v14, v19
	v_add_f32_e32 v19, v17, v16
	v_exp_f32_e32 v16, v6
	v_sub_f32_e32 v7, v7, v73
	v_mul_f32_e32 v7, 0x3fb8aa3b, v7
	v_exp_f32_e32 v21, v7
	v_sub_f32_e32 v7, v8, v73
	v_mul_f32_e32 v7, 0x3fb8aa3b, v7
	v_add_f32_e32 v6, v16, v19
	v_exp_f32_e32 v19, v7
	v_sub_f32_e32 v7, v9, v73
	v_mul_f32_e32 v7, 0x3fb8aa3b, v7
	v_exp_f32_e32 v66, v7
	v_add_f32_e32 v6, v21, v6
	v_add_f32_e32 v6, v19, v6
	v_bfe_u32 v8, v102, 16, 1
	v_add_f32_e32 v6, v66, v6
	ds_bpermute_b32 v7, v109, v6
	v_bfe_u32 v9, v100, 16, 1
	v_add3_u32 v73, v100, v9, s91
	v_add3_u32 v74, v102, v8, s91
	v_bfe_u32 v8, v79, 16, 1
	s_waitcnt lgkmcnt(0)
	v_add_f32_e32 v6, v6, v7
	ds_bpermute_b32 v7, v110, v6
	v_bfe_u32 v9, v101, 16, 1
	v_bfe_u32 v75, v103, 16, 1
	v_bfe_u32 v76, v105, 16, 1
	v_add3_u32 v75, v103, v75, s91
	s_waitcnt lgkmcnt(0)
	v_add_f32_e32 v22, v6, v7
	v_bfe_u32 v7, v104, 16, 1
	v_add3_u32 v9, v101, v9, s91
	v_add3_u32 v8, v79, v8, s91
	v_bfe_u32 v6, v111, 16, 1
	v_add3_u32 v7, v104, v7, s91
	v_add3_u32 v76, v105, v76, s91
	v_lshrrev_b32_e32 v77, 16, v8
	v_lshrrev_b32_e32 v79, 16, v9
	v_lshrrev_b32_e32 v8, 16, v75
	v_add3_u32 v6, v111, v6, s91
	v_lshrrev_b32_e32 v9, 16, v76
	v_and_or_b32 v8, v7, s33, v8
	v_and_or_b32 v7, v74, s33, v79
	v_add_u32_e32 v79, 0x9000, v32
	v_add_u32_e32 v96, 0xb000, v32
	v_add_u32_e32 v97, 0xd000, v32
	v_add_u32_e32 v98, 0xf000, v32
	v_and_or_b32 v9, v6, s33, v9
	v_and_or_b32 v6, v73, s33, v77
	ds_read2_b64 v[74:77], v79 offset1:4
	ds_read2_b64 v[80:83], v96 offset0:32 offset1:36
	ds_read2_b64 v[84:87], v97 offset0:64 offset1:68
	ds_read2_b64 v[88:91], v98 offset0:96 offset1:100
	ds_read2_b64 v[92:95], v79 offset0:8 offset1:12
	s_waitcnt lgkmcnt(4)
	v_mfma_f32_16x16x32_bf16 v[74:77], v[74:77], v[6:9], 0
	v_bfe_u32 v73, v72, 16, 1
	v_add3_u32 v72, v72, v73, s91
	v_bfe_u32 v73, v34, 16, 1
	s_waitcnt lgkmcnt(3)
	v_mfma_f32_16x16x32_bf16 v[80:83], v[80:83], v[6:9], 0
	v_add3_u32 v34, v34, v73, s91
	v_lshrrev_b32_e32 v34, 16, v34
	s_waitcnt lgkmcnt(2)
	v_mfma_f32_16x16x32_bf16 v[84:87], v[84:87], v[6:9], 0
	s_waitcnt lgkmcnt(1)
	v_mfma_f32_16x16x32_bf16 v[6:9], v[88:91], v[6:9], 0
	v_bfe_u32 v88, v65, 16, 1
	v_bfe_u32 v89, v55, 16, 1
	v_bfe_u32 v90, v46, 16, 1
	v_add3_u32 v46, v46, v90, s91
	v_add3_u32 v55, v55, v89, s91
	v_add3_u32 v65, v65, v88, s91
	v_bfe_u32 v88, v39, 16, 1
	v_bfe_u32 v89, v50, 16, 1
	v_bfe_u32 v90, v62, 16, 1
	v_add3_u32 v62, v62, v90, s91
	v_add3_u32 v50, v50, v89, s91
	v_add3_u32 v39, v39, v88, s91
	v_lshrrev_b32_e32 v39, 16, v39
	v_lshrrev_b32_e32 v50, 16, v50
	v_lshrrev_b32_e32 v62, 16, v62
	v_and_or_b32 v91, v72, s33, v62
	v_and_or_b32 v90, v65, s33, v50
	v_and_or_b32 v89, v55, s33, v39
	v_and_or_b32 v88, v46, s33, v34
	v_bfe_u32 v46, v54, 16, 1
	v_bfe_u32 v50, v44, 16, 1
	s_waitcnt lgkmcnt(0)
	v_mfma_f32_16x16x32_bf16 v[72:75], v[92:95], v[88:91], v[74:77]
	ds_read2_b64 v[92:95], v96 offset0:40 offset1:44
	v_add3_u32 v44, v44, v50, s91
	v_add3_u32 v46, v54, v46, s91
	s_waitcnt lgkmcnt(0)
	v_mfma_f32_16x16x32_bf16 v[80:83], v[92:95], v[88:91], v[80:83]
	ds_read2_b64 v[92:95], v97 offset0:72 offset1:76
	v_bfe_u32 v50, v33, 16, 1
	v_bfe_u32 v54, v38, 16, 1
	s_waitcnt lgkmcnt(0)
	v_mfma_f32_16x16x32_bf16 v[84:87], v[92:95], v[88:91], v[84:87]
	ds_read2_b64 v[92:95], v98 offset0:104 offset1:108
	v_bfe_u32 v55, v49, 16, 1
	s_waitcnt lgkmcnt(0)
	v_mfma_f32_16x16x32_bf16 v[6:9], v[92:95], v[88:91], v[6:9]
	ds_read2_b64 v[92:95], v79 offset0:16 offset1:20
	v_bfe_u32 v62, v60, 16, 1
	v_bfe_u32 v34, v71, 16, 1
	v_bfe_u32 v39, v64, 16, 1
	v_add3_u32 v60, v60, v62, s91
	v_add3_u32 v49, v49, v55, s91
	v_add3_u32 v38, v38, v54, s91
	v_add3_u32 v33, v33, v50, s91
	v_add3_u32 v39, v64, v39, s91
	v_add3_u32 v34, v71, v34, s91
	v_lshrrev_b32_e32 v33, 16, v33
	v_lshrrev_b32_e32 v38, 16, v38
	v_lshrrev_b32_e32 v49, 16, v49
	v_lshrrev_b32_e32 v50, 16, v60
	v_and_or_b32 v91, v34, s33, v50
	v_and_or_b32 v90, v39, s33, v49
	v_and_or_b32 v89, v46, s33, v38
	v_and_or_b32 v88, v44, s33, v33
	v_bfe_u32 v39, v43, 16, 1
	v_add3_u32 v39, v43, v39, s91
	s_waitcnt lgkmcnt(0)
	v_mfma_f32_16x16x32_bf16 v[72:75], v[92:95], v[88:91], v[72:75]
	ds_read2_b64 v[92:95], v96 offset0:48 offset1:52
	v_bfe_u32 v43, v27, 16, 1
	v_bfe_u32 v44, v37, 16, 1
	s_waitcnt lgkmcnt(0)
	v_mfma_f32_16x16x32_bf16 v[80:83], v[92:95], v[88:91], v[80:83]
	ds_read2_b64 v[92:95], v97 offset0:80 offset1:84
	v_bfe_u32 v46, v48, 16, 1
	v_bfe_u32 v49, v58, 16, 1
	s_waitcnt lgkmcnt(0)
	v_mfma_f32_16x16x32_bf16 v[84:87], v[92:95], v[88:91], v[84:87]
	ds_read2_b64 v[92:95], v98 offset0:112 offset1:116
	v_bfe_u32 v33, v70, 16, 1
	s_waitcnt lgkmcnt(0)
	v_mfma_f32_16x16x32_bf16 v[6:9], v[92:95], v[88:91], v[6:9]
	ds_read2_b64 v[88:91], v79 offset0:24 offset1:28
	v_bfe_u32 v34, v63, 16, 1
	v_bfe_u32 v38, v53, 16, 1
	v_add3_u32 v49, v58, v49, s91
	v_add3_u32 v46, v48, v46, s91
	v_add3_u32 v37, v37, v44, s91
	v_add3_u32 v27, v27, v43, s91
	v_add3_u32 v38, v53, v38, s91
	v_add3_u32 v34, v63, v34, s91
	v_add3_u32 v33, v70, v33, s91
	v_lshrrev_b32_e32 v27, 16, v27
	v_lshrrev_b32_e32 v37, 16, v37
	v_lshrrev_b32_e32 v43, 16, v46
	v_lshrrev_b32_e32 v44, 16, v49
	v_and_or_b32 v65, v33, s33, v44
	v_and_or_b32 v64, v34, s33, v43
	v_and_or_b32 v63, v38, s33, v37
	v_and_or_b32 v62, v39, s33, v27
	v_bfe_u32 v39, v47, 16, 1
	v_add3_u32 v39, v47, v39, s91
	s_waitcnt lgkmcnt(0)
	v_mfma_f32_16x16x32_bf16 v[70:73], v[88:91], v[62:65], v[72:75]
	v_bfe_u32 v37, v42, 16, 1
	v_add3_u32 v42, v42, v37, s91
	v_bfe_u32 v37, v13, 16, 1
	ds_read2_b64 v[74:77], v96 offset0:56 offset1:60
	s_waitcnt lgkmcnt(0)
	v_mfma_f32_16x16x32_bf16 v[74:77], v[74:77], v[62:65], v[80:83]
	s_nop 2
	ds_read2_b64 v[80:83], v97 offset0:88 offset1:92
	v_bfe_u32 v38, v36, 16, 1
	v_bfe_u32 v43, v57, 16, 1
	s_waitcnt lgkmcnt(0)
	v_mfma_f32_16x16x32_bf16 v[80:83], v[80:83], v[62:65], v[84:87]
	s_nop 2
	ds_read2_b64 v[84:87], v98 offset0:120 offset1:124
	ds_read2_b64 v[46:49], v79 offset0:32 offset1:36
	v_bfe_u32 v27, v69, 16, 1
	v_bfe_u32 v33, v61, 16, 1
	v_bfe_u32 v34, v52, 16, 1
	v_add3_u32 v43, v57, v43, s91
	v_add3_u32 v36, v36, v38, s91
	v_add3_u32 v13, v13, v37, s91
	v_add3_u32 v34, v52, v34, s91
	v_add3_u32 v33, v61, v33, s91
	v_add3_u32 v27, v69, v27, s91
	v_lshrrev_b32_e32 v13, 16, v13
	v_lshrrev_b32_e32 v36, 16, v36
	v_lshrrev_b32_e32 v37, 16, v39
	v_lshrrev_b32_e32 v38, 16, v43
	v_and_or_b32 v39, v27, s33, v38
	v_and_or_b32 v38, v33, s33, v37
	v_and_or_b32 v37, v34, s33, v36
	v_and_or_b32 v36, v42, s33, v13
	s_waitcnt lgkmcnt(1)
	v_mfma_f32_16x16x32_bf16 v[6:9], v[84:87], v[62:65], v[6:9]
	ds_read2_b64 v[52:55], v96 offset0:64 offset1:68
	ds_read2_b64 v[60:63], v97 offset0:96 offset1:100
	v_bfe_u32 v13, v68, 16, 1
	s_waitcnt lgkmcnt(2)
	v_mfma_f32_16x16x32_bf16 v[46:49], v[46:49], v[36:39], v[70:73]
	v_bfe_u32 v27, v59, 16, 1
	v_bfe_u32 v33, v51, 16, 1
	v_bfe_u32 v34, v41, 16, 1
	ds_read2_b64 v[70:73], v98 offset0:128 offset1:132
	s_waitcnt lgkmcnt(2)
	v_mfma_f32_16x16x32_bf16 v[52:55], v[52:55], v[36:39], v[74:77]
	v_add3_u32 v34, v41, v34, s91
	v_add3_u32 v33, v51, v33, s91
	s_waitcnt lgkmcnt(1)
	v_mfma_f32_16x16x32_bf16 v[60:63], v[60:63], v[36:39], v[80:83]
	v_add3_u32 v27, v59, v27, s91
	v_add3_u32 v13, v68, v13, s91
	s_waitcnt lgkmcnt(0)
	v_mfma_f32_16x16x32_bf16 v[6:9], v[70:73], v[36:39], v[6:9]
	v_bfe_u32 v38, v45, 16, 1
	v_add3_u32 v38, v45, v38, s91
	ds_read2_b64 v[42:45], v79 offset0:40 offset1:44
	v_bfe_u32 v36, v12, 16, 1
	v_bfe_u32 v37, v35, 16, 1
	v_bfe_u32 v39, v56, 16, 1
	v_add3_u32 v39, v56, v39, s91
	v_add3_u32 v35, v35, v37, s91
	v_add3_u32 v12, v12, v36, s91
	v_lshrrev_b32_e32 v12, 16, v12
	v_lshrrev_b32_e32 v35, 16, v35
	v_lshrrev_b32_e32 v36, 16, v38
	v_lshrrev_b32_e32 v37, 16, v39
	v_and_or_b32 v37, v13, s33, v37
	v_and_or_b32 v36, v27, s33, v36
	v_and_or_b32 v35, v33, s33, v35
	v_and_or_b32 v34, v34, s33, v12
	v_bfe_u32 v33, v40, 16, 1
	v_add3_u32 v33, v40, v33, s91
	s_waitcnt lgkmcnt(0)
	v_mfma_f32_16x16x32_bf16 v[42:45], v[42:45], v[34:37], v[46:49]
	v_bfe_u32 v13, v25, 16, 1
	v_bfe_u32 v27, v24, 16, 1
	v_add3_u32 v24, v24, v27, s91
	ds_read2_b64 v[46:49], v96 offset0:72 offset1:76
	s_waitcnt lgkmcnt(0)
	v_mfma_f32_16x16x32_bf16 v[46:49], v[46:49], v[34:37], v[52:55]
	s_nop 2
	ds_read2_b64 v[50:53], v97 offset0:104 offset1:108
	ds_read2_b64 v[54:57], v98 offset0:136 offset1:140
	ds_read2_b64 v[38:41], v79 offset0:48 offset1:52
	s_waitcnt lgkmcnt(2)
	v_mfma_f32_16x16x32_bf16 v[50:53], v[50:53], v[34:37], v[60:63]
	v_add3_u32 v13, v25, v13, s91
	v_bfe_u32 v25, v11, 16, 1
	v_bfe_u32 v27, v23, 16, 1
	s_waitcnt lgkmcnt(1)
	v_mfma_f32_16x16x32_bf16 v[6:9], v[54:57], v[34:37], v[6:9]
	v_bfe_u32 v34, v18, 16, 1
	v_bfe_u32 v35, v20, 16, 1
	v_bfe_u32 v12, v67, 16, 1
	v_add3_u32 v20, v20, v35, s91
	v_add3_u32 v18, v18, v34, s91
	v_add3_u32 v23, v23, v27, s91
	v_add3_u32 v11, v11, v25, s91
	v_add3_u32 v12, v67, v12, s91
	v_lshrrev_b32_e32 v11, 16, v11
	v_lshrrev_b32_e32 v23, 16, v23
	v_lshrrev_b32_e32 v18, 16, v18
	v_lshrrev_b32_e32 v20, 16, v20
	v_and_or_b32 v37, v12, s33, v20
	v_and_or_b32 v36, v13, s33, v18
	v_and_or_b32 v35, v24, s33, v23
	v_and_or_b32 v34, v33, s33, v11
	v_bfe_u32 v12, v21, 16, 1
	v_bfe_u32 v13, v17, 16, 1
	s_waitcnt lgkmcnt(0)
	v_mfma_f32_16x16x32_bf16 v[38:41], v[38:41], v[34:37], v[42:45]
	v_bfe_u32 v18, v15, 16, 1
	v_add3_u32 v15, v15, v18, s91
	v_add3_u32 v13, v17, v13, s91
	ds_read2_b64 v[42:45], v96 offset0:80 offset1:84
	s_waitcnt lgkmcnt(0)
	v_mfma_f32_16x16x32_bf16 v[42:45], v[42:45], v[34:37], v[46:49]
	s_nop 2
	ds_read2_b64 v[46:49], v97 offset0:112 offset1:116
	v_add3_u32 v12, v21, v12, s91
	v_bfe_u32 v17, v10, 16, 1
	s_waitcnt lgkmcnt(0)
	v_mfma_f32_16x16x32_bf16 v[46:49], v[46:49], v[34:37], v[50:53]
	s_nop 2
	ds_read2_b64 v[50:53], v98 offset0:144 offset1:148
	v_bfe_u32 v18, v14, 16, 1
	v_bfe_u32 v20, v16, 16, 1
	v_bfe_u32 v21, v19, 16, 1
	v_bfe_u32 v11, v66, 16, 1
	v_add3_u32 v19, v19, v21, s91
	v_add3_u32 v16, v16, v20, s91
	v_add3_u32 v14, v14, v18, s91
	v_add3_u32 v10, v10, v17, s91
	v_add3_u32 v11, v66, v11, s91
	v_lshrrev_b32_e32 v10, 16, v10
	v_lshrrev_b32_e32 v14, 16, v14
	v_lshrrev_b32_e32 v16, 16, v16
	v_lshrrev_b32_e32 v17, 16, v19
	s_waitcnt lgkmcnt(0)
	v_mfma_f32_16x16x32_bf16 v[6:9], v[50:53], v[34:37], v[6:9]
	v_and_or_b32 v37, v11, s33, v17
	v_and_or_b32 v36, v12, s33, v16
	v_and_or_b32 v35, v13, s33, v14
	v_and_or_b32 v34, v15, s33, v10
	ds_read2_b64 v[10:13], v79 offset0:56 offset1:60
	v_div_scale_f32 v23, s[4:5], v22, v22, 1.0
	s_waitcnt lgkmcnt(0)
	v_mfma_f32_16x16x32_bf16 v[18:21], v[10:13], v[34:37], v[38:41]
	ds_read2_b64 v[10:13], v96 offset0:88 offset1:92
	v_rcp_f32_e32 v27, v23
	s_nop 0
	ds_read2_b64 v[38:41], v98 offset0:152 offset1:156
	s_waitcnt lgkmcnt(1)
	v_mfma_f32_16x16x32_bf16 v[14:17], v[10:13], v[34:37], v[42:45]
	ds_read2_b64 v[10:13], v97 offset0:120 offset1:124
	v_lshlrev_b64 v[24:25], 11, v[28:29]
	v_fma_f32 v28, -v23, v27, 1.0
	v_fmac_f32_e32 v27, v28, v27
	v_div_scale_f32 v28, vcc, 1.0, v22, 1.0
	v_mul_f32_e32 v29, v28, v27
	v_fma_f32 v33, -v23, v29, v28
	v_fmac_f32_e32 v29, v33, v27
	v_fma_f32 v23, -v23, v29, v28
	v_div_fmas_f32 v23, v23, v27, v29
	s_waitcnt lgkmcnt(0)
	v_mfma_f32_16x16x32_bf16 v[10:13], v[10:13], v[34:37], v[46:49]
	v_div_fixup_f32 v22, v23, v22, 1.0
	v_lshl_add_u64 v[24:25], s[0:1], 0, v[24:25]
	v_lshl_add_u64 v[24:25], v[24:25], 0, s[94:95]
	v_mfma_f32_16x16x32_bf16 v[6:9], v[38:41], v[34:37], v[6:9]
	v_mov_b32_e32 v35, v20
	v_mov_b32_e32 v20, v19
	v_mov_b32_e32 v34, v18
	v_pk_mul_f32 v[18:19], v[22:23], v[20:21] op_sel_hi:[0,1]
	v_mov_b32_e32 v27, v1
	v_pk_mul_f32 v[34:35], v[22:23], v[34:35] op_sel_hi:[0,1]
	v_and_b32_sdwa v23, v19, v218 dst_sel:DWORD dst_unused:UNUSED_PAD src0_sel:WORD_1 src1_sel:DWORD
	v_lshl_add_u64 v[24:25], v[24:25], 0, v[26:27]
	v_and_b32_sdwa v20, v35, v218 dst_sel:DWORD dst_unused:UNUSED_PAD src0_sel:WORD_1 src1_sel:DWORD
	v_and_b32_sdwa v27, v18, v218 dst_sel:DWORD dst_unused:UNUSED_PAD src0_sel:WORD_1 src1_sel:DWORD
	v_add3_u32 v19, v19, v23, s91
	v_and_b32_sdwa v21, v34, v218 dst_sel:DWORD dst_unused:UNUSED_PAD src0_sel:WORD_1 src1_sel:DWORD
	v_add3_u32 v20, v35, v20, s91
	v_add3_u32 v18, v18, v27, s91
	v_and_b32_e32 v19, 0xffff0000, v19
	v_add3_u32 v21, v34, v21, s91
	v_and_b32_e32 v18, 0xffff0000, v18
	v_or_b32_sdwa v19, v19, v20 dst_sel:DWORD dst_unused:UNUSED_PAD src0_sel:DWORD src1_sel:WORD_1
	v_add_co_u32_e32 v20, vcc, s8, v24
	v_or_b32_sdwa v18, v18, v21 dst_sel:DWORD dst_unused:UNUSED_PAD src0_sel:DWORD src1_sel:WORD_1
	s_nop 0
	v_addc_co_u32_e32 v21, vcc, 0, v25, vcc
	flat_store_dwordx2 v[20:21], v[18:19] offset:1536
	v_mov_b32_e32 v18, v14
	v_mov_b32_e32 v19, v16
	v_pk_mul_f32 v[18:19], v[22:23], v[18:19] op_sel_hi:[0,1]
	v_mov_b32_e32 v16, v15
	v_pk_mul_f32 v[14:15], v[22:23], v[16:17] op_sel_hi:[0,1]
	v_and_b32_sdwa v16, v19, v218 dst_sel:DWORD dst_unused:UNUSED_PAD src0_sel:WORD_1 src1_sel:DWORD
	v_and_b32_sdwa v17, v18, v218 dst_sel:DWORD dst_unused:UNUSED_PAD src0_sel:WORD_1 src1_sel:DWORD
	v_add3_u32 v17, v18, v17, s91
	v_add3_u32 v16, v19, v16, s91
	v_and_b32_sdwa v18, v15, v218 dst_sel:DWORD dst_unused:UNUSED_PAD src0_sel:WORD_1 src1_sel:DWORD
	v_and_b32_sdwa v19, v14, v218 dst_sel:DWORD dst_unused:UNUSED_PAD src0_sel:WORD_1 src1_sel:DWORD
	v_add3_u32 v15, v15, v18, s91
	v_add3_u32 v14, v14, v19, s91
	v_and_b32_e32 v15, 0xffff0000, v15
	v_and_b32_e32 v14, 0xffff0000, v14
	v_lshl_add_u64 v[28:29], v[24:25], 0, s[10:11]
	v_or_b32_sdwa v15, v15, v16 dst_sel:DWORD dst_unused:UNUSED_PAD src0_sel:DWORD src1_sel:WORD_1
	v_or_b32_sdwa v14, v14, v17 dst_sel:DWORD dst_unused:UNUSED_PAD src0_sel:DWORD src1_sel:WORD_1
	flat_store_dwordx2 v[28:29], v[14:15] offset:32
	v_mov_b32_e32 v14, v10
	v_mov_b32_e32 v15, v12
	v_pk_mul_f32 v[14:15], v[22:23], v[14:15] op_sel_hi:[0,1]
	v_mov_b32_e32 v12, v11
	v_pk_mul_f32 v[10:11], v[22:23], v[12:13] op_sel_hi:[0,1]
	v_and_b32_sdwa v12, v15, v218 dst_sel:DWORD dst_unused:UNUSED_PAD src0_sel:WORD_1 src1_sel:DWORD
	v_and_b32_sdwa v13, v14, v218 dst_sel:DWORD dst_unused:UNUSED_PAD src0_sel:WORD_1 src1_sel:DWORD
	v_add3_u32 v13, v14, v13, s91
	v_add3_u32 v12, v15, v12, s91
	v_and_b32_sdwa v14, v11, v218 dst_sel:DWORD dst_unused:UNUSED_PAD src0_sel:WORD_1 src1_sel:DWORD
	v_and_b32_sdwa v15, v10, v218 dst_sel:DWORD dst_unused:UNUSED_PAD src0_sel:WORD_1 src1_sel:DWORD
	v_add3_u32 v11, v11, v14, s91
	v_add3_u32 v10, v10, v15, s91
	v_and_b32_e32 v11, 0xffff0000, v11
	v_and_b32_e32 v10, 0xffff0000, v10
	v_or_b32_sdwa v11, v11, v12 dst_sel:DWORD dst_unused:UNUSED_PAD src0_sel:DWORD src1_sel:WORD_1
	v_or_b32_sdwa v10, v10, v13 dst_sel:DWORD dst_unused:UNUSED_PAD src0_sel:DWORD src1_sel:WORD_1
	flat_store_dwordx2 v[28:29], v[10:11] offset:64
	v_mov_b32_e32 v10, v6
	v_mov_b32_e32 v11, v8
	v_pk_mul_f32 v[10:11], v[22:23], v[10:11] op_sel_hi:[0,1]
	v_mov_b32_e32 v8, v7
	v_pk_mul_f32 v[6:7], v[22:23], v[8:9] op_sel_hi:[0,1]
	v_and_b32_sdwa v8, v11, v218 dst_sel:DWORD dst_unused:UNUSED_PAD src0_sel:WORD_1 src1_sel:DWORD
	v_and_b32_sdwa v9, v10, v218 dst_sel:DWORD dst_unused:UNUSED_PAD src0_sel:WORD_1 src1_sel:DWORD
	v_add3_u32 v9, v10, v9, s91
	v_add3_u32 v8, v11, v8, s91
	v_and_b32_sdwa v10, v7, v218 dst_sel:DWORD dst_unused:UNUSED_PAD src0_sel:WORD_1 src1_sel:DWORD
	v_and_b32_sdwa v11, v6, v218 dst_sel:DWORD dst_unused:UNUSED_PAD src0_sel:WORD_1 src1_sel:DWORD
	v_add3_u32 v7, v7, v10, s91
	v_add3_u32 v6, v6, v11, s91
	v_and_b32_e32 v7, 0xffff0000, v7
	v_and_b32_e32 v6, 0xffff0000, v6
	v_or_b32_sdwa v7, v7, v8 dst_sel:DWORD dst_unused:UNUSED_PAD src0_sel:DWORD src1_sel:WORD_1
	v_or_b32_sdwa v6, v6, v9 dst_sel:DWORD dst_unused:UNUSED_PAD src0_sel:DWORD src1_sel:WORD_1
	s_movk_i32 s4, 0x80
	s_and_b64 vcc, exec, s[2:3]
	s_mov_b64 s[2:3], 0
	flat_store_dwordx2 v[28:29], v[6:7] offset:96
	s_cbranch_vccnz .LBB0_459
	s_waitcnt lgkmcnt(0)
	s_barrier

.LBB0_465:
	s_or_b64 exec, exec, s[4:5]
	v_pk_mul_f32 v[56:57], v[50:51], v[50:51]
	v_pk_mul_f32 v[60:61], v[52:53], v[52:53]
	v_pk_fma_f32 v[56:57], v[46:47], v[46:47], v[56:57]
	v_pk_fma_f32 v[60:61], v[48:49], v[48:49], v[60:61]
	v_add_f32_e32 v0, v57, v56
	v_pk_mul_f32 v[62:63], v[58:59], v[58:59]
	v_add_f32_e32 v0, v60, v0
	v_pk_fma_f32 v[62:63], v[64:65], v[64:65], v[62:63]
	v_add_f32_e32 v0, v61, v0
	v_pk_mul_f32 v[66:67], v[72:73], v[72:73]
	v_add_f32_e32 v0, v62, v0
	v_pk_fma_f32 v[66:67], v[70:71], v[70:71], v[66:67]
	v_add_f32_e32 v0, v63, v0
	v_add_f32_e32 v0, v66, v0
	v_add_f32_e32 v0, v67, v0
	ds_bpermute_b32 v55, v5, v0
	s_cmp_eq_u32 s13, 31
	v_readlane_b32 s6, v254, 49
	s_cselect_b64 s[4:5], -1, 0
	v_readlane_b32 s7, v254, 50
	s_waitcnt lgkmcnt(0)
	v_add_f32_e32 v0, v0, v55
	ds_bpermute_b32 v55, v106, v0
	s_and_b64 s[6:7], s[6:7], s[4:5]
	v_max_i32_e32 v54, 0, v54
	s_nop 1
	v_lshl_or_b32 v191, v54, 5, v3
	v_or_b32_e32 v196, 4, v191
	v_ashrrev_i32_e32 v197, 31, v196
	v_lshlrev_b64 v[196:197], 2, v[196:197]
	v_lshl_add_u64 v[200:201], s[10:11], 0, v[196:197]
	global_load_dwordx4 v[202:205], v[200:201], off
	s_nop 1
	v_lshl_or_b32 v190, v54, 5, v3
	v_or_b32_e32 v186, 4, v190
	v_ashrrev_i32_e32 v187, 31, v186
	v_lshlrev_b64 v[186:187], 2, v[186:187]
	v_lshl_add_u64 v[188:189], s[8:9], 0, v[186:187]
	global_load_dwordx4 v[192:195], v[188:189], off
	s_nop 1
	v_lshl_or_b32 v162, v54, 5, v3
	v_ashrrev_i32_e32 v163, 31, v162
	v_lshlrev_b64 v[158:159], 2, v[162:163]
	v_lshl_add_u64 v[160:161], s[8:9], 0, v[158:159]
	global_load_dwordx4 v[164:167], v[160:161], off
	s_nop 1
	v_lshl_or_b32 v150, v54, 5, v3
	v_ashrrev_i32_e32 v151, 31, v150
	v_lshlrev_b64 v[148:149], 2, v[150:151]
	v_lshl_add_u64 v[152:153], s[10:11], 0, v[148:149]
	global_load_dwordx4 v[154:157], v[152:153], off
	v_lshl_or_b32 v76, v54, 5, v3
	v_ashrrev_i32_e32 v77, 31, v76
	s_waitcnt lgkmcnt(0)
	v_add_f32_e32 v0, v0, v55
	v_fmamk_f32 v0, v0, 0x3c800000, v219
	v_cmp_gt_f32_e32 vcc, s85, v0
	v_mul_f32_e32 v55, 0x4f800000, v0
	s_and_b32 s20, s20, 0xffffff80
	v_cndmask_b32_e32 v0, v0, v55, vcc
	v_sqrt_f32_e32 v55, v0
	s_addk_i32 s20, 0xff80
	v_add_u32_e32 v56, -1, v55
	v_fma_f32 v57, -v56, v55, v0
	v_cmp_ge_f32_e64 s[4:5], 0, v57
	v_add_u32_e32 v57, 1, v55
	s_nop 0
	v_cndmask_b32_e64 v56, v55, v56, s[4:5]
	v_fma_f32 v55, -v57, v55, v0
	v_cmp_lt_f32_e64 s[4:5], 0, v55
	s_nop 1
	v_cndmask_b32_e64 v55, v56, v57, s[4:5]
	v_mul_f32_e32 v56, 0x37800000, v55
	v_cndmask_b32_e32 v55, v55, v56, vcc
	v_cmp_class_f32_e32 vcc, v0, v221
	s_nop 1
	v_cndmask_b32_e32 v0, v55, v0, vcc
	v_div_scale_f32 v55, s[4:5], v0, v0, 1.0
	v_rcp_f32_e32 v56, v55
	v_readlane_b32 s4, v254, 15
	v_fma_f32 v57, -v55, v56, 1.0
	v_fmac_f32_e32 v56, v57, v56
	v_div_scale_f32 v57, vcc, 1.0, v0, 1.0
	v_mul_f32_e32 v60, v57, v56
	v_fma_f32 v61, -v55, v60, v57
	v_fmac_f32_e32 v60, v61, v56
	v_fma_f32 v55, -v55, v60, v57
	v_div_fmas_f32 v55, v55, v56, v60
	v_div_fixup_f32 v74, v55, v0, 1.0
	v_mov_b32_e32 v0, s4
	ds_read_b64 v[56:57], v0
	v_lshlrev_b32_e32 v0, 2, v3
	v_lshlrev_b64 v[54:55], 2, v[76:77]
	v_lshl_add_u64 v[80:81], s[10:11], 0, v[54:55]
	s_waitcnt vmcnt(0)
	s_nop 0
	v_mov_b32_e32 v84, v154
	v_mov_b32_e32 v85, v155
	v_mov_b32_e32 v86, v156
	v_mov_b32_e32 v87, v157
	s_nop 1
	s_waitcnt lgkmcnt(0)
	v_readfirstlane_b32 s4, v56
	v_readfirstlane_b32 s5, v57
	s_nop 1
	v_lshl_add_u64 v[206:207], s[4:5], 0, v[0:1]
	global_load_dwordx4 v[208:211], v[206:207], off offset:16
	s_nop 1
	v_lshl_add_u64 v[180:181], s[4:5], 0, v[0:1]
	global_load_dwordx4 v[182:185], v[180:181], off offset:144
	s_nop 1
	v_lshl_add_u64 v[174:175], s[4:5], 0, v[0:1]
	global_load_dwordx4 v[176:179], v[174:175], off
	s_nop 1
	v_lshl_add_u64 v[168:169], s[4:5], 0, v[0:1]
	global_load_dwordx4 v[170:173], v[168:169], off offset:128
	v_lshl_add_u64 v[56:57], s[8:9], 0, v[54:55]
	s_waitcnt vmcnt(0)
	s_nop 0
	v_mov_b32_e32 v54, v164
	v_mov_b32_e32 v55, v165
	v_mov_b32_e32 v56, v166
	v_mov_b32_e32 v57, v167
	s_nop 1
	v_lshl_add_u64 v[66:67], s[4:5], 0, v[0:1]
	s_waitcnt vmcnt(0)
	s_nop 0
	v_mov_b32_e32 v60, v170
	v_mov_b32_e32 v61, v171
	v_mov_b32_e32 v62, v172
	v_mov_b32_e32 v63, v173
	s_nop 1
	s_waitcnt vmcnt(0)
	s_nop 0
	v_mov_b32_e32 v88, v176
	v_mov_b32_e32 v89, v177
	v_mov_b32_e32 v90, v178
	v_mov_b32_e32 v91, v179
	s_nop 1
	v_pk_mul_f32 v[50:51], v[50:51], v[74:75] op_sel_hi:[1,0]
	v_pk_mul_f32 v[46:47], v[46:47], v[74:75] op_sel_hi:[1,0]
	v_pk_mul_f32 v[52:53], v[52:53], v[74:75] op_sel_hi:[1,0]
	v_pk_mul_f32 v[48:49], v[48:49], v[74:75] op_sel_hi:[1,0]
	v_pk_mul_f32 v[58:59], v[58:59], v[74:75] op_sel_hi:[1,0]
	s_movk_i32 s4, 0x7f
	v_cmp_lt_i32_e32 vcc, s4, v82
	s_and_b64 s[22:23], s[6:7], vcc
	s_waitcnt vmcnt(0) lgkmcnt(0)
	v_pk_mul_f32 v[60:61], v[60:61], v[50:51]
	v_pk_mul_f32 v[46:47], v[88:89], v[46:47]
	v_pk_mul_f32 v[50:51], v[84:85], v[60:61]
	v_pk_mul_f32 v[48:49], v[48:49], v[90:91]
	v_pk_fma_f32 v[50:51], v[54:55], v[46:47], v[50:51] neg_lo:[0,0,1] neg_hi:[0,0,1]
	v_pk_mul_f32 v[54:55], v[54:55], v[60:61]
	v_bfe_u32 v69, v50, 16, 1
	v_pk_fma_f32 v[46:47], v[84:85], v[46:47], v[54:55]
	v_pk_mul_f32 v[54:55], v[52:53], v[62:63]
	s_waitcnt vmcnt(0)
	s_nop 0
	v_mov_b32_e32 v60, v182
	v_mov_b32_e32 v61, v183
	v_mov_b32_e32 v62, v184
	v_mov_b32_e32 v63, v185
	s_nop 1
	v_pk_mul_f32 v[52:53], v[86:87], v[54:55]
	v_pk_mul_f32 v[54:55], v[56:57], v[54:55]
	v_pk_fma_f32 v[52:53], v[56:57], v[48:49], v[52:53] neg_lo:[0,0,1] neg_hi:[0,0,1]
	v_pk_fma_f32 v[48:49], v[86:87], v[48:49], v[54:55]
	v_or_b32_e32 v54, 4, v76
	v_ashrrev_i32_e32 v55, 31, v54
	v_lshlrev_b64 v[54:55], 2, v[54:55]
	v_lshl_add_u64 v[80:81], s[10:11], 0, v[54:55]
	v_lshl_add_u64 v[56:57], s[8:9], 0, v[54:55]
	s_waitcnt vmcnt(0)
	s_nop 0
	v_mov_b32_e32 v54, v192
	v_mov_b32_e32 v55, v193
	v_mov_b32_e32 v56, v194
	v_mov_b32_e32 v57, v195
	s_nop 1
	v_add3_u32 v69, v50, v69, s91
	v_lshrrev_b32_e32 v69, 16, v69
	s_waitcnt vmcnt(0) lgkmcnt(0)
	v_pk_mul_f32 v[76:77], v[58:59], v[60:61]
	s_waitcnt vmcnt(0)
	s_nop 0
	v_mov_b32_e32 v58, v202
	v_mov_b32_e32 v59, v203
	v_mov_b32_e32 v60, v204
	v_mov_b32_e32 v61, v205
	s_nop 1
	v_pk_mul_f32 v[80:81], v[64:65], v[74:75] op_sel_hi:[1,0]
	s_waitcnt vmcnt(0)
	s_nop 0
	v_mov_b32_e32 v64, v208
	v_mov_b32_e32 v65, v209
	v_mov_b32_e32 v66, v210
	v_mov_b32_e32 v67, v211
	s_nop 1
	s_waitcnt vmcnt(0) lgkmcnt(0)
	v_pk_mul_f32 v[80:81], v[80:81], v[64:65]
	v_pk_mul_f32 v[64:65], v[58:59], v[76:77]
	s_nop 0
	v_pk_fma_f32 v[64:65], v[54:55], v[80:81], v[64:65] neg_lo:[0,0,1] neg_hi:[0,0,1]
	v_pk_mul_f32 v[54:55], v[54:55], v[76:77]
	s_nop 0
	v_pk_fma_f32 v[54:55], v[58:59], v[80:81], v[54:55]
	v_pk_mul_f32 v[58:59], v[72:73], v[74:75] op_sel_hi:[1,0]
	s_nop 0
	v_pk_mul_f32 v[58:59], v[58:59], v[62:63]
	v_pk_mul_f32 v[62:63], v[70:71], v[74:75] op_sel_hi:[1,0]
	v_bfe_u32 v70, v64, 16, 1
	v_pk_mul_f32 v[62:63], v[62:63], v[66:67]
	v_pk_mul_f32 v[66:67], v[60:61], v[58:59]
	v_add3_u32 v70, v64, v70, s91
	v_pk_fma_f32 v[66:67], v[56:57], v[62:63], v[66:67] neg_lo:[0,0,1] neg_hi:[0,0,1]
	v_pk_mul_f32 v[56:57], v[56:57], v[58:59]
	v_bfe_u32 v58, v65, 16, 1
	v_pk_fma_f32 v[56:57], v[60:61], v[62:63], v[56:57]
	v_bfe_u32 v60, v67, 16, 1
	v_bfe_u32 v61, v53, 16, 1
	v_add3_u32 v62, v53, v61, s91
	v_add3_u32 v61, v67, v60, s91
	v_bfe_u32 v60, v52, 16, 1
	v_bfe_u32 v59, v51, 16, 1
	v_bfe_u32 v63, v66, 16, 1
	v_add3_u32 v60, v52, v60, s91
	v_add3_u32 v59, v51, v59, s91
	v_add3_u32 v58, v65, v58, s91
	v_add3_u32 v63, v66, v63, s91
	v_lshrrev_b32_e32 v71, 16, v60
	v_lshrrev_b32_e32 v60, 16, v70
	v_lshrrev_b32_e32 v63, 16, v63
	v_and_or_b32 v60, v58, s33, v60
	v_and_or_b32 v58, v59, s33, v69
	v_and_or_b32 v59, v62, s33, v71
	v_mul_lo_u32 v62, v82, s88
	v_and_or_b32 v61, v61, s33, v63
	v_add3_u32 v62, 0, v62, v68
	ds_write_b128 v62, v[58:61]
	v_bfe_u32 v60, v57, 16, 1
	v_bfe_u32 v61, v49, 16, 1
	v_add3_u32 v63, v49, v61, s91
	v_add3_u32 v61, v57, v60, s91
	v_bfe_u32 v60, v48, 16, 1
	v_bfe_u32 v69, v56, 16, 1
	v_bfe_u32 v70, v46, 16, 1
	v_bfe_u32 v71, v54, 16, 1
	v_bfe_u32 v58, v55, 16, 1
	v_bfe_u32 v59, v47, 16, 1
	v_add3_u32 v71, v54, v71, s91
	v_add3_u32 v70, v46, v70, s91
	v_add3_u32 v69, v56, v69, s91
	v_add3_u32 v60, v48, v60, s91
	v_add3_u32 v59, v47, v59, s91
	v_add3_u32 v58, v55, v58, s91
	v_lshrrev_b32_e32 v72, 16, v60
	v_lshrrev_b32_e32 v69, 16, v69
	v_lshrrev_b32_e32 v70, 16, v70
	v_lshrrev_b32_e32 v60, 16, v71
	v_and_or_b32 v60, v58, s33, v60
	v_and_or_b32 v58, v59, s33, v70
	v_and_or_b32 v61, v61, s33, v69
	v_and_or_b32 v59, v63, s33, v72
	ds_write_b128 v62, v[58:61] offset:64
	s_and_saveexec_b64 s[4:5], s[22:23]
	s_cbranch_execz .LBB0_467
	v_readlane_b32 s21, v254, 8
	s_lshl_b32 s94, s15, 2
	s_nop 0
	v_mov_b32_e32 v58, s21
	ds_read_b64 v[58:59], v58
	s_mov_b32 s21, 0x4158000
	s_waitcnt lgkmcnt(0)
	v_readfirstlane_b32 s22, v58
	v_add_u32_e32 v58, s20, v82
	v_readfirstlane_b32 s23, v59
	v_ashrrev_i32_e32 v59, 31, v58
	v_lshlrev_b64 v[58:59], 10, v[58:59]
	v_lshl_add_u64 v[58:59], s[22:23], 0, v[58:59]
	v_lshl_add_u64 v[58:59], v[58:59], 0, s[94:95]
	v_lshl_add_u64 v[58:59], v[58:59], 0, v[0:1]
	s_mov_b64 s[22:23], 0x4158000
	v_lshl_add_u64 v[60:61], v[58:59], 0, s[22:23]
	v_add_co_u32_e32 v58, vcc, s21, v58
	s_nop 1
	v_addc_co_u32_e32 v59, vcc, 0, v59, vcc
	flat_store_dwordx4 v[58:59], v[50:53]
	flat_store_dwordx4 v[60:61], v[64:67] offset:16
	flat_store_dwordx4 v[60:61], v[46:49] offset:128
	flat_store_dwordx4 v[60:61], v[54:57] offset:144

.LBB0_469:
	s_or_b64 exec, exec, s[4:5]
	v_pk_mul_f32 v[56:57], v[50:51], v[50:51]
	v_pk_mul_f32 v[60:61], v[52:53], v[52:53]
	v_pk_fma_f32 v[56:57], v[46:47], v[46:47], v[56:57]
	v_pk_fma_f32 v[60:61], v[48:49], v[48:49], v[60:61]
	v_add_f32_e32 v55, v57, v56
	v_pk_mul_f32 v[62:63], v[58:59], v[58:59]
	v_add_f32_e32 v55, v60, v55
	v_pk_fma_f32 v[62:63], v[64:65], v[64:65], v[62:63]
	v_add_f32_e32 v55, v61, v55
	v_pk_mul_f32 v[66:67], v[72:73], v[72:73]
	v_add_f32_e32 v55, v62, v55
	v_pk_fma_f32 v[66:67], v[70:71], v[70:71], v[66:67]
	v_add_f32_e32 v55, v63, v55
	v_add_f32_e32 v55, v66, v55
	v_add_f32_e32 v55, v67, v55
	ds_bpermute_b32 v56, v5, v55
	v_max_i32_e32 v54, 0, v54
	s_nop 1
	v_lshl_or_b32 v191, v54, 5, v3
	v_or_b32_e32 v196, 4, v191
	v_ashrrev_i32_e32 v197, 31, v196
	v_lshlrev_b64 v[196:197], 2, v[196:197]
	v_lshl_add_u64 v[200:201], s[10:11], 0, v[196:197]
	global_load_dwordx4 v[202:205], v[200:201], off
	s_nop 1
	v_lshl_or_b32 v190, v54, 5, v3
	v_or_b32_e32 v186, 4, v190
	v_ashrrev_i32_e32 v187, 31, v186
	v_lshlrev_b64 v[186:187], 2, v[186:187]
	v_lshl_add_u64 v[188:189], s[8:9], 0, v[186:187]
	global_load_dwordx4 v[192:195], v[188:189], off
	s_nop 1
	v_lshl_or_b32 v162, v54, 5, v3
	v_ashrrev_i32_e32 v163, 31, v162
	v_lshlrev_b64 v[158:159], 2, v[162:163]
	v_lshl_add_u64 v[160:161], s[8:9], 0, v[158:159]
	global_load_dwordx4 v[164:167], v[160:161], off
	s_nop 1
	v_lshl_or_b32 v150, v54, 5, v3
	v_ashrrev_i32_e32 v151, 31, v150
	v_lshlrev_b64 v[148:149], 2, v[150:151]
	v_lshl_add_u64 v[152:153], s[10:11], 0, v[148:149]
	global_load_dwordx4 v[154:157], v[152:153], off
	v_lshl_or_b32 v76, v54, 5, v3
	v_ashrrev_i32_e32 v77, 31, v76
	s_waitcnt lgkmcnt(0)
	v_add_f32_e32 v55, v55, v56
	ds_bpermute_b32 v56, v106, v55
	s_waitcnt lgkmcnt(0)
	v_add_f32_e32 v55, v55, v56
	v_fmamk_f32 v55, v55, 0x3c800000, v219
	v_cmp_gt_f32_e32 vcc, s85, v55
	v_mul_f32_e32 v56, 0x4f800000, v55
	s_nop 0
	v_cndmask_b32_e32 v55, v55, v56, vcc
	v_sqrt_f32_e32 v56, v55
	s_nop 0
	v_add_u32_e32 v57, -1, v56
	v_fma_f32 v60, -v57, v56, v55
	v_cmp_ge_f32_e64 s[4:5], 0, v60
	v_add_u32_e32 v60, 1, v56
	s_nop 0
	v_cndmask_b32_e64 v57, v56, v57, s[4:5]
	v_fma_f32 v56, -v60, v56, v55
	v_cmp_lt_f32_e64 s[4:5], 0, v56
	s_nop 1
	v_cndmask_b32_e64 v56, v57, v60, s[4:5]
	v_mul_f32_e32 v57, 0x37800000, v56
	v_cndmask_b32_e32 v56, v56, v57, vcc
	v_cmp_class_f32_e32 vcc, v55, v221
	s_nop 1
	v_cndmask_b32_e32 v55, v56, v55, vcc
	v_div_scale_f32 v56, s[4:5], v55, v55, 1.0
	v_rcp_f32_e32 v57, v56
	v_readlane_b32 s4, v254, 15
	v_fma_f32 v60, -v56, v57, 1.0
	v_fmac_f32_e32 v57, v60, v57
	v_div_scale_f32 v60, vcc, 1.0, v55, 1.0
	v_mul_f32_e32 v61, v60, v57
	v_fma_f32 v62, -v56, v61, v60
	v_fmac_f32_e32 v61, v62, v57
	v_fma_f32 v56, -v56, v61, v60
	v_div_fmas_f32 v56, v56, v57, v61
	v_div_fixup_f32 v74, v56, v55, 1.0
	v_mov_b32_e32 v55, s4
	ds_read_b64 v[56:57], v55
	v_lshlrev_b64 v[54:55], 2, v[76:77]
	v_lshl_add_u64 v[80:81], s[10:11], 0, v[54:55]
	s_waitcnt vmcnt(0)
	s_nop 0
	v_mov_b32_e32 v84, v154
	v_mov_b32_e32 v85, v155
	v_mov_b32_e32 v86, v156
	v_mov_b32_e32 v87, v157
	s_nop 1
	v_pk_mul_f32 v[50:51], v[50:51], v[74:75] op_sel_hi:[1,0]
	s_waitcnt lgkmcnt(0)
	v_readfirstlane_b32 s4, v56
	v_readfirstlane_b32 s5, v57
	s_nop 1
	v_lshl_add_u64 v[206:207], s[4:5], 0, v[0:1]
	global_load_dwordx4 v[208:211], v[206:207], off offset:16
	s_nop 1
	v_lshl_add_u64 v[180:181], s[4:5], 0, v[0:1]
	global_load_dwordx4 v[182:185], v[180:181], off offset:144
	s_nop 1
	v_lshl_add_u64 v[174:175], s[4:5], 0, v[0:1]
	global_load_dwordx4 v[176:179], v[174:175], off
	s_nop 1
	v_lshl_add_u64 v[168:169], s[4:5], 0, v[0:1]
	global_load_dwordx4 v[170:173], v[168:169], off offset:128
	v_lshl_add_u64 v[56:57], s[8:9], 0, v[54:55]
	s_waitcnt vmcnt(0)
	s_nop 0
	v_mov_b32_e32 v54, v164
	v_mov_b32_e32 v55, v165
	v_mov_b32_e32 v56, v166
	v_mov_b32_e32 v57, v167
	s_nop 1
	v_lshl_add_u64 v[66:67], s[4:5], 0, v[0:1]
	s_waitcnt vmcnt(0)
	s_nop 0
	v_mov_b32_e32 v60, v170
	v_mov_b32_e32 v61, v171
	v_mov_b32_e32 v62, v172
	v_mov_b32_e32 v63, v173
	s_nop 1
	s_waitcnt vmcnt(0)
	s_nop 0
	v_mov_b32_e32 v88, v176
	v_mov_b32_e32 v89, v177
	v_mov_b32_e32 v90, v178
	v_mov_b32_e32 v91, v179
	s_nop 1
	v_pk_mul_f32 v[46:47], v[46:47], v[74:75] op_sel_hi:[1,0]
	v_pk_mul_f32 v[52:53], v[52:53], v[74:75] op_sel_hi:[1,0]
	v_pk_mul_f32 v[48:49], v[48:49], v[74:75] op_sel_hi:[1,0]
	v_pk_mul_f32 v[58:59], v[58:59], v[74:75] op_sel_hi:[1,0]
	s_movk_i32 s4, 0x7f
	v_cmp_lt_i32_e32 vcc, s4, v82
	s_waitcnt vmcnt(0) lgkmcnt(0)
	v_pk_mul_f32 v[60:61], v[60:61], v[50:51]
	v_pk_mul_f32 v[46:47], v[88:89], v[46:47]
	v_pk_mul_f32 v[50:51], v[84:85], v[60:61]
	v_pk_mul_f32 v[48:49], v[48:49], v[90:91]
	v_pk_fma_f32 v[50:51], v[54:55], v[46:47], v[50:51] neg_lo:[0,0,1] neg_hi:[0,0,1]
	v_pk_mul_f32 v[54:55], v[54:55], v[60:61]
	s_nop 0
	v_pk_fma_f32 v[46:47], v[84:85], v[46:47], v[54:55]
	v_pk_mul_f32 v[54:55], v[52:53], v[62:63]
	s_waitcnt vmcnt(0)
	s_nop 0
	v_mov_b32_e32 v60, v182
	v_mov_b32_e32 v61, v183
	v_mov_b32_e32 v62, v184
	v_mov_b32_e32 v63, v185
	s_nop 1
	v_pk_mul_f32 v[52:53], v[86:87], v[54:55]
	v_pk_mul_f32 v[54:55], v[56:57], v[54:55]
	v_pk_fma_f32 v[52:53], v[56:57], v[48:49], v[52:53] neg_lo:[0,0,1] neg_hi:[0,0,1]
	v_pk_fma_f32 v[48:49], v[86:87], v[48:49], v[54:55]
	v_or_b32_e32 v54, 4, v76
	v_ashrrev_i32_e32 v55, 31, v54
	v_lshlrev_b64 v[54:55], 2, v[54:55]
	v_lshl_add_u64 v[80:81], s[10:11], 0, v[54:55]
	v_lshl_add_u64 v[56:57], s[8:9], 0, v[54:55]
	s_waitcnt vmcnt(0)
	s_nop 0
	v_mov_b32_e32 v54, v192
	v_mov_b32_e32 v55, v193
	v_mov_b32_e32 v56, v194
	v_mov_b32_e32 v57, v195
	s_nop 1
	s_and_b64 s[8:9], s[6:7], vcc
	s_waitcnt vmcnt(0) lgkmcnt(0)
	v_pk_mul_f32 v[76:77], v[58:59], v[60:61]
	s_waitcnt vmcnt(0)
	s_nop 0
	v_mov_b32_e32 v58, v202
	v_mov_b32_e32 v59, v203
	v_mov_b32_e32 v60, v204
	v_mov_b32_e32 v61, v205
	s_nop 1
	v_pk_mul_f32 v[80:81], v[64:65], v[74:75] op_sel_hi:[1,0]
	s_waitcnt vmcnt(0)
	s_nop 0
	v_mov_b32_e32 v64, v208
	v_mov_b32_e32 v65, v209
	v_mov_b32_e32 v66, v210
	v_mov_b32_e32 v67, v211
	s_nop 1
	s_waitcnt vmcnt(0) lgkmcnt(0)
	v_pk_mul_f32 v[80:81], v[80:81], v[64:65]
	v_pk_mul_f32 v[64:65], v[58:59], v[76:77]
	s_nop 0
	v_pk_fma_f32 v[64:65], v[54:55], v[80:81], v[64:65] neg_lo:[0,0,1] neg_hi:[0,0,1]
	v_pk_mul_f32 v[54:55], v[54:55], v[76:77]
	v_bfe_u32 v69, v64, 16, 1
	v_pk_fma_f32 v[54:55], v[58:59], v[80:81], v[54:55]
	v_pk_mul_f32 v[58:59], v[72:73], v[74:75] op_sel_hi:[1,0]
	v_bfe_u32 v3, v65, 16, 1
	v_pk_mul_f32 v[58:59], v[58:59], v[62:63]
	v_pk_mul_f32 v[62:63], v[70:71], v[74:75] op_sel_hi:[1,0]
	v_add3_u32 v69, v64, v69, s91
	v_pk_mul_f32 v[62:63], v[62:63], v[66:67]
	v_pk_mul_f32 v[66:67], v[60:61], v[58:59]
	v_add3_u32 v3, v65, v3, s91
	v_pk_fma_f32 v[66:67], v[56:57], v[62:63], v[66:67] neg_lo:[0,0,1] neg_hi:[0,0,1]
	v_pk_mul_f32 v[56:57], v[56:57], v[58:59]
	v_bfe_u32 v58, v51, 16, 1
	v_pk_fma_f32 v[56:57], v[60:61], v[62:63], v[56:57]
	v_bfe_u32 v60, v53, 16, 1
	v_add3_u32 v62, v53, v60, s91
	v_bfe_u32 v60, v52, 16, 1
	v_bfe_u32 v61, v66, 16, 1
	v_bfe_u32 v63, v50, 16, 1
	v_add3_u32 v60, v52, v60, s91
	v_bfe_u32 v59, v67, 16, 1
	v_add3_u32 v63, v50, v63, s91
	v_add3_u32 v61, v66, v61, s91
	v_lshrrev_b32_e32 v70, 16, v60
	v_lshrrev_b32_e32 v60, 16, v69
	v_add3_u32 v59, v67, v59, s91
	v_add3_u32 v58, v51, v58, s91
	v_lshrrev_b32_e32 v61, 16, v61
	v_lshrrev_b32_e32 v63, 16, v63
	v_and_or_b32 v60, v3, s33, v60
	v_mul_lo_u32 v3, v82, s88
	v_and_or_b32 v58, v58, s33, v63
	v_and_or_b32 v61, v59, s33, v61
	v_and_or_b32 v59, v62, s33, v70
	v_add3_u32 v3, 0, v3, v68
	ds_write_b128 v3, v[58:61]
	v_bfe_u32 v60, v57, 16, 1
	v_bfe_u32 v61, v49, 16, 1
	v_add3_u32 v62, v49, v61, s91
	v_add3_u32 v61, v57, v60, s91
	v_bfe_u32 v60, v48, 16, 1
	v_bfe_u32 v63, v56, 16, 1
	v_bfe_u32 v68, v46, 16, 1
	v_bfe_u32 v69, v54, 16, 1
	v_bfe_u32 v58, v55, 16, 1
	v_bfe_u32 v59, v47, 16, 1
	v_add3_u32 v69, v54, v69, s91
	v_add3_u32 v68, v46, v68, s91
	v_add3_u32 v63, v56, v63, s91
	v_add3_u32 v60, v48, v60, s91
	v_add3_u32 v59, v47, v59, s91
	v_add3_u32 v58, v55, v58, s91
	v_lshrrev_b32_e32 v70, 16, v60
	v_lshrrev_b32_e32 v63, 16, v63
	v_lshrrev_b32_e32 v68, 16, v68
	v_lshrrev_b32_e32 v60, 16, v69
	v_and_or_b32 v60, v58, s33, v60
	v_and_or_b32 v58, v59, s33, v68
	v_and_or_b32 v61, v61, s33, v63
	v_and_or_b32 v59, v62, s33, v70
	ds_write_b128 v3, v[58:61] offset:64
	s_and_saveexec_b64 s[4:5], s[8:9]
	s_cbranch_execz .LBB0_471
	v_readlane_b32 s8, v254, 8
	s_lshl_b32 s94, s15, 2
	s_nop 0
	v_mov_b32_e32 v3, s8
	ds_read_b64 v[58:59], v3
	s_waitcnt lgkmcnt(0)
	v_readfirstlane_b32 s8, v58
	v_add_u32_e32 v58, s20, v82
	v_readfirstlane_b32 s9, v59
	v_ashrrev_i32_e32 v59, 31, v58
	v_lshlrev_b64 v[58:59], 10, v[58:59]
	v_lshl_add_u64 v[58:59], s[8:9], 0, v[58:59]
	v_lshl_add_u64 v[58:59], v[58:59], 0, s[94:95]
	v_lshl_add_u64 v[58:59], v[58:59], 0, v[0:1]
	s_mov_b64 s[8:9], 0x4158000
	v_lshl_add_u64 v[60:61], v[58:59], 0, s[8:9]
	s_mov_b32 s8, 0x4158000
	v_add_co_u32_e32 v58, vcc, s8, v58
	s_nop 1
	v_addc_co_u32_e32 v59, vcc, 0, v59, vcc
	flat_store_dwordx4 v[58:59], v[50:53]
	flat_store_dwordx4 v[60:61], v[64:67] offset:16
	flat_store_dwordx4 v[60:61], v[46:49] offset:128
	flat_store_dwordx4 v[60:61], v[54:57] offset:144
.LBB0_471:
	s_or_b64 exec, exec, s[4:5]
	s_nop 0
	v_and_b32_e32 v56, 0xff, v78
	v_add_u32_e32 v0, s19, v56
	v_cmp_lt_i32_e64 s[4:5], -1, v0
	v_ashrrev_i32_e32 v3, 3, v78
	v_add_u32_e32 v0, s18, v0
	v_mov_b64_e32 v[46:47], s[2:3]
	s_movk_i32 s2, 0xc00
	v_and_b32_e32 v54, 0xffffffe0, v3
	v_mad_i64_i32 v[46:47], s[2:3], v0, s2, v[46:47]
	s_lshl_b32 s94, s15, 1
	v_lshl_add_u64 v[46:47], v[46:47], 0, s[94:95]
	v_ashrrev_i32_e32 v55, 31, v54
	v_lshl_add_u64 v[58:59], v[54:55], 1, v[46:47]
	v_mov_b32_e32 v46, 0
	v_mov_b32_e32 v47, 0
	v_mov_b32_e32 v48, 0
	v_mov_b32_e32 v49, 0
	v_mov_b32_e32 v50, 0
	v_mov_b32_e32 v51, 0
	v_mov_b32_e32 v52, 0
	v_mov_b32_e32 v53, 0
	s_and_saveexec_b64 s[2:3], s[4:5]
	global_load_dwordx4 v[132:135], v[58:59], off offset:2560
	global_load_dwordx4 v[136:139], v[58:59], off offset:2576
	global_load_dwordx4 v[140:143], v[58:59], off offset:2592
	global_load_dwordx4 v[144:147], v[58:59], off offset:2608
	s_or_b64 exec, exec, s[2:3]
	s_and_saveexec_b64 s[2:3], s[4:5]
	s_cbranch_execz .LBB0_473
	s_waitcnt vmcnt(3)
	v_mov_b32_e32 v50, v132
	v_mov_b32_e32 v51, v133
	v_mov_b32_e32 v52, v134
	v_mov_b32_e32 v53, v135
	v_lshlrev_b32_e32 v46, 16, v50
	v_and_b32_e32 v47, 0xffff0000, v50
	v_lshlrev_b32_e32 v48, 16, v51
	v_and_b32_e32 v49, 0xffff0000, v51
	v_lshlrev_b32_e32 v50, 16, v52
	v_and_b32_e32 v51, 0xffff0000, v52
	v_lshlrev_b32_e32 v52, 16, v53
	v_and_b32_e32 v53, 0xffff0000, v53

.LBB0_475:
	s_or_b64 exec, exec, s[6:7]
	v_mov_b32_e32 v46, 0
	v_mov_b32_e32 v47, 0
	v_mov_b32_e32 v48, 0
	v_mov_b32_e32 v49, 0
	v_mov_b32_e32 v50, 0
	v_mov_b32_e32 v51, 0
	v_mov_b32_e32 v52, 0
	v_mov_b32_e32 v53, 0
	s_and_saveexec_b64 s[6:7], s[4:5]
	s_cbranch_execz .LBB0_477
	s_waitcnt vmcnt(2)
	v_mov_b32_e32 v50, v136
	v_mov_b32_e32 v51, v137
	v_mov_b32_e32 v52, v138
	v_mov_b32_e32 v53, v139
	v_lshlrev_b32_e32 v46, 16, v50
	v_and_b32_e32 v47, 0xffff0000, v50
	v_lshlrev_b32_e32 v48, 16, v51
	v_and_b32_e32 v49, 0xffff0000, v51
	v_lshlrev_b32_e32 v50, 16, v52
	v_and_b32_e32 v51, 0xffff0000, v52
	v_lshlrev_b32_e32 v52, 16, v53
	v_and_b32_e32 v53, 0xffff0000, v53

.LBB0_479:
	s_or_b64 exec, exec, s[6:7]
	v_mov_b32_e32 v46, 0
	v_mov_b32_e32 v47, 0
	v_mov_b32_e32 v48, 0
	v_mov_b32_e32 v49, 0
	v_mov_b32_e32 v50, 0
	v_mov_b32_e32 v51, 0
	v_mov_b32_e32 v52, 0
	v_mov_b32_e32 v53, 0
	s_and_saveexec_b64 s[6:7], s[4:5]
	s_cbranch_execz .LBB0_481
	s_waitcnt vmcnt(1)
	v_mov_b32_e32 v50, v140
	v_mov_b32_e32 v51, v141
	v_mov_b32_e32 v52, v142
	v_mov_b32_e32 v53, v143
	v_lshlrev_b32_e32 v46, 16, v50
	v_and_b32_e32 v47, 0xffff0000, v50
	v_lshlrev_b32_e32 v48, 16, v51
	v_and_b32_e32 v49, 0xffff0000, v51
	v_lshlrev_b32_e32 v50, 16, v52
	v_and_b32_e32 v51, 0xffff0000, v52
	v_lshlrev_b32_e32 v52, 16, v53
	v_and_b32_e32 v53, 0xffff0000, v53

.LBB0_483:
	s_or_b64 exec, exec, s[6:7]
	v_mov_b32_e32 v46, 0
	v_mov_b32_e32 v47, 0
	v_mov_b32_e32 v48, 0
	v_mov_b32_e32 v49, 0
	v_mov_b32_e32 v50, 0
	v_mov_b32_e32 v51, 0
	v_mov_b32_e32 v52, 0
	v_mov_b32_e32 v53, 0
	s_and_saveexec_b64 s[6:7], s[4:5]
	s_cbranch_execz .LBB0_485
	s_waitcnt vmcnt(0)
	v_mov_b32_e32 v50, v144
	v_mov_b32_e32 v51, v145
	v_mov_b32_e32 v52, v146
	v_mov_b32_e32 v53, v147
	v_lshlrev_b32_e32 v46, 16, v50
	v_and_b32_e32 v47, 0xffff0000, v50
	v_lshlrev_b32_e32 v48, 16, v51
	v_and_b32_e32 v49, 0xffff0000, v51
	v_lshlrev_b32_e32 v50, 16, v52
	v_and_b32_e32 v51, 0xffff0000, v52
	v_lshlrev_b32_e32 v52, 16, v53
	v_and_b32_e32 v53, 0xffff0000, v53

.LBB0_497:
	ds_read_b32 v12, v9
	v_add_u32_e32 v8, 64, v8
	v_max_f32_e32 v11, v11, v11
	v_cmp_lt_u32_e32 vcc, 64, v8
	v_add_u32_e32 v9, 0x100, v9
	s_waitcnt lgkmcnt(0)
	v_max_f32_e32 v12, v12, v12
	s_or_b64 s[6:7], vcc, s[6:7]
	v_max_f32_e32 v11, v11, v12
	s_andn2_b64 exec, exec, s[6:7]
	s_cbranch_execnz .LBB0_497
	s_or_b64 exec, exec, s[6:7]
	ds_bpermute_b32 v8, v5, v11
	v_max_f32_e32 v9, v11, v11
	v_readfirstlane_b32 s6, v6
	v_readfirstlane_b32 s7, v7
	s_nop 1
	v_add_u32_e32 v150, s40, v2
	v_ashrrev_i32_e32 v151, 31, v150
	v_mov_b32_e32 v148, s6
	v_mov_b32_e32 v149, s7
	v_lshl_add_u64 v[148:149], v[150:151], 2, v[148:149]
	global_load_dword v152, v[148:149], off
	v_add_u32_e32 v12, s40, v2
	s_waitcnt lgkmcnt(0)
	v_max_f32_e32 v8, v8, v8
	v_max_f32_e32 v8, v9, v8
	ds_bpermute_b32 v9, v106, v8
	v_ashrrev_i32_e32 v13, 31, v12
	s_mov_b32 s8, 0
	s_waitcnt lgkmcnt(0)
	v_max_f32_e32 v9, v9, v9
	v_max_f32_e32 v8, v8, v9
	ds_bpermute_b32 v9, v107, v8
	s_waitcnt lgkmcnt(0)
	v_max_f32_e32 v9, v9, v9
	v_max_f32_e32 v8, v8, v9
	ds_bpermute_b32 v9, v108, v8
	s_waitcnt lgkmcnt(0)
	v_max_f32_e32 v9, v9, v9
	v_max_f32_e32 v8, v8, v9
	ds_bpermute_b32 v9, v109, v8
	s_waitcnt lgkmcnt(0)
	v_max_f32_e32 v9, v9, v9
	v_max_f32_e32 v11, v8, v9
	v_mov_b32_e32 v8, s6
	v_mov_b32_e32 v9, s7
	v_lshl_add_u64 v[8:9], v[12:13], 2, v[8:9]
	s_waitcnt vmcnt(0)
	s_nop 0
	v_mov_b32_e32 v8, v152
	s_nop 1
	ds_bpermute_b32 v14, v110, v11
	s_mov_b64 s[6:7], 0
	v_mov_b32_e32 v12, v3
	s_waitcnt vmcnt(0) lgkmcnt(0)
	v_max3_f32 v9, v11, v14, v8
	v_mov_b32_e32 v11, 0

.LBB0_560:
	s_cmpk_gt_i32 s43, 0x68b
	s_cbranch_scc1 .LBB0_634
	v_and_b32_e32 v0, 0xffffffc0, v223
	v_add_u32_e32 v0, 64, v0
	v_xor_b32_e32 v2, 1, v223
	v_cmp_lt_i32_e32 vcc, v2, v0
	s_ashr_i32 s1, s0, 31
	s_lshl_b32 s2, s0, 6
	v_cndmask_b32_e32 v2, v223, v2, vcc
	v_lshlrev_b32_e32 v5, 2, v2
	v_xor_b32_e32 v2, 2, v223
	v_cmp_lt_i32_e32 vcc, v2, v0
	s_lshl_b64 s[8:9], s[0:1], 23
	s_ashr_i32 s3, s2, 31
	v_cndmask_b32_e32 v2, v223, v2, vcc
	v_lshlrev_b32_e32 v88, 2, v2
	v_xor_b32_e32 v2, 4, v223
	v_cmp_lt_i32_e32 vcc, v2, v0
	s_mul_hi_i32 s22, s0, 0x3000
	s_mul_i32 s23, s0, 0x3000
	v_cndmask_b32_e32 v2, v223, v2, vcc
	v_lshlrev_b32_e32 v89, 2, v2
	v_xor_b32_e32 v2, 8, v223
	v_cmp_lt_i32_e32 vcc, v2, v0
	s_mul_i32 s10, s0, 0x300
	s_mul_i32 s24, s0, 12
	v_cndmask_b32_e32 v2, v223, v2, vcc
	v_lshlrev_b32_e32 v90, 2, v2
	v_xor_b32_e32 v2, 16, v223
	v_cmp_lt_i32_e32 vcc, v2, v0
	s_lshl_b32 s25, s0, 7
	s_lshl_b32 s26, s0, 2
	v_cndmask_b32_e32 v2, v223, v2, vcc
	v_lshlrev_b32_e32 v91, 2, v2
	v_xor_b32_e32 v2, 32, v223
	v_cmp_lt_i32_e32 vcc, v2, v0
	s_lshl_b64 s[12:13], s[0:1], 25
	s_lshl_b32 s0, s43, 10
	v_cndmask_b32_e32 v0, v223, v2, vcc
	v_lshlrev_b32_e32 v92, 2, v0
	s_ashr_i32 s11, s10, 31
	s_add_i32 s14, s43, 0xfffff9f4
	s_add_i32 s16, s0, 0xffe7d000
	s_lshl_b32 s27, s90, 10
	s_lshl_b64 s[18:19], s[2:3], 2
	v_mov_b32_e32 v2, v229
	s_mov_b32 s28, s43
	s_mov_b32 s73, 0
	s_cmp_eq_u32 s90, 0x100
	s_cbranch_scc0 .Lra_sched_off
	s_mov_b32 s73, 1
	s_mov_b32 s64, 0
	s_cmp_lt_u32 s43, 12
	s_cbranch_scc0 .Lra_cls_b
	s_mul_i32 s69, s43, 3
	s_mov_b32 s68, 3
	s_add_i32 s70, s43, 0x600
	s_branch .Lra_cls_done
.Lra_cls_b:
	s_cmp_lt_u32 s43, 0x8c
	s_cbranch_scc0 .Lra_cls_c
	s_sub_i32 s71, s43, 12
	s_mul_i32 s69, s71, 5
	s_min_u32 s72, s71, 48
	s_add_i32 s69, s69, s72
	s_add_i32 s69, s69, 36
	s_cmp_lt_u32 s71, 48
	s_cselect_b32 s68, 6, 5
	s_add_i32 s70, s43, 0x600
	s_branch .Lra_cls_done
.Lra_cls_c:
	s_sub_i32 s71, s43, 0x8c
	s_mul_i32 s69, s71, 7
	s_add_i32 s69, s69, 0x2d4
	s_mov_b32 s68, 7
	s_mov_b32 s70, -1
.Lra_cls_done:
	s_mov_b32 s28, s69
	s_cmp_eq_u32 s70, -1
	s_cbranch_scc1 .Lra_first_set
	s_mov_b32 s28, s70
	s_sub_i32 s69, s69, 1
	s_add_i32 s68, s68, 1
.Lra_first_set:
	s_add_i32 s14, s28, 0xfffff9f4
	s_lshl_b32 s16, s14, 10
.Lra_sched_off:
	s_branch .LBB0_564
.LBB0_562:
	s_or_b64 exec, exec, s[4:5]
	s_waitcnt lgkmcnt(0)
	s_barrier
.LBB0_563:
	s_cmp_lg_u32 s73, 0
	s_cbranch_scc1 .Lra_sched_next
	s_add_i32 s28, s28, s90
	s_add_i32 s14, s14, s90
	s_add_i32 s16, s16, s27
	s_cmpk_gt_i32 s28, 0x68b
	s_waitcnt lgkmcnt(0)
	s_cbranch_scc1 .LBB0_634
	s_branch .LBB0_564
.Lra_sched_next:
	s_add_i32 s64, s64, 1
	s_add_i32 s28, s69, s64
	s_add_i32 s14, s28, 0xfffff9f4
	s_lshl_b32 s16, s14, 10
	s_cmp_ge_u32 s64, s68
	s_waitcnt lgkmcnt(0)
	s_cbranch_scc1 .LBB0_634
